# GEMM k-loops: minimal counted lgkmcnt waits at first consumer of each LDS fragment read (MFMAs start after 5 of 8 reads)
# speedup vs baseline: 1.0050x; 1.0050x over previous
; template <bool SWAP, class Epi, bool THIN = false> ...
;     ...
;     for (int st = 0; st < ns; ++st) {
;       asm volatile("s_waitcnt vmcnt(0)" ::: "memory");
;       __builtin_amdgcn_s_barrier();
;       asm volatile("" ::: "memory");
;       if (st + 1 < ns) {
;         char* nb = smem + ((st + 1) & 1) * 65536;
;         const int ko = (st + 1) * 64;
; #pragma unroll
;         for (int i = 0; i < 4; ++i) { GLDS16(A + (size_t)(ap[i] + ko), nb + tid * 16 + i * 8192); GLDS16(Bt + (size_t)(bp[i] + ko), nb + 32768 + tid * 16 + i * 8192); }
;       }
;       const char* sa = smem + (st & 1) * 65536 + (wr * 64 + fr) * 128;
;       const char* sb = smem + (st & 1) * 65536 + 32768 + (wc * 128 + fr) * 128;
;       if constexpr (THIN) {
;         if (wc == 0) {
; #pragma unroll
;           for (int ks = 0; ks < 2; ++ks) {
;             bf16x8 af[4], bf[2];
; #pragma unroll
;             for (int m = 0; m < 4; ++m) af[m] = *(const bf16x8*)(sa + m * 2048 + (((ks * 4 + fq) ^ swz) << 4));
; #pragma unroll
;             for (int n = 0; n < 2; ++n) bf[n] = *(const bf16x8*)(sb + n * 2048 + (((ks * 4 + fq) ^ swz) << 4));
; #pragma unroll
;             for (int m = 0; m < 4; ++m)
; #pragma unroll
;               for (int n = 0; n < 2; ++n)
;                 acc[m][n] = SWAP ? __builtin_amdgcn_mfma_f32_16x16x32_bf16(bf[n], af[m], acc[m][n], 0, 0, 0)
;                                  : __builtin_amdgcn_mfma_f32_16x16x32_bf16(af[m], bf[n], acc[m][n], 0, 0, 0);
;           }
;         }
;       } else {
;       bf16x8 afA[4], afB[4], bfb[2][2];
; #pragma unroll
;       for (int m = 0; m < 4; ++m) afA[m] = *(const bf16x8*)(sa + m * 2048 + ((fq ^ swz) << 4));
; #pragma unroll
;       for (int n = 0; n < 2; ++n) bfb[0][n] = *(const bf16x8*)(sb + n * 2048 + ((fq ^ swz) << 4));
; #pragma unroll
;       for (int gq = 0; gq < 8; ++gq) {
;         const int ks = gq >> 2, nh = gq & 3;
;         if (gq < 7) {
;           const int ks2 = (gq + 1) >> 2, nh2 = (gq + 1) & 3;
; #pragma unroll
;           for (int n = 0; n < 2; ++n) bfb[(gq + 1) & 1][n] = *(const bf16x8*)(sb + (nh2 * 2 + n) * 2048 + (((ks2 * 4 + fq) ^ swz) << 4));
;         }
;         if (gq == 3) {
; #pragma unroll
;           for (int m = 0; m < 4; ++m) afB[m] = *(const bf16x8*)(sa + m * 2048 + (((4 + fq) ^ swz) << 4));
;         }
;         __builtin_amdgcn_sched_barrier(0);
; #pragma unroll
.LBB0_339:
	s_add_i32 s8, s7, 0x10000
	s_and_b32 s9, s8, 0x10000
	v_add_u32_e32 v171, s9, v144
	s_nop 0
	v_readfirstlane_b32 s9, v171
	s_waitcnt vmcnt(0)
	s_barrier
	s_and_b32 s7, s7, 0x10000
	v_add_u32_e32 v130, s7, v145
	v_add_u32_e32 v140, v130, v147
	ds_read_b128 v[172:175], v140
	ds_read_b128 v[176:179], v140 offset:2048
	ds_read_b128 v[180:183], v140 offset:4096
	ds_read_b128 v[184:187], v140 offset:6144
	v_or_b32_e32 v140, s7, v146
	v_add_u32_e32 v141, v140, v147
	ds_read_b128 v[188:191], v141 offset:32768
	ds_read_b128 v[192:195], v141 offset:34816
	ds_read_b128 v[196:199], v141 offset:36864
	ds_read_b128 v[200:203], v141 offset:38912
	v_add_u32_e32 v130, v130, v148
	s_waitcnt lgkmcnt(3)
	v_mfma_f32_16x16x32_bf16 v[126:129], v[188:191], v[172:175], v[126:129]
	s_mov_b32 m0, s9
	v_mfma_f32_16x16x32_bf16 v[110:113], v[188:191], v[176:179], v[110:113]
	global_load_lds_dwordx4 v139, s[36:37]
	v_add_u32_e32 v139, 0x80, v139
	v_mfma_f32_16x16x32_bf16 v[82:85], v[188:191], v[180:183], v[82:85]
	v_mfma_f32_16x16x32_bf16 v[50:53], v[188:191], v[184:187], v[50:53]
	ds_read_b128 v[188:191], v141 offset:40960
	ds_read_b128 v[204:207], v141 offset:43008
	s_waitcnt lgkmcnt(4)
	v_mfma_f32_16x16x32_bf16 v[122:125], v[192:195], v[172:175], v[122:125]
	s_add_u32 m0, s9, 0x8000
	v_mfma_f32_16x16x32_bf16 v[106:109], v[192:195], v[176:179], v[106:109]
	global_load_lds_dwordx4 v138, s[22:23]
	v_add_u32_e32 v138, 0x80, v138
	v_mfma_f32_16x16x32_bf16 v[78:81], v[192:195], v[180:183], v[78:81]
	v_mfma_f32_16x16x32_bf16 v[42:45], v[192:195], v[184:187], v[42:45]
	s_waitcnt lgkmcnt(3)
	v_mfma_f32_16x16x32_bf16 v[118:121], v[196:199], v[172:175], v[118:121]
	s_add_u32 m0, s9, 0x2000
	v_mfma_f32_16x16x32_bf16 v[94:97], v[196:199], v[176:179], v[94:97]
	global_load_lds_dwordx4 v137, s[36:37]
	v_add_u32_e32 v137, 0x80, v137
	v_mfma_f32_16x16x32_bf16 v[58:61], v[196:199], v[180:183], v[58:61]
	v_mfma_f32_16x16x32_bf16 v[26:29], v[196:199], v[184:187], v[26:29]
	ds_read_b128 v[192:195], v141 offset:45056
	ds_read_b128 v[196:199], v141 offset:47104
	s_waitcnt lgkmcnt(4)
	v_mfma_f32_16x16x32_bf16 v[114:117], v[200:203], v[172:175], v[114:117]
	s_add_u32 m0, s9, 0xa000
	v_mfma_f32_16x16x32_bf16 v[86:89], v[200:203], v[176:179], v[86:89]
	global_load_lds_dwordx4 v136, s[22:23]
	v_add_u32_e32 v136, 0x80, v136
	v_mfma_f32_16x16x32_bf16 v[54:57], v[200:203], v[180:183], v[54:57]
	v_mfma_f32_16x16x32_bf16 v[22:25], v[200:203], v[184:187], v[22:25]
	v_add_u32_e32 v140, v140, v148
	s_waitcnt lgkmcnt(3)
	v_mfma_f32_16x16x32_bf16 v[102:105], v[188:191], v[172:175], v[102:105]
	ds_read_b128 v[200:203], v140 offset:32768
	ds_read_b128 v[208:211], v140 offset:34816
	s_add_u32 m0, s9, 0x4000
	v_mfma_f32_16x16x32_bf16 v[74:77], v[188:191], v[176:179], v[74:77]
	global_load_lds_dwordx4 v135, s[36:37]
	v_add_u32_e32 v135, 0x80, v135
	v_mfma_f32_16x16x32_bf16 v[46:49], v[188:191], v[180:183], v[46:49]
	v_mfma_f32_16x16x32_bf16 v[10:13], v[188:191], v[184:187], v[10:13]
	ds_read_b128 v[188:191], v130
	ds_read_b128 v[212:215], v130 offset:2048
	ds_read_b128 v[216:219], v130 offset:4096
	ds_read_b128 v[220:223], v130 offset:6144
	s_waitcnt lgkmcnt(8)
	v_mfma_f32_16x16x32_bf16 v[98:101], v[204:207], v[172:175], v[98:101]
	s_add_u32 m0, s9, 0xc000
	v_mfma_f32_16x16x32_bf16 v[66:69], v[204:207], v[176:179], v[66:69]
	global_load_lds_dwordx4 v134, s[22:23]
	v_add_u32_e32 v134, 0x80, v134
	v_mfma_f32_16x16x32_bf16 v[30:33], v[204:207], v[180:183], v[30:33]
	v_mfma_f32_16x16x32_bf16 v[6:9], v[204:207], v[184:187], v[6:9]
	s_waitcnt lgkmcnt(7)
	v_mfma_f32_16x16x32_bf16 v[70:73], v[192:195], v[172:175], v[70:73]
	s_add_u32 m0, s9, 0x6000
	s_waitcnt lgkmcnt(6)
	v_mfma_f32_16x16x32_bf16 v[62:65], v[196:199], v[172:175], v[62:65]
	global_load_lds_dwordx4 v133, s[36:37]
	v_add_u32_e32 v133, 0x80, v133
	v_mfma_f32_16x16x32_bf16 v[38:41], v[192:195], v[176:179], v[38:41]
	v_mfma_f32_16x16x32_bf16 v[34:37], v[196:199], v[176:179], v[34:37]
	ds_read_b128 v[172:175], v140 offset:36864
	ds_read_b128 v[176:179], v140 offset:38912
	v_mfma_f32_16x16x32_bf16 v[18:21], v[192:195], v[180:183], v[18:21]
	s_add_u32 m0, s9, 0xe000
	v_mfma_f32_16x16x32_bf16 v[14:17], v[196:199], v[180:183], v[14:17]
	global_load_lds_dwordx4 v132, s[22:23]
	v_add_u32_e32 v132, 0x80, v132
	v_mfma_f32_16x16x32_bf16 v[2:5], v[192:195], v[184:187], v[2:5]
	v_mfma_f32_16x16x32_bf16 v[90:93], v[196:199], v[184:187], v[90:93]
	ds_read_b128 v[180:183], v140 offset:40960
	ds_read_b128 v[184:187], v140 offset:43008
	s_waitcnt lgkmcnt(7)
	v_mfma_f32_16x16x32_bf16 v[126:129], v[200:203], v[188:191], v[126:129]
	v_mfma_f32_16x16x32_bf16 v[122:125], v[208:211], v[188:191], v[122:125]
	s_waitcnt lgkmcnt(6)
	v_mfma_f32_16x16x32_bf16 v[110:113], v[200:203], v[212:215], v[110:113]
	v_mfma_f32_16x16x32_bf16 v[106:109], v[208:211], v[212:215], v[106:109]
	s_waitcnt lgkmcnt(5)
	v_mfma_f32_16x16x32_bf16 v[82:85], v[200:203], v[216:219], v[82:85]
	v_mfma_f32_16x16x32_bf16 v[78:81], v[208:211], v[216:219], v[78:81]
	s_waitcnt lgkmcnt(4)
	v_mfma_f32_16x16x32_bf16 v[50:53], v[200:203], v[220:223], v[50:53]
	v_mfma_f32_16x16x32_bf16 v[42:45], v[208:211], v[220:223], v[42:45]
	s_waitcnt lgkmcnt(3)
	v_mfma_f32_16x16x32_bf16 v[118:121], v[172:175], v[188:191], v[118:121]
	v_mfma_f32_16x16x32_bf16 v[94:97], v[172:175], v[212:215], v[94:97]
	v_mfma_f32_16x16x32_bf16 v[58:61], v[172:175], v[216:219], v[58:61]
	v_mfma_f32_16x16x32_bf16 v[26:29], v[172:175], v[220:223], v[26:29]
	ds_read_b128 v[172:175], v140 offset:45056
	ds_read_b128 v[192:195], v140 offset:47104
	s_waitcnt lgkmcnt(4)
; template <bool SWAP, class Epi, bool THIN = false> ...
;     ...
;       bf16x8 afA[4], afB[4], bfb[2][2];
; #pragma unroll
;       for (int m = 0; m < 4; ++m) afA[m] = *(const bf16x8*)(sa + m * 2048 + ((fq ^ swz) << 4));
; #pragma unroll
;       for (int n = 0; n < 2; ++n) bfb[0][n] = *(const bf16x8*)(sb + n * 2048 + ((fq ^ swz) << 4));
; #pragma unroll
;       for (int gq = 0; gq < 8; ++gq) {
;         const int ks = gq >> 2, nh = gq & 3;
;         if (gq < 7) {
;           const int ks2 = (gq + 1) >> 2, nh2 = (gq + 1) & 3;
; #pragma unroll
;           for (int n = 0; n < 2; ++n) bfb[(gq + 1) & 1][n] = *(const bf16x8*)(sb + (nh2 * 2 + n) * 2048 + (((ks2 * 4 + fq) ^ swz) << 4));
;         }
;         if (gq == 3) {
; #pragma unroll
;           for (int m = 0; m < 4; ++m) afB[m] = *(const bf16x8*)(sa + m * 2048 + (((4 + fq) ^ swz) << 4));
;         }
;         __builtin_amdgcn_sched_barrier(0);
; #pragma unroll
;         for (int m = 0; m < 4; ++m)
; #pragma unroll
;           for (int n = 0; n < 2; ++n) {
;             const bf16x8 av = ks ? afB[m] : afA[m];
;             acc[m][nh * 2 + n] = SWAP ? __builtin_amdgcn_mfma_f32_16x16x32_bf16(bfb[gq & 1][n], av, acc[m][nh * 2 + n], 0, 0, 0)
;                                       : __builtin_amdgcn_mfma_f32_16x16x32_bf16(av, bfb[gq & 1][n], acc[m][nh * 2 + n], 0, 0, 0);
;           }
;       }
	v_mfma_f32_16x16x32_bf16 v[114:117], v[176:179], v[188:191], v[114:117]
	v_mfma_f32_16x16x32_bf16 v[86:89], v[176:179], v[212:215], v[86:89]
	v_mfma_f32_16x16x32_bf16 v[54:57], v[176:179], v[216:219], v[54:57]
	v_mfma_f32_16x16x32_bf16 v[22:25], v[176:179], v[220:223], v[22:25]
	s_waitcnt lgkmcnt(3)
	v_mfma_f32_16x16x32_bf16 v[102:105], v[180:183], v[188:191], v[102:105]
	s_waitcnt lgkmcnt(2)
	v_mfma_f32_16x16x32_bf16 v[98:101], v[184:187], v[188:191], v[98:101]
	v_mfma_f32_16x16x32_bf16 v[74:77], v[180:183], v[212:215], v[74:77]
	v_mfma_f32_16x16x32_bf16 v[66:69], v[184:187], v[212:215], v[66:69]
	v_mfma_f32_16x16x32_bf16 v[46:49], v[180:183], v[216:219], v[46:49]
	v_mfma_f32_16x16x32_bf16 v[30:33], v[184:187], v[216:219], v[30:33]
	v_mfma_f32_16x16x32_bf16 v[10:13], v[180:183], v[220:223], v[10:13]
	v_mfma_f32_16x16x32_bf16 v[6:9], v[184:187], v[220:223], v[6:9]
	s_waitcnt lgkmcnt(1)
	v_mfma_f32_16x16x32_bf16 v[70:73], v[172:175], v[188:191], v[70:73]
	s_add_i32 s6, s6, 64
	s_cmpk_eq_i32 s6, 0x3c0
	s_mov_b32 s7, s8
	s_waitcnt lgkmcnt(0)
	v_mfma_f32_16x16x32_bf16 v[62:65], v[192:195], v[188:191], v[62:65]
	v_mfma_f32_16x16x32_bf16 v[38:41], v[172:175], v[212:215], v[38:41]
	v_mfma_f32_16x16x32_bf16 v[34:37], v[192:195], v[212:215], v[34:37]
	v_mfma_f32_16x16x32_bf16 v[18:21], v[172:175], v[216:219], v[18:21]
	v_mfma_f32_16x16x32_bf16 v[14:17], v[192:195], v[216:219], v[14:17]
	v_mfma_f32_16x16x32_bf16 v[2:5], v[172:175], v[220:223], v[2:5]
	v_mfma_f32_16x16x32_bf16 v[90:93], v[192:195], v[220:223], v[90:93]
	s_cbranch_scc0 .LBB0_339
	s_waitcnt vmcnt(0)
	s_barrier
	v_add_u32_e32 v130, v159, v147
	ds_read_b128 v[132:135], v130
	ds_read_b128 v[136:139], v130 offset:2048
	ds_read_b128 v[172:175], v130 offset:4096
	ds_read_b128 v[176:179], v130 offset:6144
	v_add_u32_e32 v130, v160, v147
	ds_read_b128 v[180:183], v130
	ds_read_b128 v[184:187], v130 offset:2048
	ds_read_b128 v[188:191], v130 offset:4096
	ds_read_b128 v[192:195], v130 offset:6144
	s_waitcnt lgkmcnt(0)
	v_mfma_f32_16x16x32_bf16 v[126:129], v[180:183], v[132:135], v[126:129]
	v_mfma_f32_16x16x32_bf16 v[110:113], v[180:183], v[136:139], v[110:113]
	v_mfma_f32_16x16x32_bf16 v[82:85], v[180:183], v[172:175], v[82:85]
	v_mfma_f32_16x16x32_bf16 v[50:53], v[180:183], v[176:179], v[50:53]
	ds_read_b128 v[180:183], v130 offset:8192
	ds_read_b128 v[196:199], v130 offset:10240
	v_mfma_f32_16x16x32_bf16 v[122:125], v[184:187], v[132:135], v[122:125]
	v_mfma_f32_16x16x32_bf16 v[106:109], v[184:187], v[136:139], v[106:109]
	v_mfma_f32_16x16x32_bf16 v[78:81], v[184:187], v[172:175], v[78:81]
	v_mfma_f32_16x16x32_bf16 v[42:45], v[184:187], v[176:179], v[42:45]
	v_mfma_f32_16x16x32_bf16 v[118:121], v[188:191], v[132:135], v[118:121]
	v_mfma_f32_16x16x32_bf16 v[184:187], v[188:191], v[136:139], v[94:97]
	v_mfma_f32_16x16x32_bf16 v[204:207], v[188:191], v[172:175], v[58:61]
	v_mfma_f32_16x16x32_bf16 v[208:211], v[192:195], v[172:175], v[54:57]
	v_mfma_f32_16x16x32_bf16 v[188:191], v[188:191], v[176:179], v[26:29]
	s_nop 2
	ds_read_b128 v[26:29], v130 offset:12288
	ds_read_b128 v[54:57], v130 offset:14336
	v_mfma_f32_16x16x32_bf16 v[114:117], v[192:195], v[132:135], v[114:117]
	v_mfma_f32_16x16x32_bf16 v[200:203], v[192:195], v[136:139], v[86:89]
	v_mfma_f32_16x16x32_bf16 v[192:195], v[192:195], v[176:179], v[22:25]
	v_add_u32_e32 v130, v160, v148
	s_waitcnt lgkmcnt(0)
	v_mfma_f32_16x16x32_bf16 v[212:215], v[196:199], v[172:175], v[30:33]
	ds_read_b128 v[22:25], v130
	ds_read_b128 v[86:89], v130 offset:2048
	s_nop 0
	v_add_u32_e32 v30, v159, v148
	v_mfma_f32_16x16x32_bf16 v[102:105], v[180:183], v[132:135], v[102:105]
	v_mfma_f32_16x16x32_bf16 v[74:77], v[180:183], v[136:139], v[74:77]
	v_mfma_f32_16x16x32_bf16 v[46:49], v[180:183], v[172:175], v[46:49]
	v_mfma_f32_16x16x32_bf16 v[10:13], v[180:183], v[176:179], v[10:13]
	ds_read_b128 v[180:183], v30
	ds_read_b128 v[216:219], v30 offset:2048
	ds_read_b128 v[220:223], v30 offset:4096
	ds_read_b128 v[224:227], v30 offset:6144
	v_mfma_f32_16x16x32_bf16 v[98:101], v[196:199], v[132:135], v[98:101]
	v_mfma_f32_16x16x32_bf16 v[66:69], v[196:199], v[136:139], v[66:69]
	v_mfma_f32_16x16x32_bf16 v[6:9], v[196:199], v[176:179], v[6:9]
	v_mfma_f32_16x16x32_bf16 v[196:199], v[26:29], v[172:175], v[18:21]
	v_mfma_f32_16x16x32_bf16 v[172:175], v[54:57], v[172:175], v[14:17]
	s_nop 2
	ds_read_b128 v[14:17], v130 offset:4096
	ds_read_b128 v[18:21], v130 offset:6144
	v_mfma_f32_16x16x32_bf16 v[70:73], v[26:29], v[132:135], v[70:73]
	v_mfma_f32_16x16x32_bf16 v[132:135], v[54:57], v[132:135], v[62:65]
	v_mfma_f32_16x16x32_bf16 v[38:41], v[26:29], v[136:139], v[38:41]
	v_mfma_f32_16x16x32_bf16 v[34:37], v[54:57], v[136:139], v[34:37]
	v_mfma_f32_16x16x32_bf16 v[2:5], v[26:29], v[176:179], v[2:5]
	v_mfma_f32_16x16x32_bf16 v[176:179], v[54:57], v[176:179], v[90:93]
	ds_read_b128 v[136:139], v130 offset:8192
	ds_read_b128 v[228:231], v130 offset:10240
	s_waitcnt lgkmcnt(0)
	v_mfma_f32_16x16x32_bf16 v[126:129], v[22:25], v[180:183], v[126:129]
	v_mfma_f32_16x16x32_bf16 v[122:125], v[86:89], v[180:183], v[122:125]
	v_mfma_f32_16x16x32_bf16 v[94:97], v[22:25], v[216:219], v[110:113]
	v_mfma_f32_16x16x32_bf16 v[90:93], v[86:89], v[216:219], v[106:109]
	v_mfma_f32_16x16x32_bf16 v[62:65], v[22:25], v[220:223], v[82:85]
	v_mfma_f32_16x16x32_bf16 v[58:61], v[86:89], v[220:223], v[78:81]
	v_mfma_f32_16x16x32_bf16 v[30:33], v[22:25], v[224:227], v[50:53]
	v_mfma_f32_16x16x32_bf16 v[26:29], v[86:89], v[224:227], v[42:45]
	v_mfma_f32_16x16x32_bf16 v[86:89], v[14:17], v[216:219], v[184:187]
	v_mfma_f32_16x16x32_bf16 v[22:25], v[14:17], v[224:227], v[188:191]
	s_nop 1
	ds_read_b128 v[184:187], v130 offset:12288
	ds_read_b128 v[188:191], v130 offset:14336
	v_mfma_f32_16x16x32_bf16 v[118:121], v[14:17], v[180:183], v[118:121]
	v_mfma_f32_16x16x32_bf16 v[114:117], v[18:21], v[180:183], v[114:117]
	v_mfma_f32_16x16x32_bf16 v[82:85], v[18:21], v[216:219], v[200:203]
	v_mfma_f32_16x16x32_bf16 v[54:57], v[14:17], v[220:223], v[204:207]
	v_mfma_f32_16x16x32_bf16 v[50:53], v[18:21], v[220:223], v[208:211]
	v_mfma_f32_16x16x32_bf16 v[18:21], v[18:21], v[224:227], v[192:195]
	v_mfma_f32_16x16x32_bf16 v[110:113], v[136:139], v[180:183], v[102:105]
	v_mfma_f32_16x16x32_bf16 v[106:109], v[228:231], v[180:183], v[98:101]
	v_mfma_f32_16x16x32_bf16 v[78:81], v[136:139], v[216:219], v[74:77]
	v_mfma_f32_16x16x32_bf16 v[74:77], v[228:231], v[216:219], v[66:69]
	v_mfma_f32_16x16x32_bf16 v[46:49], v[136:139], v[220:223], v[46:49]
	v_mfma_f32_16x16x32_bf16 v[42:45], v[228:231], v[220:223], v[212:215]
	v_mfma_f32_16x16x32_bf16 v[14:17], v[136:139], v[224:227], v[10:13]
	v_mfma_f32_16x16x32_bf16 v[6:9], v[228:231], v[224:227], v[6:9]
	s_nop 1
	v_mov_b32_e32 v10, v1
	s_waitcnt vmcnt(0) lgkmcnt(0)
	s_barrier
; __device__ __forceinline__ int get_tid512() { int t = threadIdx.x; asm volatile("" : "+v"(t)); return t; }
; __device__ __forceinline__ unsigned pack2(float a, float b) { unsigned r; asm("v_cvt_pk_bf16_f32 %0, %1, %2" : "=v"(r) : "v"(a), "v"(b)); return r; }
;   __device__ __forceinline__ float c4(int g, int rig, int col, f32x4 v) const {
;     ...
;     uint2 u; u.x = pack2(v[0], v[1]); u.y = pack2(v[2], v[3]);
;     *(uint2*)(out + row * ld + col) = u;
;     return v[0] * v[0] + v[1] * v[1] + v[2] * v[2] + v[3] * v[3];
;   }
;   __device__ __forceinline__ void rowsum(int g, int rig, int slot, float ss) const {
;     if (slot < nslots) part[(size_t)slot * ((size_t)8 * ostride) + (size_t)g * ostride + rig] = ss;
; template <bool SWAP, class Epi, bool THIN = false> ...
;     ...
;     __syncthreads();
;     const int te = get_tid512();
;     const int fr_e = te & 15, fq_e = (te & 63) >> 4, wr_e = te >> 7, wc_e = (te >> 6) & 1;
;     const int sub = 2 * mt + (wr_e >> 1);
;     const int g = sub / tpg, ti = sub - g * tpg;
;     const int rig0 = ti * step - halo;
;     const int rw = (wr_e & 1) * 64;
;     if constexpr (Epi::KIND == 0) {
; #pragma unroll
;       for (int m = 0; m < 4; ++m) {
;         const int rig = rig0 + rw + m * 16 + fr_e;
;         if constexpr (Epi::ROWSUM) {
;           float ss = 0.f;
; #pragma unroll
;           for (int n = 0; n < 8; ++n) {
;             const int col = nt * 256 + wc_e * 128 + n * 16 + fq_e * 4;
;             if (col < N) ss += epi.c4(g, rig, col, acc[m][n]);
;           }
;           ss += __shfl_xor(ss, 16); ss += __shfl_xor(ss, 32);
;           if (fq_e == 0) epi.rowsum(g, rig, nt * 2 + wc_e, ss);
	v_mfma_f32_16x16x32_bf16 v[98:101], v[188:191], v[180:183], v[132:135]
	v_ashrrev_i32_e32 v11, 8, v10
	v_add_u32_e32 v11, s5, v11
	v_ashrrev_i32_e32 v12, 31, v11
	v_lshrrev_b32_e32 v12, 28, v12
	v_add_u32_e32 v12, v11, v12
	v_ashrrev_i32_e32 v138, 4, v12
	v_and_b32_e32 v132, 15, v10
	v_bfe_u32 v130, v10, 4, 2
	v_bfe_u32 v171, v10, 6, 1
	v_lshlrev_b32_e32 v12, 11, v138
	v_lshlrev_b32_e32 v11, 7, v11
	v_lshrrev_b32_e32 v10, 1, v10
	v_sub_u32_e32 v133, v11, v12
	v_and_b32_e32 v135, 64, v10
	v_lshlrev_b32_e32 v134, 7, v171
	v_mfma_f32_16x16x32_bf16 v[10:13], v[184:187], v[224:227], v[2:5]
	v_ashrrev_i32_e32 v139, 31, v138
	v_or3_b32 v132, v133, v135, v132
	v_ashrrev_i32_e32 v133, 31, v132
	v_lshlrev_b32_e32 v2, 2, v130
	v_mfma_f32_16x16x32_bf16 v[102:105], v[184:187], v[180:183], v[70:73]
	v_or3_b32 v134, v134, v2, s4
	v_lshlrev_b64 v[136:137], 21, v[138:139]
	v_cmp_gt_i32_e32 vcc, s29, v134
	v_mfma_f32_16x16x32_bf16 v[70:73], v[184:187], v[216:219], v[38:41]
	v_lshlrev_b64 v[140:141], 10, v[132:133]
	v_ashrrev_i32_e32 v135, 31, v134
	v_lshl_add_u64 v[136:137], s[38:39], 0, v[136:137]
	v_mfma_f32_16x16x32_bf16 v[66:69], v[188:191], v[216:219], v[34:37]
	v_mfma_f32_16x16x32_bf16 v[38:41], v[184:187], v[220:223], v[196:199]
	v_mfma_f32_16x16x32_bf16 v[34:37], v[188:191], v[220:223], v[172:175]
	v_mfma_f32_16x16x32_bf16 v[2:5], v[188:191], v[224:227], v[176:179]
	s_nop 1
	v_mov_b32_e32 v172, 0
	s_and_saveexec_b64 s[4:5], vcc
	s_cbranch_execz .LBB0_342
	v_cvt_pk_bf16_f32 v172, v126, v127
	v_pk_mul_f32 v[126:127], v[126:127], v[126:127]
	v_cvt_pk_bf16_f32 v173, v128, v129
	v_lshl_add_u64 v[174:175], v[136:137], 0, v[140:141]
	v_pk_mul_f32 v[128:129], v[128:129], v[128:129]
	v_add_f32_e32 v126, v126, v127
	v_lshl_add_u64 v[174:175], v[134:135], 1, v[174:175]
	v_add_f32_e32 v126, v128, v126
	global_store_dwordx2 v[174:175], v[172:173], off
	v_add_f32_e32 v172, v129, v126

; template <bool SWAP, class Epi, bool THIN = false> ...
;     ...
;     for (int st = 0; st < ns; ++st) {
;       asm volatile("s_waitcnt vmcnt(0)" ::: "memory");
;       __builtin_amdgcn_s_barrier();
;       asm volatile("" ::: "memory");
;       if (st + 1 < ns) {
;         char* nb = smem + ((st + 1) & 1) * 65536;
;         const int ko = (st + 1) * 64;
; #pragma unroll
;         for (int i = 0; i < 4; ++i) { GLDS16(A + (size_t)(ap[i] + ko), nb + tid * 16 + i * 8192); GLDS16(Bt + (size_t)(bp[i] + ko), nb + 32768 + tid * 16 + i * 8192); }
;       }
;       const char* sa = smem + (st & 1) * 65536 + (wr * 64 + fr) * 128;
;       const char* sb = smem + (st & 1) * 65536 + 32768 + (wc * 128 + fr) * 128;
;       if constexpr (THIN) {
;         if (wc == 0) {
; #pragma unroll
;           for (int ks = 0; ks < 2; ++ks) {
;             bf16x8 af[4], bf[2];
; #pragma unroll
;             for (int m = 0; m < 4; ++m) af[m] = *(const bf16x8*)(sa + m * 2048 + (((ks * 4 + fq) ^ swz) << 4));
; #pragma unroll
;             for (int n = 0; n < 2; ++n) bf[n] = *(const bf16x8*)(sb + n * 2048 + (((ks * 4 + fq) ^ swz) << 4));
; #pragma unroll
;             for (int m = 0; m < 4; ++m)
; #pragma unroll
;               for (int n = 0; n < 2; ++n)
;                 acc[m][n] = SWAP ? __builtin_amdgcn_mfma_f32_16x16x32_bf16(bf[n], af[m], acc[m][n], 0, 0, 0)
;                                  : __builtin_amdgcn_mfma_f32_16x16x32_bf16(af[m], bf[n], acc[m][n], 0, 0, 0);
;           }
;         }
;       } else {
;       bf16x8 afA[4], afB[4], bfb[2][2];
; #pragma unroll
;       for (int m = 0; m < 4; ++m) afA[m] = *(const bf16x8*)(sa + m * 2048 + ((fq ^ swz) << 4));
; #pragma unroll
;       for (int n = 0; n < 2; ++n) bfb[0][n] = *(const bf16x8*)(sb + n * 2048 + ((fq ^ swz) << 4));
; #pragma unroll
;       for (int gq = 0; gq < 8; ++gq) {
;         const int ks = gq >> 2, nh = gq & 3;
;         if (gq < 7) {
;           const int ks2 = (gq + 1) >> 2, nh2 = (gq + 1) & 3;
; #pragma unroll
;           for (int n = 0; n < 2; ++n) bfb[(gq + 1) & 1][n] = *(const bf16x8*)(sb + (nh2 * 2 + n) * 2048 + (((ks2 * 4 + fq) ^ swz) << 4));
;         }
;         if (gq == 3) {
; #pragma unroll
;           for (int m = 0; m < 4; ++m) afB[m] = *(const bf16x8*)(sa + m * 2048 + (((4 + fq) ^ swz) << 4));
;         }
;         __builtin_amdgcn_sched_barrier(0);
; #pragma unroll
.LBB0_418:
	s_add_i32 s8, s7, 0x10000
	s_and_b32 s9, s8, 0x10000
	v_add_u32_e32 v170, s9, v138
	s_nop 0
	v_readfirstlane_b32 s9, v170
	s_waitcnt vmcnt(0)
	s_barrier
	s_and_b32 s7, s7, 0x10000
	v_or_b32_e32 v204, s7, v140
	v_add_u32_e32 v205, v204, v141
	v_add_u32_e32 v130, s7, v139
	v_add_u32_e32 v180, v130, v141
	ds_read_b128 v[168:171], v180
	ds_read_b128 v[172:175], v180 offset:2048
	ds_read_b128 v[176:179], v180 offset:4096
	ds_read_b128 v[180:183], v180 offset:6144
	ds_read_b128 v[184:187], v205 offset:32768
	ds_read_b128 v[188:191], v205 offset:34816
	ds_read_b128 v[192:195], v205 offset:36864
	ds_read_b128 v[196:199], v205 offset:38912
	v_add_u32_e32 v130, v130, v142
	s_waitcnt lgkmcnt(3)
	v_mfma_f32_16x16x32_bf16 v[126:129], v[184:187], v[168:171], v[126:129]
	s_mov_b32 m0, s9
	v_mfma_f32_16x16x32_bf16 v[110:113], v[184:187], v[172:175], v[110:113]
	global_load_lds_dwordx4 v167, s[36:37]
	v_add_u32_e32 v167, 0x80, v167
	v_mfma_f32_16x16x32_bf16 v[82:85], v[184:187], v[176:179], v[82:85]
	v_mfma_f32_16x16x32_bf16 v[50:53], v[184:187], v[180:183], v[50:53]
	ds_read_b128 v[184:187], v205 offset:40960
	ds_read_b128 v[200:203], v205 offset:43008
	s_waitcnt lgkmcnt(4)
	v_mfma_f32_16x16x32_bf16 v[122:125], v[188:191], v[168:171], v[122:125]
	s_add_u32 m0, s9, 0x8000
	v_mfma_f32_16x16x32_bf16 v[106:109], v[188:191], v[172:175], v[106:109]
	global_load_lds_dwordx4 v166, s[38:39]
	v_add_u32_e32 v166, 0x80, v166
	v_mfma_f32_16x16x32_bf16 v[78:81], v[188:191], v[176:179], v[78:81]
	v_mfma_f32_16x16x32_bf16 v[42:45], v[188:191], v[180:183], v[42:45]
	s_waitcnt lgkmcnt(3)
	v_mfma_f32_16x16x32_bf16 v[118:121], v[192:195], v[168:171], v[118:121]
	s_add_u32 m0, s9, 0x2000
	v_mfma_f32_16x16x32_bf16 v[94:97], v[192:195], v[172:175], v[94:97]
	global_load_lds_dwordx4 v165, s[36:37]
	v_add_u32_e32 v165, 0x80, v165
	v_mfma_f32_16x16x32_bf16 v[58:61], v[192:195], v[176:179], v[58:61]
	v_mfma_f32_16x16x32_bf16 v[26:29], v[192:195], v[180:183], v[26:29]
	ds_read_b128 v[188:191], v205 offset:45056
	ds_read_b128 v[192:195], v205 offset:47104
	s_waitcnt lgkmcnt(4)
	v_mfma_f32_16x16x32_bf16 v[114:117], v[196:199], v[168:171], v[114:117]
	s_add_u32 m0, s9, 0xa000
	v_mfma_f32_16x16x32_bf16 v[86:89], v[196:199], v[172:175], v[86:89]
	global_load_lds_dwordx4 v164, s[38:39]
	v_add_u32_e32 v164, 0x80, v164
	v_mfma_f32_16x16x32_bf16 v[54:57], v[196:199], v[176:179], v[54:57]
	v_mfma_f32_16x16x32_bf16 v[22:25], v[196:199], v[180:183], v[22:25]
	v_add_u32_e32 v220, v204, v142
	s_waitcnt lgkmcnt(3)
	v_mfma_f32_16x16x32_bf16 v[102:105], v[184:187], v[168:171], v[102:105]
	ds_read_b128 v[196:199], v220 offset:32768
	ds_read_b128 v[204:207], v220 offset:34816
	s_add_u32 m0, s9, 0x4000
	v_mfma_f32_16x16x32_bf16 v[74:77], v[184:187], v[172:175], v[74:77]
	global_load_lds_dwordx4 v135, s[36:37]
	v_add_u32_e32 v135, 0x80, v135
	v_mfma_f32_16x16x32_bf16 v[46:49], v[184:187], v[176:179], v[46:49]
	v_mfma_f32_16x16x32_bf16 v[10:13], v[184:187], v[180:183], v[10:13]
	ds_read_b128 v[184:187], v130
	ds_read_b128 v[208:211], v130 offset:2048
	ds_read_b128 v[212:215], v130 offset:4096
	ds_read_b128 v[216:219], v130 offset:6144
	s_waitcnt lgkmcnt(8)
	v_mfma_f32_16x16x32_bf16 v[98:101], v[200:203], v[168:171], v[98:101]
	s_add_u32 m0, s9, 0xc000
	v_mfma_f32_16x16x32_bf16 v[66:69], v[200:203], v[172:175], v[66:69]
	global_load_lds_dwordx4 v134, s[38:39]
	v_add_u32_e32 v134, 0x80, v134
	v_mfma_f32_16x16x32_bf16 v[30:33], v[200:203], v[176:179], v[30:33]
	v_mfma_f32_16x16x32_bf16 v[6:9], v[200:203], v[180:183], v[6:9]
	s_waitcnt lgkmcnt(7)
	v_mfma_f32_16x16x32_bf16 v[70:73], v[188:191], v[168:171], v[70:73]
	s_add_u32 m0, s9, 0x6000
	s_waitcnt lgkmcnt(6)
	v_mfma_f32_16x16x32_bf16 v[62:65], v[192:195], v[168:171], v[62:65]
	global_load_lds_dwordx4 v133, s[36:37]
	v_add_u32_e32 v133, 0x80, v133
	v_mfma_f32_16x16x32_bf16 v[38:41], v[188:191], v[172:175], v[38:41]
	v_mfma_f32_16x16x32_bf16 v[34:37], v[192:195], v[172:175], v[34:37]
	ds_read_b128 v[168:171], v220 offset:36864
	ds_read_b128 v[172:175], v220 offset:38912
	v_mfma_f32_16x16x32_bf16 v[18:21], v[188:191], v[176:179], v[18:21]
	s_add_u32 m0, s9, 0xe000
	v_mfma_f32_16x16x32_bf16 v[14:17], v[192:195], v[176:179], v[14:17]
	global_load_lds_dwordx4 v132, s[38:39]
	v_add_u32_e32 v132, 0x80, v132
	v_mfma_f32_16x16x32_bf16 v[2:5], v[188:191], v[180:183], v[2:5]
	v_mfma_f32_16x16x32_bf16 v[90:93], v[192:195], v[180:183], v[90:93]
	ds_read_b128 v[176:179], v220 offset:40960
	ds_read_b128 v[180:183], v220 offset:43008
	s_waitcnt lgkmcnt(7)
	v_mfma_f32_16x16x32_bf16 v[126:129], v[196:199], v[184:187], v[126:129]
	v_mfma_f32_16x16x32_bf16 v[122:125], v[204:207], v[184:187], v[122:125]
	s_waitcnt lgkmcnt(6)
	v_mfma_f32_16x16x32_bf16 v[110:113], v[196:199], v[208:211], v[110:113]
	v_mfma_f32_16x16x32_bf16 v[106:109], v[204:207], v[208:211], v[106:109]
	s_waitcnt lgkmcnt(5)
	v_mfma_f32_16x16x32_bf16 v[82:85], v[196:199], v[212:215], v[82:85]
	v_mfma_f32_16x16x32_bf16 v[78:81], v[204:207], v[212:215], v[78:81]
	s_waitcnt lgkmcnt(4)
	v_mfma_f32_16x16x32_bf16 v[50:53], v[196:199], v[216:219], v[50:53]
	v_mfma_f32_16x16x32_bf16 v[42:45], v[204:207], v[216:219], v[42:45]
	s_waitcnt lgkmcnt(3)
	v_mfma_f32_16x16x32_bf16 v[118:121], v[168:171], v[184:187], v[118:121]
	v_mfma_f32_16x16x32_bf16 v[94:97], v[168:171], v[208:211], v[94:97]
	v_mfma_f32_16x16x32_bf16 v[58:61], v[168:171], v[212:215], v[58:61]
	v_mfma_f32_16x16x32_bf16 v[26:29], v[168:171], v[216:219], v[26:29]
	ds_read_b128 v[168:171], v220 offset:45056
	ds_read_b128 v[188:191], v220 offset:47104
	s_waitcnt lgkmcnt(4)
; template <bool SWAP, class Epi, bool THIN = false> ...
;     ...
;       bf16x8 afA[4], afB[4], bfb[2][2];
; #pragma unroll
;       for (int m = 0; m < 4; ++m) afA[m] = *(const bf16x8*)(sa + m * 2048 + ((fq ^ swz) << 4));
; #pragma unroll
;       for (int n = 0; n < 2; ++n) bfb[0][n] = *(const bf16x8*)(sb + n * 2048 + ((fq ^ swz) << 4));
; #pragma unroll
;       for (int gq = 0; gq < 8; ++gq) {
;         const int ks = gq >> 2, nh = gq & 3;
;         if (gq < 7) {
;           const int ks2 = (gq + 1) >> 2, nh2 = (gq + 1) & 3;
; #pragma unroll
;           for (int n = 0; n < 2; ++n) bfb[(gq + 1) & 1][n] = *(const bf16x8*)(sb + (nh2 * 2 + n) * 2048 + (((ks2 * 4 + fq) ^ swz) << 4));
;         }
;         if (gq == 3) {
; #pragma unroll
;           for (int m = 0; m < 4; ++m) afB[m] = *(const bf16x8*)(sa + m * 2048 + (((4 + fq) ^ swz) << 4));
;         }
;         __builtin_amdgcn_sched_barrier(0);
; #pragma unroll
;         for (int m = 0; m < 4; ++m)
; #pragma unroll
;           for (int n = 0; n < 2; ++n) {
;             const bf16x8 av = ks ? afB[m] : afA[m];
;             acc[m][nh * 2 + n] = SWAP ? __builtin_amdgcn_mfma_f32_16x16x32_bf16(bfb[gq & 1][n], av, acc[m][nh * 2 + n], 0, 0, 0)
;                                       : __builtin_amdgcn_mfma_f32_16x16x32_bf16(av, bfb[gq & 1][n], acc[m][nh * 2 + n], 0, 0, 0);
;           }
;       }
	v_mfma_f32_16x16x32_bf16 v[114:117], v[172:175], v[184:187], v[114:117]
	v_mfma_f32_16x16x32_bf16 v[86:89], v[172:175], v[208:211], v[86:89]
	v_mfma_f32_16x16x32_bf16 v[54:57], v[172:175], v[212:215], v[54:57]
	v_mfma_f32_16x16x32_bf16 v[22:25], v[172:175], v[216:219], v[22:25]
	s_waitcnt lgkmcnt(3)
	v_mfma_f32_16x16x32_bf16 v[102:105], v[176:179], v[184:187], v[102:105]
	s_waitcnt lgkmcnt(2)
	v_mfma_f32_16x16x32_bf16 v[98:101], v[180:183], v[184:187], v[98:101]
	v_mfma_f32_16x16x32_bf16 v[74:77], v[176:179], v[208:211], v[74:77]
	v_mfma_f32_16x16x32_bf16 v[66:69], v[180:183], v[208:211], v[66:69]
	v_mfma_f32_16x16x32_bf16 v[46:49], v[176:179], v[212:215], v[46:49]
	v_mfma_f32_16x16x32_bf16 v[30:33], v[180:183], v[212:215], v[30:33]
	v_mfma_f32_16x16x32_bf16 v[10:13], v[176:179], v[216:219], v[10:13]
	v_mfma_f32_16x16x32_bf16 v[6:9], v[180:183], v[216:219], v[6:9]
	s_waitcnt lgkmcnt(1)
	v_mfma_f32_16x16x32_bf16 v[70:73], v[168:171], v[184:187], v[70:73]
	s_add_i32 s6, s6, 64
	s_cmpk_eq_i32 s6, 0x3c0
	s_mov_b32 s7, s8
	s_waitcnt lgkmcnt(0)
	v_mfma_f32_16x16x32_bf16 v[62:65], v[188:191], v[184:187], v[62:65]
	v_mfma_f32_16x16x32_bf16 v[38:41], v[168:171], v[208:211], v[38:41]
	v_mfma_f32_16x16x32_bf16 v[34:37], v[188:191], v[208:211], v[34:37]
	v_mfma_f32_16x16x32_bf16 v[18:21], v[168:171], v[212:215], v[18:21]
	v_mfma_f32_16x16x32_bf16 v[14:17], v[188:191], v[212:215], v[14:17]
	v_mfma_f32_16x16x32_bf16 v[2:5], v[168:171], v[216:219], v[2:5]
	v_mfma_f32_16x16x32_bf16 v[90:93], v[188:191], v[216:219], v[90:93]
	s_cbranch_scc0 .LBB0_418
	s_waitcnt vmcnt(0)
	s_barrier
	v_add_u32_e32 v130, v153, v141
	ds_read_b128 v[132:135], v130
	ds_read_b128 v[164:167], v130 offset:2048
	ds_read_b128 v[168:171], v130 offset:4096
	ds_read_b128 v[172:175], v130 offset:6144
	v_add_u32_e32 v130, v154, v141
	ds_read_b128 v[176:179], v130
	ds_read_b128 v[180:183], v130 offset:2048
	ds_read_b128 v[184:187], v130 offset:4096
	ds_read_b128 v[188:191], v130 offset:6144
	s_waitcnt lgkmcnt(0)
	v_mfma_f32_16x16x32_bf16 v[126:129], v[176:179], v[132:135], v[126:129]
	v_mfma_f32_16x16x32_bf16 v[110:113], v[176:179], v[164:167], v[110:113]
	v_mfma_f32_16x16x32_bf16 v[82:85], v[176:179], v[168:171], v[82:85]
	v_mfma_f32_16x16x32_bf16 v[50:53], v[176:179], v[172:175], v[50:53]
	ds_read_b128 v[176:179], v130 offset:8192
	ds_read_b128 v[192:195], v130 offset:10240
	v_mfma_f32_16x16x32_bf16 v[122:125], v[180:183], v[132:135], v[122:125]
	v_mfma_f32_16x16x32_bf16 v[106:109], v[180:183], v[164:167], v[106:109]
	v_mfma_f32_16x16x32_bf16 v[78:81], v[180:183], v[168:171], v[78:81]
	v_mfma_f32_16x16x32_bf16 v[42:45], v[180:183], v[172:175], v[42:45]
	v_mfma_f32_16x16x32_bf16 v[118:121], v[184:187], v[132:135], v[118:121]
	v_mfma_f32_16x16x32_bf16 v[180:183], v[184:187], v[164:167], v[94:97]
	v_mfma_f32_16x16x32_bf16 v[200:203], v[184:187], v[168:171], v[58:61]
	v_mfma_f32_16x16x32_bf16 v[204:207], v[188:191], v[168:171], v[54:57]
	v_mfma_f32_16x16x32_bf16 v[184:187], v[184:187], v[172:175], v[26:29]
	s_nop 2
	ds_read_b128 v[26:29], v130 offset:12288
	ds_read_b128 v[54:57], v130 offset:14336
	v_mfma_f32_16x16x32_bf16 v[114:117], v[188:191], v[132:135], v[114:117]
	v_mfma_f32_16x16x32_bf16 v[196:199], v[188:191], v[164:167], v[86:89]
	v_mfma_f32_16x16x32_bf16 v[188:191], v[188:191], v[172:175], v[22:25]
	v_add_u32_e32 v130, v154, v142
	s_waitcnt lgkmcnt(0)
	v_mfma_f32_16x16x32_bf16 v[208:211], v[192:195], v[168:171], v[30:33]
	ds_read_b128 v[22:25], v130
	ds_read_b128 v[86:89], v130 offset:2048
	s_nop 0
	v_add_u32_e32 v30, v153, v142
	v_mfma_f32_16x16x32_bf16 v[102:105], v[176:179], v[132:135], v[102:105]
	v_mfma_f32_16x16x32_bf16 v[74:77], v[176:179], v[164:167], v[74:77]
	v_mfma_f32_16x16x32_bf16 v[46:49], v[176:179], v[168:171], v[46:49]
	v_mfma_f32_16x16x32_bf16 v[10:13], v[176:179], v[172:175], v[10:13]
	ds_read_b128 v[176:179], v30
	ds_read_b128 v[212:215], v30 offset:2048
	ds_read_b128 v[216:219], v30 offset:4096
	ds_read_b128 v[220:223], v30 offset:6144
	v_mfma_f32_16x16x32_bf16 v[98:101], v[192:195], v[132:135], v[98:101]
	v_mfma_f32_16x16x32_bf16 v[66:69], v[192:195], v[164:167], v[66:69]
	v_mfma_f32_16x16x32_bf16 v[6:9], v[192:195], v[172:175], v[6:9]
	v_mfma_f32_16x16x32_bf16 v[38:41], v[26:29], v[164:167], v[38:41]
	v_mfma_f32_16x16x32_bf16 v[34:37], v[54:57], v[164:167], v[34:37]
	v_mfma_f32_16x16x32_bf16 v[192:195], v[26:29], v[168:171], v[18:21]
	v_mfma_f32_16x16x32_bf16 v[166:169], v[54:57], v[168:171], v[14:17]
	s_nop 2
	ds_read_b128 v[14:17], v130 offset:4096
	ds_read_b128 v[18:21], v130 offset:6144
	v_mfma_f32_16x16x32_bf16 v[70:73], v[26:29], v[132:135], v[70:73]
	v_mfma_f32_16x16x32_bf16 v[132:135], v[54:57], v[132:135], v[62:65]
	v_mfma_f32_16x16x32_bf16 v[2:5], v[26:29], v[172:175], v[2:5]
	v_mfma_f32_16x16x32_bf16 v[170:173], v[54:57], v[172:175], v[90:93]
	ds_read_b128 v[224:227], v130 offset:8192
	ds_read_b128 v[228:231], v130 offset:10240
	s_waitcnt lgkmcnt(0)
	v_mfma_f32_16x16x32_bf16 v[126:129], v[22:25], v[176:179], v[126:129]
	v_mfma_f32_16x16x32_bf16 v[122:125], v[86:89], v[176:179], v[122:125]
	v_mfma_f32_16x16x32_bf16 v[94:97], v[22:25], v[212:215], v[110:113]
	v_mfma_f32_16x16x32_bf16 v[90:93], v[86:89], v[212:215], v[106:109]
	v_mfma_f32_16x16x32_bf16 v[62:65], v[22:25], v[216:219], v[82:85]
	v_mfma_f32_16x16x32_bf16 v[58:61], v[86:89], v[216:219], v[78:81]
	v_mfma_f32_16x16x32_bf16 v[30:33], v[22:25], v[220:223], v[50:53]
	v_mfma_f32_16x16x32_bf16 v[26:29], v[86:89], v[220:223], v[42:45]
	v_mfma_f32_16x16x32_bf16 v[86:89], v[14:17], v[212:215], v[180:183]
	v_mfma_f32_16x16x32_bf16 v[22:25], v[14:17], v[220:223], v[184:187]
	s_nop 1
	ds_read_b128 v[180:183], v130 offset:12288
	ds_read_b128 v[184:187], v130 offset:14336
	v_mfma_f32_16x16x32_bf16 v[118:121], v[14:17], v[176:179], v[118:121]
	v_mfma_f32_16x16x32_bf16 v[114:117], v[18:21], v[176:179], v[114:117]
	v_mfma_f32_16x16x32_bf16 v[82:85], v[18:21], v[212:215], v[196:199]
	v_mfma_f32_16x16x32_bf16 v[54:57], v[14:17], v[216:219], v[200:203]
	v_mfma_f32_16x16x32_bf16 v[50:53], v[18:21], v[216:219], v[204:207]
	v_mfma_f32_16x16x32_bf16 v[18:21], v[18:21], v[220:223], v[188:191]
	v_mfma_f32_16x16x32_bf16 v[110:113], v[224:227], v[176:179], v[102:105]
	v_mfma_f32_16x16x32_bf16 v[106:109], v[228:231], v[176:179], v[98:101]
	v_mfma_f32_16x16x32_bf16 v[78:81], v[224:227], v[212:215], v[74:77]
	v_mfma_f32_16x16x32_bf16 v[74:77], v[228:231], v[212:215], v[66:69]
	v_mfma_f32_16x16x32_bf16 v[46:49], v[224:227], v[216:219], v[46:49]
	v_mfma_f32_16x16x32_bf16 v[42:45], v[228:231], v[216:219], v[208:211]
	v_mfma_f32_16x16x32_bf16 v[14:17], v[224:227], v[220:223], v[10:13]
	v_mfma_f32_16x16x32_bf16 v[10:13], v[228:231], v[220:223], v[6:9]
	s_nop 2
	v_mov_b32_e32 v6, v1
	s_waitcnt vmcnt(0) lgkmcnt(0)
	s_barrier
; __device__ __forceinline__ int get_tid512() { int t = threadIdx.x; asm volatile("" : "+v"(t)); return t; }
; __device__ __forceinline__ unsigned pack2(float a, float b) { unsigned r; asm("v_cvt_pk_bf16_f32 %0, %1, %2" : "=v"(r) : "v"(a), "v"(b)); return r; }
;   __device__ __forceinline__ float c4(int g, int rig, int col, f32x4 v) const {
;     ...
;     uint2 u; u.x = pack2(v[0], v[1]); u.y = pack2(v[2], v[3]);
;     *(uint2*)(out + row * ld + col) = u;
;     return v[0] * v[0] + v[1] * v[1] + v[2] * v[2] + v[3] * v[3];
;   }
;   __device__ __forceinline__ void rowsum(int g, int rig, int slot, float ss) const {
;     if (slot < nslots) part[(size_t)slot * ((size_t)8 * ostride) + (size_t)g * ostride + rig] = ss;
; template <bool SWAP, class Epi, bool THIN = false> ...
;     ...
;     __syncthreads();
;     const int te = get_tid512();
;     const int fr_e = te & 15, fq_e = (te & 63) >> 4, wr_e = te >> 7, wc_e = (te >> 6) & 1;
;     const int sub = 2 * mt + (wr_e >> 1);
;     const int g = sub / tpg, ti = sub - g * tpg;
;     const int rig0 = ti * step - halo;
;     const int rw = (wr_e & 1) * 64;
;     if constexpr (Epi::KIND == 0) {
; #pragma unroll
;       for (int m = 0; m < 4; ++m) {
;         const int rig = rig0 + rw + m * 16 + fr_e;
;         if constexpr (Epi::ROWSUM) {
;           float ss = 0.f;
; #pragma unroll
;           for (int n = 0; n < 8; ++n) {
;             const int col = nt * 256 + wc_e * 128 + n * 16 + fq_e * 4;
;             if (col < N) ss += epi.c4(g, rig, col, acc[m][n]);
;           }
;           ss += __shfl_xor(ss, 16); ss += __shfl_xor(ss, 32);
;           if (fq_e == 0) epi.rowsum(g, rig, nt * 2 + wc_e, ss);
	v_mfma_f32_16x16x32_bf16 v[98:101], v[184:187], v[176:179], v[132:135]
	v_ashrrev_i32_e32 v7, 8, v6
	v_add_u32_e32 v7, s5, v7
	v_mul_hi_i32 v8, v7, s23
	v_lshrrev_b32_e32 v9, 31, v8
	v_ashrrev_i32_e32 v8, 2, v8
	v_add_u32_e32 v130, v8, v9
	v_and_b32_e32 v132, 15, v6
	v_bfe_u32 v164, v6, 4, 2
	v_bfe_u32 v165, v6, 6, 1
	v_mul_lo_u32 v8, v130, s24
	v_lshrrev_b32_e32 v6, 1, v6
	v_mfma_f32_16x16x32_bf16 v[102:105], v[180:183], v[176:179], v[70:73]
	v_add_lshl_u32 v133, v8, v7, 7
	v_and_b32_e32 v135, 64, v6
	v_lshlrev_b32_e32 v134, 7, v165
	v_mfma_f32_16x16x32_bf16 v[70:73], v[180:183], v[212:215], v[38:41]
	v_or3_b32 v132, v133, v135, v132
	v_ashrrev_i32_e32 v133, 31, v132
	v_mfma_f32_16x16x32_bf16 v[66:69], v[184:187], v[212:215], v[34:37]
	v_mfma_f32_16x16x32_bf16 v[38:41], v[180:183], v[216:219], v[192:195]
	v_mfma_f32_16x16x32_bf16 v[34:37], v[184:187], v[216:219], v[166:169]
	v_mfma_f32_16x16x32_bf16 v[6:9], v[180:183], v[220:223], v[2:5]
	s_nop 1
	v_lshlrev_b32_e32 v166, 2, v164
	v_or3_b32 v134, v134, v166, s4
	v_cmp_gt_i32_e32 vcc, s27, v134
	v_mfma_f32_16x16x32_bf16 v[2:5], v[184:187], v[220:223], v[170:173]
	v_mov_b32_e32 v166, 0
	v_ashrrev_i32_e32 v135, 31, v134
	s_and_saveexec_b64 s[4:5], vcc
	s_cbranch_execz .LBB0_421
	v_mad_i64_i32 v[166:167], s[6:7], v130, s25, v[132:133]
	v_mov_b64_e32 v[170:171], s[30:31]
	v_cvt_pk_bf16_f32 v168, v126, v127
	v_mad_u64_u32 v[170:171], s[6:7], v166, s28, v[170:171]
	v_pk_mul_f32 v[126:127], v[126:127], v[126:127]
	v_cvt_pk_bf16_f32 v169, v128, v129
	v_mad_i32_i24 v171, v167, s28, v171
	v_pk_mul_f32 v[128:129], v[128:129], v[128:129]
	v_add_f32_e32 v126, v126, v127
	v_lshl_add_u64 v[166:167], v[134:135], 1, v[170:171]
	v_add_f32_e32 v126, v128, v126
	global_store_dwordx2 v[166:167], v[168:169], off
	v_add_f32_e32 v166, v129, v126

; template <bool SWAP, class Epi, bool THIN = false> ...
;     ...
;     for (int st = 0; st < ns; ++st) {
;       asm volatile("s_waitcnt vmcnt(0)" ::: "memory");
;       __builtin_amdgcn_s_barrier();
;       asm volatile("" ::: "memory");
;       if (st + 1 < ns) {
;         char* nb = smem + ((st + 1) & 1) * 65536;
;         const int ko = (st + 1) * 64;
; #pragma unroll
;         for (int i = 0; i < 4; ++i) { GLDS16(A + (size_t)(ap[i] + ko), nb + tid * 16 + i * 8192); GLDS16(Bt + (size_t)(bp[i] + ko), nb + 32768 + tid * 16 + i * 8192); }
;       }
;       const char* sa = smem + (st & 1) * 65536 + (wr * 64 + fr) * 128;
;       const char* sb = smem + (st & 1) * 65536 + 32768 + (wc * 128 + fr) * 128;
;       if constexpr (THIN) {
;         if (wc == 0) {
; #pragma unroll
;           for (int ks = 0; ks < 2; ++ks) {
;             bf16x8 af[4], bf[2];
; #pragma unroll
;             for (int m = 0; m < 4; ++m) af[m] = *(const bf16x8*)(sa + m * 2048 + (((ks * 4 + fq) ^ swz) << 4));
; #pragma unroll
;             for (int n = 0; n < 2; ++n) bf[n] = *(const bf16x8*)(sb + n * 2048 + (((ks * 4 + fq) ^ swz) << 4));
; #pragma unroll
;             for (int m = 0; m < 4; ++m)
; #pragma unroll
;               for (int n = 0; n < 2; ++n)
;                 acc[m][n] = SWAP ? __builtin_amdgcn_mfma_f32_16x16x32_bf16(bf[n], af[m], acc[m][n], 0, 0, 0)
;                                  : __builtin_amdgcn_mfma_f32_16x16x32_bf16(af[m], bf[n], acc[m][n], 0, 0, 0);
;           }
;         }
;       } else {
;       bf16x8 afA[4], afB[4], bfb[2][2];
; #pragma unroll
;       for (int m = 0; m < 4; ++m) afA[m] = *(const bf16x8*)(sa + m * 2048 + ((fq ^ swz) << 4));
; #pragma unroll
;       for (int n = 0; n < 2; ++n) bfb[0][n] = *(const bf16x8*)(sb + n * 2048 + ((fq ^ swz) << 4));
; #pragma unroll
;       for (int gq = 0; gq < 8; ++gq) {
;         const int ks = gq >> 2, nh = gq & 3;
;         if (gq < 7) {
;           const int ks2 = (gq + 1) >> 2, nh2 = (gq + 1) & 3;
; #pragma unroll
;           for (int n = 0; n < 2; ++n) bfb[(gq + 1) & 1][n] = *(const bf16x8*)(sb + (nh2 * 2 + n) * 2048 + (((ks2 * 4 + fq) ^ swz) << 4));
;         }
;         if (gq == 3) {
; #pragma unroll
;           for (int m = 0; m < 4; ++m) afB[m] = *(const bf16x8*)(sa + m * 2048 + (((4 + fq) ^ swz) << 4));
;         }
;         __builtin_amdgcn_sched_barrier(0);
; #pragma unroll
.LBB0_2116:
	s_add_i32 s8, s7, 0x10000
	s_and_b32 s9, s8, 0x10000
	v_add_u32_e32 v169, s9, v144
	s_nop 0
	v_readfirstlane_b32 s9, v169
	s_waitcnt vmcnt(0)
	s_barrier
	s_and_b32 s7, s7, 0x10000
	v_add_u32_e32 v130, s7, v145
	v_add_u32_e32 v140, v130, v147
	ds_read_b128 v[170:173], v140
	ds_read_b128 v[174:177], v140 offset:2048
	ds_read_b128 v[178:181], v140 offset:4096
	ds_read_b128 v[182:185], v140 offset:6144
	v_or_b32_e32 v140, s7, v146
	v_add_u32_e32 v141, v140, v147
	ds_read_b128 v[186:189], v141 offset:32768
	ds_read_b128 v[190:193], v141 offset:34816
	ds_read_b128 v[194:197], v141 offset:36864
	ds_read_b128 v[198:201], v141 offset:38912
	v_add_u32_e32 v130, v130, v148
	s_waitcnt lgkmcnt(3)
	v_mfma_f32_16x16x32_bf16 v[126:129], v[186:189], v[170:173], v[126:129]
	s_mov_b32 m0, s9
	v_mfma_f32_16x16x32_bf16 v[110:113], v[186:189], v[174:177], v[110:113]
	global_load_lds_dwordx4 v139, s[18:19]
	v_add_u32_e32 v139, 0x80, v139
	v_mfma_f32_16x16x32_bf16 v[82:85], v[186:189], v[178:181], v[82:85]
	v_mfma_f32_16x16x32_bf16 v[50:53], v[186:189], v[182:185], v[50:53]
	ds_read_b128 v[186:189], v141 offset:40960
	ds_read_b128 v[202:205], v141 offset:43008
	s_waitcnt lgkmcnt(4)
	v_mfma_f32_16x16x32_bf16 v[122:125], v[190:193], v[170:173], v[122:125]
	s_add_u32 m0, s9, 0x8000
	v_mfma_f32_16x16x32_bf16 v[106:109], v[190:193], v[174:177], v[106:109]
	global_load_lds_dwordx4 v138, s[24:25]
	v_add_u32_e32 v138, 0x80, v138
	v_mfma_f32_16x16x32_bf16 v[78:81], v[190:193], v[178:181], v[78:81]
	v_mfma_f32_16x16x32_bf16 v[42:45], v[190:193], v[182:185], v[42:45]
	s_waitcnt lgkmcnt(3)
	v_mfma_f32_16x16x32_bf16 v[118:121], v[194:197], v[170:173], v[118:121]
	s_add_u32 m0, s9, 0x2000
	v_mfma_f32_16x16x32_bf16 v[94:97], v[194:197], v[174:177], v[94:97]
	global_load_lds_dwordx4 v137, s[18:19]
	v_add_u32_e32 v137, 0x80, v137
	v_mfma_f32_16x16x32_bf16 v[58:61], v[194:197], v[178:181], v[58:61]
	v_mfma_f32_16x16x32_bf16 v[26:29], v[194:197], v[182:185], v[26:29]
	ds_read_b128 v[190:193], v141 offset:45056
	ds_read_b128 v[194:197], v141 offset:47104
	s_waitcnt lgkmcnt(4)
	v_mfma_f32_16x16x32_bf16 v[114:117], v[198:201], v[170:173], v[114:117]
	s_add_u32 m0, s9, 0xa000
	v_mfma_f32_16x16x32_bf16 v[86:89], v[198:201], v[174:177], v[86:89]
	global_load_lds_dwordx4 v136, s[24:25]
	v_add_u32_e32 v136, 0x80, v136
	v_mfma_f32_16x16x32_bf16 v[54:57], v[198:201], v[178:181], v[54:57]
	v_mfma_f32_16x16x32_bf16 v[22:25], v[198:201], v[182:185], v[22:25]
	v_add_u32_e32 v140, v140, v148
	s_waitcnt lgkmcnt(3)
	v_mfma_f32_16x16x32_bf16 v[102:105], v[186:189], v[170:173], v[102:105]
	ds_read_b128 v[198:201], v140 offset:32768
	ds_read_b128 v[206:209], v140 offset:34816
	s_add_u32 m0, s9, 0x4000
	v_mfma_f32_16x16x32_bf16 v[74:77], v[186:189], v[174:177], v[74:77]
	global_load_lds_dwordx4 v135, s[18:19]
	v_add_u32_e32 v135, 0x80, v135
	v_mfma_f32_16x16x32_bf16 v[46:49], v[186:189], v[178:181], v[46:49]
	v_mfma_f32_16x16x32_bf16 v[10:13], v[186:189], v[182:185], v[10:13]
	ds_read_b128 v[186:189], v130
	ds_read_b128 v[210:213], v130 offset:2048
	ds_read_b128 v[214:217], v130 offset:4096
	ds_read_b128 v[218:221], v130 offset:6144
	s_waitcnt lgkmcnt(8)
	v_mfma_f32_16x16x32_bf16 v[98:101], v[202:205], v[170:173], v[98:101]
	s_add_u32 m0, s9, 0xc000
	v_mfma_f32_16x16x32_bf16 v[66:69], v[202:205], v[174:177], v[66:69]
	global_load_lds_dwordx4 v134, s[24:25]
	v_add_u32_e32 v134, 0x80, v134
	v_mfma_f32_16x16x32_bf16 v[30:33], v[202:205], v[178:181], v[30:33]
	v_mfma_f32_16x16x32_bf16 v[6:9], v[202:205], v[182:185], v[6:9]
	s_waitcnt lgkmcnt(7)
	v_mfma_f32_16x16x32_bf16 v[70:73], v[190:193], v[170:173], v[70:73]
	s_add_u32 m0, s9, 0x6000
	s_waitcnt lgkmcnt(6)
	v_mfma_f32_16x16x32_bf16 v[62:65], v[194:197], v[170:173], v[62:65]
	global_load_lds_dwordx4 v133, s[18:19]
	v_add_u32_e32 v133, 0x80, v133
	v_mfma_f32_16x16x32_bf16 v[38:41], v[190:193], v[174:177], v[38:41]
	v_mfma_f32_16x16x32_bf16 v[34:37], v[194:197], v[174:177], v[34:37]
	ds_read_b128 v[170:173], v140 offset:36864
	ds_read_b128 v[174:177], v140 offset:38912
	v_mfma_f32_16x16x32_bf16 v[18:21], v[190:193], v[178:181], v[18:21]
	s_add_u32 m0, s9, 0xe000
	v_mfma_f32_16x16x32_bf16 v[14:17], v[194:197], v[178:181], v[14:17]
	global_load_lds_dwordx4 v132, s[24:25]
	v_add_u32_e32 v132, 0x80, v132
	v_mfma_f32_16x16x32_bf16 v[2:5], v[190:193], v[182:185], v[2:5]
	v_mfma_f32_16x16x32_bf16 v[90:93], v[194:197], v[182:185], v[90:93]
	ds_read_b128 v[178:181], v140 offset:40960
	ds_read_b128 v[182:185], v140 offset:43008
	s_waitcnt lgkmcnt(7)
	v_mfma_f32_16x16x32_bf16 v[126:129], v[198:201], v[186:189], v[126:129]
	v_mfma_f32_16x16x32_bf16 v[122:125], v[206:209], v[186:189], v[122:125]
	s_waitcnt lgkmcnt(6)
	v_mfma_f32_16x16x32_bf16 v[110:113], v[198:201], v[210:213], v[110:113]
	v_mfma_f32_16x16x32_bf16 v[106:109], v[206:209], v[210:213], v[106:109]
	s_waitcnt lgkmcnt(5)
	v_mfma_f32_16x16x32_bf16 v[82:85], v[198:201], v[214:217], v[82:85]
	v_mfma_f32_16x16x32_bf16 v[78:81], v[206:209], v[214:217], v[78:81]
	s_waitcnt lgkmcnt(4)
	v_mfma_f32_16x16x32_bf16 v[50:53], v[198:201], v[218:221], v[50:53]
	v_mfma_f32_16x16x32_bf16 v[42:45], v[206:209], v[218:221], v[42:45]
	s_waitcnt lgkmcnt(3)
	v_mfma_f32_16x16x32_bf16 v[118:121], v[170:173], v[186:189], v[118:121]
	v_mfma_f32_16x16x32_bf16 v[94:97], v[170:173], v[210:213], v[94:97]
	v_mfma_f32_16x16x32_bf16 v[58:61], v[170:173], v[214:217], v[58:61]
	v_mfma_f32_16x16x32_bf16 v[26:29], v[170:173], v[218:221], v[26:29]
	ds_read_b128 v[170:173], v140 offset:45056
	ds_read_b128 v[190:193], v140 offset:47104
	s_waitcnt lgkmcnt(4)
; template <bool SWAP, class Epi, bool THIN = false> ...
;     ...
;       bf16x8 afA[4], afB[4], bfb[2][2];
; #pragma unroll
;       for (int m = 0; m < 4; ++m) afA[m] = *(const bf16x8*)(sa + m * 2048 + ((fq ^ swz) << 4));
; #pragma unroll
;       for (int n = 0; n < 2; ++n) bfb[0][n] = *(const bf16x8*)(sb + n * 2048 + ((fq ^ swz) << 4));
; #pragma unroll
;       for (int gq = 0; gq < 8; ++gq) {
;         const int ks = gq >> 2, nh = gq & 3;
;         if (gq < 7) {
;           const int ks2 = (gq + 1) >> 2, nh2 = (gq + 1) & 3;
; #pragma unroll
;           for (int n = 0; n < 2; ++n) bfb[(gq + 1) & 1][n] = *(const bf16x8*)(sb + (nh2 * 2 + n) * 2048 + (((ks2 * 4 + fq) ^ swz) << 4));
;         }
;         if (gq == 3) {
; #pragma unroll
;           for (int m = 0; m < 4; ++m) afB[m] = *(const bf16x8*)(sa + m * 2048 + (((4 + fq) ^ swz) << 4));
;         }
;         __builtin_amdgcn_sched_barrier(0);
; #pragma unroll
;         for (int m = 0; m < 4; ++m)
; #pragma unroll
;           for (int n = 0; n < 2; ++n) {
;             const bf16x8 av = ks ? afB[m] : afA[m];
;             acc[m][nh * 2 + n] = SWAP ? __builtin_amdgcn_mfma_f32_16x16x32_bf16(bfb[gq & 1][n], av, acc[m][nh * 2 + n], 0, 0, 0)
;                                       : __builtin_amdgcn_mfma_f32_16x16x32_bf16(av, bfb[gq & 1][n], acc[m][nh * 2 + n], 0, 0, 0);
;           }
;       }
	v_mfma_f32_16x16x32_bf16 v[114:117], v[174:177], v[186:189], v[114:117]
	v_mfma_f32_16x16x32_bf16 v[86:89], v[174:177], v[210:213], v[86:89]
	v_mfma_f32_16x16x32_bf16 v[54:57], v[174:177], v[214:217], v[54:57]
	v_mfma_f32_16x16x32_bf16 v[22:25], v[174:177], v[218:221], v[22:25]
	s_waitcnt lgkmcnt(3)
	v_mfma_f32_16x16x32_bf16 v[102:105], v[178:181], v[186:189], v[102:105]
	s_waitcnt lgkmcnt(2)
	v_mfma_f32_16x16x32_bf16 v[98:101], v[182:185], v[186:189], v[98:101]
	v_mfma_f32_16x16x32_bf16 v[74:77], v[178:181], v[210:213], v[74:77]
	v_mfma_f32_16x16x32_bf16 v[66:69], v[182:185], v[210:213], v[66:69]
	v_mfma_f32_16x16x32_bf16 v[46:49], v[178:181], v[214:217], v[46:49]
	v_mfma_f32_16x16x32_bf16 v[30:33], v[182:185], v[214:217], v[30:33]
	v_mfma_f32_16x16x32_bf16 v[10:13], v[178:181], v[218:221], v[10:13]
	v_mfma_f32_16x16x32_bf16 v[6:9], v[182:185], v[218:221], v[6:9]
	s_waitcnt lgkmcnt(1)
	v_mfma_f32_16x16x32_bf16 v[70:73], v[170:173], v[186:189], v[70:73]
	s_add_i32 s6, s6, 64
	s_cmpk_eq_i32 s6, 0x3c0
	s_mov_b32 s7, s8
	s_waitcnt lgkmcnt(0)
	v_mfma_f32_16x16x32_bf16 v[62:65], v[190:193], v[186:189], v[62:65]
	v_mfma_f32_16x16x32_bf16 v[38:41], v[170:173], v[210:213], v[38:41]
	v_mfma_f32_16x16x32_bf16 v[34:37], v[190:193], v[210:213], v[34:37]
	v_mfma_f32_16x16x32_bf16 v[18:21], v[170:173], v[214:217], v[18:21]
	v_mfma_f32_16x16x32_bf16 v[14:17], v[190:193], v[214:217], v[14:17]
	v_mfma_f32_16x16x32_bf16 v[2:5], v[170:173], v[218:221], v[2:5]
	v_mfma_f32_16x16x32_bf16 v[90:93], v[190:193], v[218:221], v[90:93]
	s_cbranch_scc0 .LBB0_2116
	s_waitcnt vmcnt(0)
	s_barrier
	v_add_u32_e32 v130, v159, v147
	ds_read_b128 v[132:135], v130
	ds_read_b128 v[136:139], v130 offset:2048
	ds_read_b128 v[170:173], v130 offset:4096
	ds_read_b128 v[174:177], v130 offset:6144
	v_add_u32_e32 v130, v160, v147
	ds_read_b128 v[178:181], v130
	ds_read_b128 v[182:185], v130 offset:2048
	ds_read_b128 v[186:189], v130 offset:4096
	ds_read_b128 v[190:193], v130 offset:6144
	s_waitcnt lgkmcnt(0)
	v_mfma_f32_16x16x32_bf16 v[126:129], v[178:181], v[132:135], v[126:129]
	v_mfma_f32_16x16x32_bf16 v[110:113], v[178:181], v[136:139], v[110:113]
	v_mfma_f32_16x16x32_bf16 v[82:85], v[178:181], v[170:173], v[82:85]
	v_mfma_f32_16x16x32_bf16 v[50:53], v[178:181], v[174:177], v[50:53]
	ds_read_b128 v[178:181], v130 offset:8192
	ds_read_b128 v[194:197], v130 offset:10240
	v_mfma_f32_16x16x32_bf16 v[122:125], v[182:185], v[132:135], v[122:125]
	v_mfma_f32_16x16x32_bf16 v[106:109], v[182:185], v[136:139], v[106:109]
	v_mfma_f32_16x16x32_bf16 v[78:81], v[182:185], v[170:173], v[78:81]
	v_mfma_f32_16x16x32_bf16 v[42:45], v[182:185], v[174:177], v[42:45]
	v_mfma_f32_16x16x32_bf16 v[118:121], v[186:189], v[132:135], v[118:121]
	v_mfma_f32_16x16x32_bf16 v[182:185], v[186:189], v[136:139], v[94:97]
	v_mfma_f32_16x16x32_bf16 v[202:205], v[186:189], v[170:173], v[58:61]
	v_mfma_f32_16x16x32_bf16 v[206:209], v[190:193], v[170:173], v[54:57]
	v_mfma_f32_16x16x32_bf16 v[186:189], v[186:189], v[174:177], v[26:29]
	s_nop 2
	ds_read_b128 v[26:29], v130 offset:12288
	ds_read_b128 v[54:57], v130 offset:14336
	v_mfma_f32_16x16x32_bf16 v[114:117], v[190:193], v[132:135], v[114:117]
	v_mfma_f32_16x16x32_bf16 v[198:201], v[190:193], v[136:139], v[86:89]
	v_mfma_f32_16x16x32_bf16 v[190:193], v[190:193], v[174:177], v[22:25]
	v_add_u32_e32 v130, v160, v148
	s_waitcnt lgkmcnt(0)
	v_mfma_f32_16x16x32_bf16 v[210:213], v[194:197], v[170:173], v[30:33]
	ds_read_b128 v[22:25], v130
	ds_read_b128 v[86:89], v130 offset:2048
	s_nop 0
	v_add_u32_e32 v30, v159, v148
	v_mfma_f32_16x16x32_bf16 v[102:105], v[178:181], v[132:135], v[102:105]
	v_mfma_f32_16x16x32_bf16 v[74:77], v[178:181], v[136:139], v[74:77]
	v_mfma_f32_16x16x32_bf16 v[46:49], v[178:181], v[170:173], v[46:49]
	v_mfma_f32_16x16x32_bf16 v[10:13], v[178:181], v[174:177], v[10:13]
	ds_read_b128 v[178:181], v30
	ds_read_b128 v[214:217], v30 offset:2048
	ds_read_b128 v[218:221], v30 offset:4096
	ds_read_b128 v[222:225], v30 offset:6144
	v_mfma_f32_16x16x32_bf16 v[98:101], v[194:197], v[132:135], v[98:101]
	v_mfma_f32_16x16x32_bf16 v[66:69], v[194:197], v[136:139], v[66:69]
	v_mfma_f32_16x16x32_bf16 v[6:9], v[194:197], v[174:177], v[6:9]
	v_mfma_f32_16x16x32_bf16 v[38:41], v[26:29], v[136:139], v[38:41]
	v_mfma_f32_16x16x32_bf16 v[34:37], v[54:57], v[136:139], v[34:37]
	v_mfma_f32_16x16x32_bf16 v[136:139], v[26:29], v[170:173], v[18:21]
	v_mfma_f32_16x16x32_bf16 v[170:173], v[54:57], v[170:173], v[14:17]
	s_nop 2
	ds_read_b128 v[14:17], v130 offset:4096
	ds_read_b128 v[18:21], v130 offset:6144
	v_mfma_f32_16x16x32_bf16 v[70:73], v[26:29], v[132:135], v[70:73]
	v_mfma_f32_16x16x32_bf16 v[132:135], v[54:57], v[132:135], v[62:65]
	v_mfma_f32_16x16x32_bf16 v[2:5], v[26:29], v[174:177], v[2:5]
	v_mfma_f32_16x16x32_bf16 v[174:177], v[54:57], v[174:177], v[90:93]
	ds_read_b128 v[194:197], v130 offset:8192
	ds_read_b128 v[226:229], v130 offset:10240
	s_waitcnt lgkmcnt(0)
	v_mfma_f32_16x16x32_bf16 v[126:129], v[22:25], v[178:181], v[126:129]
	v_mfma_f32_16x16x32_bf16 v[122:125], v[86:89], v[178:181], v[122:125]
	v_mfma_f32_16x16x32_bf16 v[94:97], v[22:25], v[214:217], v[110:113]
	v_mfma_f32_16x16x32_bf16 v[90:93], v[86:89], v[214:217], v[106:109]
	v_mfma_f32_16x16x32_bf16 v[62:65], v[22:25], v[218:221], v[82:85]
	v_mfma_f32_16x16x32_bf16 v[58:61], v[86:89], v[218:221], v[78:81]
	v_mfma_f32_16x16x32_bf16 v[30:33], v[22:25], v[222:225], v[50:53]
	v_mfma_f32_16x16x32_bf16 v[26:29], v[86:89], v[222:225], v[42:45]
	v_mfma_f32_16x16x32_bf16 v[86:89], v[14:17], v[214:217], v[182:185]
	v_mfma_f32_16x16x32_bf16 v[22:25], v[14:17], v[222:225], v[186:189]
	s_nop 1
	ds_read_b128 v[182:185], v130 offset:12288
	ds_read_b128 v[186:189], v130 offset:14336
	v_mfma_f32_16x16x32_bf16 v[118:121], v[14:17], v[178:181], v[118:121]
	v_mfma_f32_16x16x32_bf16 v[114:117], v[18:21], v[178:181], v[114:117]
	v_mfma_f32_16x16x32_bf16 v[82:85], v[18:21], v[214:217], v[198:201]
	v_mfma_f32_16x16x32_bf16 v[54:57], v[14:17], v[218:221], v[202:205]
	v_mfma_f32_16x16x32_bf16 v[50:53], v[18:21], v[218:221], v[206:209]
	v_mfma_f32_16x16x32_bf16 v[18:21], v[18:21], v[222:225], v[190:193]
	v_mfma_f32_16x16x32_bf16 v[110:113], v[194:197], v[178:181], v[102:105]
	v_mfma_f32_16x16x32_bf16 v[106:109], v[226:229], v[178:181], v[98:101]
	v_mfma_f32_16x16x32_bf16 v[78:81], v[194:197], v[214:217], v[74:77]
	v_mfma_f32_16x16x32_bf16 v[74:77], v[226:229], v[214:217], v[66:69]
	v_mfma_f32_16x16x32_bf16 v[46:49], v[194:197], v[218:221], v[46:49]
	v_mfma_f32_16x16x32_bf16 v[42:45], v[226:229], v[218:221], v[210:213]
	v_mfma_f32_16x16x32_bf16 v[14:17], v[194:197], v[222:225], v[10:13]
	v_mfma_f32_16x16x32_bf16 v[6:9], v[226:229], v[222:225], v[6:9]
	v_mov_b32_e32 v130, v1
	s_waitcnt vmcnt(0) lgkmcnt(0)
	s_barrier
; __device__ __forceinline__ int get_tid512() { int t = threadIdx.x; asm volatile("" : "+v"(t)); return t; }
; __device__ __forceinline__ unsigned pack2(float a, float b) { unsigned r; asm("v_cvt_pk_bf16_f32 %0, %1, %2" : "=v"(r) : "v"(a), "v"(b)); return r; }
; __device__ __forceinline__ float bf2f(bf16_t h) { return __uint_as_float(((unsigned)h) << 16); }
;   __device__ __forceinline__ void c4(int g, int rig, int col, f32x4 v) const {
;     const size_t o = ((size_t)g * 2048 + rig) * 1024 + col;
;     f32x4 bs;
;     if (BASE_F32) bs = __builtin_nontemporal_load((const f32x4*)((const float*)base + o));
;     else {
;       const uint2 u = *(const uint2*)((const bf16_t*)base + o);
;       bs[0] = bf2f((bf16_t)(u.x & 0xffff)); bs[1] = bf2f((bf16_t)(u.x >> 16)); bs[2] = bf2f((bf16_t)(u.y & 0xffff)); bs[3] = bf2f((bf16_t)(u.y >> 16));
;     }
;     const f32x4 gt = *(const f32x4*)(gate + (size_t)g * 6144 + col);
;     f32x4 bi = {0.f, 0.f, 0.f, 0.f};
;     if (bias) bi = *(const f32x4*)(bias + col);
;     f32x4 r;
; #pragma unroll
;     for (int j = 0; j < 4; ++j) r[j] = bs[j] + gt[j] * (v[j] + bi[j]);
;     uint2 w; w.x = pack2(r[0], r[1]); w.y = pack2(r[2], r[3]);
;     *(uint2*)(X16 + o) = w;
; template <bool SWAP, class Epi, bool THIN = false> ...
;     ...
;     const int te = get_tid512();
;     const int fr_e = te & 15, fq_e = (te & 63) >> 4, wr_e = te >> 7, wc_e = (te >> 6) & 1;
;     const int sub = 2 * mt + (wr_e >> 1);
;     const int g = sub / tpg, ti = sub - g * tpg;
;     const int rig0 = ti * step - halo;
;     const int rw = (wr_e & 1) * 64;
;     if constexpr (Epi::KIND == 0) {
; #pragma unroll
;       for (int m = 0; m < 4; ++m) {
;         const int rig = rig0 + rw + m * 16 + fr_e;
;         if constexpr (Epi::ROWSUM) {
;           float ss = 0.f;
; #pragma unroll
;           for (int n = 0; n < 8; ++n) {
;             const int col = nt * 256 + wc_e * 128 + n * 16 + fq_e * 4;
;             if (col < N) ss += epi.c4(g, rig, col, acc[m][n]);
;           }
;           ss += __shfl_xor(ss, 16); ss += __shfl_xor(ss, 32);
;           if (fq_e == 0) epi.rowsum(g, rig, nt * 2 + wc_e, ss);
;         } else {
; #pragma unroll
;           for (int n = 0; n < 8; ++n) {
;             const int col = nt * 256 + wc_e * 128 + n * 16 + fq_e * 4;
;             if (col < N) epi.c4(g, rig, col, acc[m][n]);
	v_mfma_f32_16x16x32_bf16 v[98:101], v[186:189], v[178:181], v[132:135]
	v_ashrrev_i32_e32 v11, 8, v130
	v_add_u32_e32 v11, s5, v11
	v_ashrrev_i32_e32 v12, 31, v11
	v_lshrrev_b32_e32 v12, 28, v12
	v_add_u32_e32 v12, v11, v12
	v_ashrrev_i32_e32 v134, 4, v12
	v_lshlrev_b32_e32 v12, 11, v134
	v_lshlrev_b32_e32 v11, 7, v11
	v_sub_u32_e32 v11, v11, v12
	v_lshrrev_b32_e32 v12, 1, v130
	v_and_b32_e32 v10, 15, v130
	v_and_b32_e32 v12, 64, v12
	v_mfma_f32_16x16x32_bf16 v[102:105], v[182:185], v[178:181], v[70:73]
	v_ashrrev_i32_e32 v135, 31, v134
	v_mfma_f32_16x16x32_bf16 v[70:73], v[182:185], v[214:217], v[38:41]
	v_mfma_f32_16x16x32_bf16 v[38:41], v[182:185], v[218:221], v[136:139]
	s_nop 2
	v_or3_b32 v136, v11, v12, v10
	v_lshlrev_b32_e32 v10, 1, v130
	v_and_b32_e32 v132, 0x80, v10
	v_mfma_f32_16x16x32_bf16 v[10:13], v[182:185], v[222:225], v[2:5]
	v_ashrrev_i32_e32 v137, 31, v136
	v_lshlrev_b64 v[138:139], 21, v[134:135]
	v_lshlrev_b64 v[140:141], 10, v[136:137]
	v_lshrrev_b32_e32 v2, 2, v130
	v_and_b32_e32 v2, 12, v2
	v_mfma_f32_16x16x32_bf16 v[66:69], v[186:189], v[214:217], v[34:37]
	v_or3_b32 v132, v2, v132, s4
	v_mad_i64_i32 v[134:135], s[4:5], v134, s33, 0
	v_mfma_f32_16x16x32_bf16 v[34:37], v[186:189], v[218:221], v[170:173]
	v_lshl_add_u64 v[140:141], v[140:141], 0, v[138:139]
	v_cmp_gt_i32_e32 vcc, s34, v132
	v_ashrrev_i32_e32 v133, 31, v132
	v_mfma_f32_16x16x32_bf16 v[2:5], v[186:189], v[222:225], v[174:177]
	v_lshl_add_u64 v[134:135], s[26:27], 0, v[134:135]
	s_and_saveexec_b64 s[4:5], vcc
	s_cbranch_execz .LBB0_2119
	v_lshl_add_u64 v[178:179], v[140:141], 0, v[132:133]
	v_lshl_add_u64 v[174:175], v[178:179], 2, s[22:23]
	v_lshl_add_u64 v[170:171], v[132:133], 2, v[134:135]
	global_load_dwordx4 v[170:173], v[170:171], off
	s_nop 0
	global_load_dwordx4 v[174:177], v[174:175], off nt
	v_add_f32_e32 v126, 0, v126
	v_add_f32_e32 v127, 0, v127
	v_add_f32_e32 v128, 0, v128
	v_add_f32_e32 v129, 0, v129
	s_waitcnt vmcnt(0)
	v_fma_f32 v126, v126, v170, v174
	v_fma_f32 v127, v127, v171, v175
	v_fma_f32 v128, v128, v172, v176
	v_fmac_f32_e32 v177, v129, v173
	v_cvt_pk_bf16_f32 v126, v126, v127
	v_cvt_pk_bf16_f32 v127, v128, v177
	v_lshl_add_u64 v[128:129], v[178:179], 1, s[20:21]
	global_store_dwordx2 v[128:129], v[126:127], off

; template <bool SWAP, class Epi, bool THIN = false> ...
;     ...
;     for (int st = 0; st < ns; ++st) {
;       asm volatile("s_waitcnt vmcnt(0)" ::: "memory");
;       __builtin_amdgcn_s_barrier();
;       asm volatile("" ::: "memory");
;       if (st + 1 < ns) {
;         char* nb = smem + ((st + 1) & 1) * 65536;
;         const int ko = (st + 1) * 64;
; #pragma unroll
;         for (int i = 0; i < 4; ++i) { GLDS16(A + (size_t)(ap[i] + ko), nb + tid * 16 + i * 8192); GLDS16(Bt + (size_t)(bp[i] + ko), nb + 32768 + tid * 16 + i * 8192); }
;       }
;       const char* sa = smem + (st & 1) * 65536 + (wr * 64 + fr) * 128;
;       const char* sb = smem + (st & 1) * 65536 + 32768 + (wc * 128 + fr) * 128;
;       if constexpr (THIN) {
;         if (wc == 0) {
; #pragma unroll
;           for (int ks = 0; ks < 2; ++ks) {
;             bf16x8 af[4], bf[2];
; #pragma unroll
;             for (int m = 0; m < 4; ++m) af[m] = *(const bf16x8*)(sa + m * 2048 + (((ks * 4 + fq) ^ swz) << 4));
; #pragma unroll
;             for (int n = 0; n < 2; ++n) bf[n] = *(const bf16x8*)(sb + n * 2048 + (((ks * 4 + fq) ^ swz) << 4));
; #pragma unroll
;             for (int m = 0; m < 4; ++m)
; #pragma unroll
;               for (int n = 0; n < 2; ++n)
;                 acc[m][n] = SWAP ? __builtin_amdgcn_mfma_f32_16x16x32_bf16(bf[n], af[m], acc[m][n], 0, 0, 0)
;                                  : __builtin_amdgcn_mfma_f32_16x16x32_bf16(af[m], bf[n], acc[m][n], 0, 0, 0);
;           }
;         }
;       } else {
;       bf16x8 afA[4], afB[4], bfb[2][2];
; #pragma unroll
;       for (int m = 0; m < 4; ++m) afA[m] = *(const bf16x8*)(sa + m * 2048 + ((fq ^ swz) << 4));
; #pragma unroll
;       for (int n = 0; n < 2; ++n) bfb[0][n] = *(const bf16x8*)(sb + n * 2048 + ((fq ^ swz) << 4));
; #pragma unroll
;       for (int gq = 0; gq < 8; ++gq) {
;         const int ks = gq >> 2, nh = gq & 3;
;         if (gq < 7) {
;           const int ks2 = (gq + 1) >> 2, nh2 = (gq + 1) & 3;
; #pragma unroll
;           for (int n = 0; n < 2; ++n) bfb[(gq + 1) & 1][n] = *(const bf16x8*)(sb + (nh2 * 2 + n) * 2048 + (((ks2 * 4 + fq) ^ swz) << 4));
;         }
;         if (gq == 3) {
; #pragma unroll
;           for (int m = 0; m < 4; ++m) afB[m] = *(const bf16x8*)(sa + m * 2048 + (((4 + fq) ^ swz) << 4));
;         }
;         __builtin_amdgcn_sched_barrier(0);
; #pragma unroll
.LBB0_2334:
	s_add_i32 s8, s7, 0x10000
	s_and_b32 s9, s8, 0x10000
	v_add_u32_e32 v170, s9, v135
	s_nop 0
	v_readfirstlane_b32 s9, v170
	s_waitcnt vmcnt(0)
	s_barrier
	s_and_b32 s7, s7, 0x10000
	v_or_b32_e32 v204, s7, v139
	v_add_u32_e32 v205, v204, v140
	v_add_u32_e32 v136, s7, v138
	v_add_u32_e32 v180, v136, v140
	ds_read_b128 v[168:171], v180
	ds_read_b128 v[172:175], v180 offset:2048
	ds_read_b128 v[176:179], v180 offset:4096
	ds_read_b128 v[180:183], v180 offset:6144
	ds_read_b128 v[184:187], v205 offset:32768
	ds_read_b128 v[188:191], v205 offset:34816
	ds_read_b128 v[192:195], v205 offset:36864
	ds_read_b128 v[196:199], v205 offset:38912
	v_add_u32_e32 v136, v136, v141
	s_waitcnt lgkmcnt(3)
	v_mfma_f32_16x16x32_bf16 v[126:129], v[184:187], v[168:171], v[126:129]
	s_mov_b32 m0, s9
	v_mfma_f32_16x16x32_bf16 v[110:113], v[184:187], v[172:175], v[110:113]
	global_load_lds_dwordx4 v167, s[16:17]
	v_add_u32_e32 v167, 0x80, v167
	v_mfma_f32_16x16x32_bf16 v[82:85], v[184:187], v[176:179], v[82:85]
	v_mfma_f32_16x16x32_bf16 v[50:53], v[184:187], v[180:183], v[50:53]
	ds_read_b128 v[184:187], v205 offset:40960
	ds_read_b128 v[200:203], v205 offset:43008
	s_waitcnt lgkmcnt(4)
	v_mfma_f32_16x16x32_bf16 v[122:125], v[188:191], v[168:171], v[122:125]
	s_add_u32 m0, s9, 0x8000
	v_mfma_f32_16x16x32_bf16 v[106:109], v[188:191], v[172:175], v[106:109]
	global_load_lds_dwordx4 v166, s[18:19]
	v_add_u32_e32 v166, 0x80, v166
	v_mfma_f32_16x16x32_bf16 v[78:81], v[188:191], v[176:179], v[78:81]
	v_mfma_f32_16x16x32_bf16 v[42:45], v[188:191], v[180:183], v[42:45]
	s_waitcnt lgkmcnt(3)
	v_mfma_f32_16x16x32_bf16 v[118:121], v[192:195], v[168:171], v[118:121]
	s_add_u32 m0, s9, 0x2000
	v_mfma_f32_16x16x32_bf16 v[94:97], v[192:195], v[172:175], v[94:97]
	global_load_lds_dwordx4 v165, s[16:17]
	v_add_u32_e32 v165, 0x80, v165
	v_mfma_f32_16x16x32_bf16 v[58:61], v[192:195], v[176:179], v[58:61]
	v_mfma_f32_16x16x32_bf16 v[26:29], v[192:195], v[180:183], v[26:29]
	ds_read_b128 v[188:191], v205 offset:45056
	ds_read_b128 v[192:195], v205 offset:47104
	s_waitcnt lgkmcnt(4)
	v_mfma_f32_16x16x32_bf16 v[114:117], v[196:199], v[168:171], v[114:117]
	s_add_u32 m0, s9, 0xa000
	v_mfma_f32_16x16x32_bf16 v[90:93], v[196:199], v[172:175], v[90:93]
	global_load_lds_dwordx4 v164, s[18:19]
	v_add_u32_e32 v164, 0x80, v164
	v_mfma_f32_16x16x32_bf16 v[54:57], v[196:199], v[176:179], v[54:57]
	v_mfma_f32_16x16x32_bf16 v[22:25], v[196:199], v[180:183], v[22:25]
	v_add_u32_e32 v220, v204, v141
	s_waitcnt lgkmcnt(3)
	v_mfma_f32_16x16x32_bf16 v[102:105], v[184:187], v[168:171], v[102:105]
	ds_read_b128 v[196:199], v220 offset:32768
	ds_read_b128 v[204:207], v220 offset:34816
	s_add_u32 m0, s9, 0x4000
	v_mfma_f32_16x16x32_bf16 v[74:77], v[184:187], v[172:175], v[74:77]
	global_load_lds_dwordx4 v163, s[16:17]
	v_add_u32_e32 v163, 0x80, v163
	v_mfma_f32_16x16x32_bf16 v[46:49], v[184:187], v[176:179], v[46:49]
	v_mfma_f32_16x16x32_bf16 v[10:13], v[184:187], v[180:183], v[10:13]
	ds_read_b128 v[184:187], v136
	ds_read_b128 v[208:211], v136 offset:2048
	ds_read_b128 v[212:215], v136 offset:4096
	ds_read_b128 v[216:219], v136 offset:6144
	s_waitcnt lgkmcnt(8)
	v_mfma_f32_16x16x32_bf16 v[98:101], v[200:203], v[168:171], v[98:101]
	s_add_u32 m0, s9, 0xc000
	v_mfma_f32_16x16x32_bf16 v[66:69], v[200:203], v[172:175], v[66:69]
	global_load_lds_dwordx4 v162, s[18:19]
	v_add_u32_e32 v162, 0x80, v162
	v_mfma_f32_16x16x32_bf16 v[30:33], v[200:203], v[176:179], v[30:33]
	v_mfma_f32_16x16x32_bf16 v[6:9], v[200:203], v[180:183], v[6:9]
	s_waitcnt lgkmcnt(7)
	v_mfma_f32_16x16x32_bf16 v[70:73], v[188:191], v[168:171], v[70:73]
	s_add_u32 m0, s9, 0x6000
	s_waitcnt lgkmcnt(6)
	v_mfma_f32_16x16x32_bf16 v[62:65], v[192:195], v[168:171], v[62:65]
	global_load_lds_dwordx4 v161, s[16:17]
	v_add_u32_e32 v161, 0x80, v161
	v_mfma_f32_16x16x32_bf16 v[38:41], v[188:191], v[172:175], v[38:41]
	v_mfma_f32_16x16x32_bf16 v[34:37], v[192:195], v[172:175], v[34:37]
	ds_read_b128 v[168:171], v220 offset:36864
	ds_read_b128 v[172:175], v220 offset:38912
	v_mfma_f32_16x16x32_bf16 v[18:21], v[188:191], v[176:179], v[18:21]
	s_add_u32 m0, s9, 0xe000
	v_mfma_f32_16x16x32_bf16 v[14:17], v[192:195], v[176:179], v[14:17]
	global_load_lds_dwordx4 v160, s[18:19]
	v_add_u32_e32 v160, 0x80, v160
	v_mfma_f32_16x16x32_bf16 v[2:5], v[188:191], v[180:183], v[2:5]
	v_mfma_f32_16x16x32_bf16 v[86:89], v[192:195], v[180:183], v[86:89]
	ds_read_b128 v[176:179], v220 offset:40960
	ds_read_b128 v[180:183], v220 offset:43008
	s_waitcnt lgkmcnt(7)
	v_mfma_f32_16x16x32_bf16 v[126:129], v[196:199], v[184:187], v[126:129]
	v_mfma_f32_16x16x32_bf16 v[122:125], v[204:207], v[184:187], v[122:125]
	s_waitcnt lgkmcnt(6)
	v_mfma_f32_16x16x32_bf16 v[110:113], v[196:199], v[208:211], v[110:113]
	v_mfma_f32_16x16x32_bf16 v[106:109], v[204:207], v[208:211], v[106:109]
	s_waitcnt lgkmcnt(5)
	v_mfma_f32_16x16x32_bf16 v[82:85], v[196:199], v[212:215], v[82:85]
	v_mfma_f32_16x16x32_bf16 v[78:81], v[204:207], v[212:215], v[78:81]
	s_waitcnt lgkmcnt(4)
	v_mfma_f32_16x16x32_bf16 v[50:53], v[196:199], v[216:219], v[50:53]
	v_mfma_f32_16x16x32_bf16 v[42:45], v[204:207], v[216:219], v[42:45]
	s_waitcnt lgkmcnt(3)
	v_mfma_f32_16x16x32_bf16 v[118:121], v[168:171], v[184:187], v[118:121]
	v_mfma_f32_16x16x32_bf16 v[94:97], v[168:171], v[208:211], v[94:97]
	v_mfma_f32_16x16x32_bf16 v[58:61], v[168:171], v[212:215], v[58:61]
	v_mfma_f32_16x16x32_bf16 v[26:29], v[168:171], v[216:219], v[26:29]
	ds_read_b128 v[168:171], v220 offset:45056
	ds_read_b128 v[188:191], v220 offset:47104
	s_waitcnt lgkmcnt(4)
; template <bool SWAP, class Epi, bool THIN = false> ...
;     ...
;     for (int st = 0; st < ns; ++st) {
;       asm volatile("s_waitcnt vmcnt(0)" ::: "memory");
;       __builtin_amdgcn_s_barrier();
;       asm volatile("" ::: "memory");
;       if (st + 1 < ns) {
;         char* nb = smem + ((st + 1) & 1) * 65536;
;         const int ko = (st + 1) * 64;
; #pragma unroll
;         for (int i = 0; i < 4; ++i) { GLDS16(A + (size_t)(ap[i] + ko), nb + tid * 16 + i * 8192); GLDS16(Bt + (size_t)(bp[i] + ko), nb + 32768 + tid * 16 + i * 8192); }
;       }
;       const char* sa = smem + (st & 1) * 65536 + (wr * 64 + fr) * 128;
;       const char* sb = smem + (st & 1) * 65536 + 32768 + (wc * 128 + fr) * 128;
;       if constexpr (THIN) {
;         if (wc == 0) {
; #pragma unroll
;           for (int ks = 0; ks < 2; ++ks) {
;             bf16x8 af[4], bf[2];
; #pragma unroll
;             for (int m = 0; m < 4; ++m) af[m] = *(const bf16x8*)(sa + m * 2048 + (((ks * 4 + fq) ^ swz) << 4));
; #pragma unroll
;             for (int n = 0; n < 2; ++n) bf[n] = *(const bf16x8*)(sb + n * 2048 + (((ks * 4 + fq) ^ swz) << 4));
; #pragma unroll
;             for (int m = 0; m < 4; ++m)
; #pragma unroll
;               for (int n = 0; n < 2; ++n)
;                 acc[m][n] = SWAP ? __builtin_amdgcn_mfma_f32_16x16x32_bf16(bf[n], af[m], acc[m][n], 0, 0, 0)
;                                  : __builtin_amdgcn_mfma_f32_16x16x32_bf16(af[m], bf[n], acc[m][n], 0, 0, 0);
;           }
;         }
;       } else {
;       bf16x8 afA[4], afB[4], bfb[2][2];
; #pragma unroll
;       for (int m = 0; m < 4; ++m) afA[m] = *(const bf16x8*)(sa + m * 2048 + ((fq ^ swz) << 4));
; #pragma unroll
;       for (int n = 0; n < 2; ++n) bfb[0][n] = *(const bf16x8*)(sb + n * 2048 + ((fq ^ swz) << 4));
; #pragma unroll
;       for (int gq = 0; gq < 8; ++gq) {
;         const int ks = gq >> 2, nh = gq & 3;
;         if (gq < 7) {
;           const int ks2 = (gq + 1) >> 2, nh2 = (gq + 1) & 3;
; #pragma unroll
;           for (int n = 0; n < 2; ++n) bfb[(gq + 1) & 1][n] = *(const bf16x8*)(sb + (nh2 * 2 + n) * 2048 + (((ks2 * 4 + fq) ^ swz) << 4));
;         }
;         if (gq == 3) {
; #pragma unroll
;           for (int m = 0; m < 4; ++m) afB[m] = *(const bf16x8*)(sa + m * 2048 + (((4 + fq) ^ swz) << 4));
;         }
;         __builtin_amdgcn_sched_barrier(0);
; #pragma unroll
	v_mfma_f32_16x16x32_bf16 v[114:117], v[172:175], v[184:187], v[114:117]
	v_mfma_f32_16x16x32_bf16 v[90:93], v[172:175], v[208:211], v[90:93]
	v_mfma_f32_16x16x32_bf16 v[54:57], v[172:175], v[212:215], v[54:57]
	v_mfma_f32_16x16x32_bf16 v[22:25], v[172:175], v[216:219], v[22:25]
	s_waitcnt lgkmcnt(3)
	v_mfma_f32_16x16x32_bf16 v[102:105], v[176:179], v[184:187], v[102:105]
	s_waitcnt lgkmcnt(2)
	v_mfma_f32_16x16x32_bf16 v[98:101], v[180:183], v[184:187], v[98:101]
	v_mfma_f32_16x16x32_bf16 v[74:77], v[176:179], v[208:211], v[74:77]
	v_mfma_f32_16x16x32_bf16 v[66:69], v[180:183], v[208:211], v[66:69]
	v_mfma_f32_16x16x32_bf16 v[46:49], v[176:179], v[212:215], v[46:49]
	v_mfma_f32_16x16x32_bf16 v[30:33], v[180:183], v[212:215], v[30:33]
	v_mfma_f32_16x16x32_bf16 v[10:13], v[176:179], v[216:219], v[10:13]
	v_mfma_f32_16x16x32_bf16 v[6:9], v[180:183], v[216:219], v[6:9]
	s_waitcnt lgkmcnt(1)
	v_mfma_f32_16x16x32_bf16 v[70:73], v[168:171], v[184:187], v[70:73]
	s_add_i32 s5, s5, 64
	s_cmpk_eq_i32 s5, 0x3c0
	s_mov_b32 s7, s8
	s_waitcnt lgkmcnt(0)
	v_mfma_f32_16x16x32_bf16 v[62:65], v[188:191], v[184:187], v[62:65]
	v_mfma_f32_16x16x32_bf16 v[38:41], v[168:171], v[208:211], v[38:41]
	v_mfma_f32_16x16x32_bf16 v[34:37], v[188:191], v[208:211], v[34:37]
	v_mfma_f32_16x16x32_bf16 v[18:21], v[168:171], v[212:215], v[18:21]
	v_mfma_f32_16x16x32_bf16 v[14:17], v[188:191], v[212:215], v[14:17]
	v_mfma_f32_16x16x32_bf16 v[2:5], v[168:171], v[216:219], v[2:5]
	v_mfma_f32_16x16x32_bf16 v[86:89], v[188:191], v[216:219], v[86:89]
	s_cbranch_scc0 .LBB0_2334
	s_waitcnt vmcnt(0)
	s_barrier
	v_add_u32_e32 v136, v150, v140
	ds_read_b128 v[160:163], v136
	ds_read_b128 v[164:167], v136 offset:2048
	ds_read_b128 v[168:171], v136 offset:4096
	ds_read_b128 v[172:175], v136 offset:6144
	v_add_u32_e32 v136, v151, v140
	ds_read_b128 v[176:179], v136
	ds_read_b128 v[180:183], v136 offset:2048
	ds_read_b128 v[184:187], v136 offset:4096
	ds_read_b128 v[188:191], v136 offset:6144
	s_waitcnt lgkmcnt(0)
	v_mfma_f32_16x16x32_bf16 v[126:129], v[176:179], v[160:163], v[126:129]
	v_mfma_f32_16x16x32_bf16 v[110:113], v[176:179], v[164:167], v[110:113]
	v_mfma_f32_16x16x32_bf16 v[82:85], v[176:179], v[168:171], v[82:85]
	v_mfma_f32_16x16x32_bf16 v[50:53], v[176:179], v[172:175], v[50:53]
	ds_read_b128 v[176:179], v136 offset:8192
	ds_read_b128 v[192:195], v136 offset:10240
	v_mfma_f32_16x16x32_bf16 v[122:125], v[180:183], v[160:163], v[122:125]
	v_mfma_f32_16x16x32_bf16 v[106:109], v[180:183], v[164:167], v[106:109]
	v_mfma_f32_16x16x32_bf16 v[78:81], v[180:183], v[168:171], v[78:81]
	v_mfma_f32_16x16x32_bf16 v[42:45], v[180:183], v[172:175], v[42:45]
	v_mfma_f32_16x16x32_bf16 v[118:121], v[184:187], v[160:163], v[118:121]
	v_mfma_f32_16x16x32_bf16 v[94:97], v[184:187], v[164:167], v[94:97]
	v_mfma_f32_16x16x32_bf16 v[58:61], v[184:187], v[168:171], v[58:61]
	v_mfma_f32_16x16x32_bf16 v[26:29], v[184:187], v[172:175], v[26:29]
	ds_read_b128 v[180:183], v136 offset:12288
	ds_read_b128 v[184:187], v136 offset:14336
	v_mfma_f32_16x16x32_bf16 v[114:117], v[188:191], v[160:163], v[114:117]
	v_mfma_f32_16x16x32_bf16 v[90:93], v[188:191], v[164:167], v[90:93]
	v_mfma_f32_16x16x32_bf16 v[54:57], v[188:191], v[168:171], v[54:57]
	v_mfma_f32_16x16x32_bf16 v[22:25], v[188:191], v[172:175], v[22:25]
	v_add_u32_e32 v136, v151, v141
	v_add_u32_e32 v208, v150, v141
	s_waitcnt lgkmcnt(0)
	v_mfma_f32_16x16x32_bf16 v[102:105], v[176:179], v[160:163], v[102:105]
	v_mfma_f32_16x16x32_bf16 v[74:77], v[176:179], v[164:167], v[74:77]
	v_mfma_f32_16x16x32_bf16 v[188:191], v[192:195], v[164:167], v[66:69]
	v_mfma_f32_16x16x32_bf16 v[196:199], v[176:179], v[168:171], v[46:49]
	s_nop 2
	ds_read_b128 v[46:49], v136
	ds_read_b128 v[66:69], v136 offset:2048
	v_mfma_f32_16x16x32_bf16 v[10:13], v[176:179], v[172:175], v[10:13]
	ds_read_b128 v[176:179], v208
	ds_read_b128 v[200:203], v208 offset:2048
	ds_read_b128 v[204:207], v208 offset:4096
	ds_read_b128 v[208:211], v208 offset:6144
	v_mfma_f32_16x16x32_bf16 v[98:101], v[192:195], v[160:163], v[98:101]
	v_mfma_f32_16x16x32_bf16 v[30:33], v[192:195], v[168:171], v[30:33]
	v_mfma_f32_16x16x32_bf16 v[6:9], v[192:195], v[172:175], v[6:9]
	v_mfma_f32_16x16x32_bf16 v[192:195], v[180:183], v[164:167], v[38:41]
	v_mfma_f32_16x16x32_bf16 v[164:167], v[184:187], v[164:167], v[34:37]
	v_mfma_f32_16x16x32_bf16 v[18:21], v[180:183], v[168:171], v[18:21]
	v_mfma_f32_16x16x32_bf16 v[168:171], v[184:187], v[168:171], v[14:17]
	s_nop 2
	ds_read_b128 v[14:17], v136 offset:4096
	ds_read_b128 v[34:37], v136 offset:6144
	v_mfma_f32_16x16x32_bf16 v[70:73], v[180:183], v[160:163], v[70:73]
	v_mfma_f32_16x16x32_bf16 v[2:5], v[180:183], v[172:175], v[2:5]
	v_mfma_f32_16x16x32_bf16 v[160:163], v[184:187], v[160:163], v[62:65]
	v_mfma_f32_16x16x32_bf16 v[86:89], v[184:187], v[172:175], v[86:89]
	s_waitcnt lgkmcnt(0)
	v_mfma_f32_16x16x32_bf16 v[172:175], v[46:49], v[208:211], v[50:53]
	s_nop 2
	ds_read_b128 v[50:53], v136 offset:8192
	ds_read_b128 v[180:183], v136 offset:10240
	v_mfma_f32_16x16x32_bf16 v[126:129], v[46:49], v[176:179], v[126:129]
	v_mfma_f32_16x16x32_bf16 v[122:125], v[66:69], v[176:179], v[122:125]
	v_mfma_f32_16x16x32_bf16 v[110:113], v[46:49], v[200:203], v[110:113]
	v_mfma_f32_16x16x32_bf16 v[106:109], v[66:69], v[200:203], v[106:109]
	v_mfma_f32_16x16x32_bf16 v[82:85], v[46:49], v[204:207], v[82:85]
	v_mfma_f32_16x16x32_bf16 v[78:81], v[66:69], v[204:207], v[78:81]
	v_mfma_f32_16x16x32_bf16 v[184:187], v[66:69], v[208:211], v[42:45]
	ds_read_b128 v[224:227], v136 offset:12288
	ds_read_b128 v[228:231], v136 offset:14336
	v_mfma_f32_16x16x32_bf16 v[118:121], v[14:17], v[176:179], v[118:121]
	v_mfma_f32_16x16x32_bf16 v[114:117], v[34:37], v[176:179], v[114:117]
	v_mfma_f32_16x16x32_bf16 v[94:97], v[14:17], v[200:203], v[94:97]
	v_mfma_f32_16x16x32_bf16 v[90:93], v[34:37], v[200:203], v[90:93]
	v_mfma_f32_16x16x32_bf16 v[212:215], v[14:17], v[204:207], v[58:61]
	v_mfma_f32_16x16x32_bf16 v[216:219], v[34:37], v[204:207], v[54:57]
	v_mfma_f32_16x16x32_bf16 v[220:223], v[14:17], v[208:211], v[26:29]
	v_mfma_f32_16x16x32_bf16 v[66:69], v[34:37], v[208:211], v[22:25]
	s_waitcnt lgkmcnt(0)
	v_mfma_f32_16x16x32_bf16 v[38:41], v[180:183], v[204:207], v[30:33]
	v_mfma_f32_16x16x32_bf16 v[62:65], v[50:53], v[176:179], v[102:105]
	v_mfma_f32_16x16x32_bf16 v[46:49], v[180:183], v[176:179], v[98:101]
	v_mfma_f32_16x16x32_bf16 v[58:61], v[50:53], v[200:203], v[74:77]
	v_mfma_f32_16x16x32_bf16 v[42:45], v[180:183], v[200:203], v[188:191]
	v_mfma_f32_16x16x32_bf16 v[54:57], v[50:53], v[204:207], v[196:199]
	v_mfma_f32_16x16x32_bf16 v[50:53], v[50:53], v[208:211], v[10:13]
	v_mfma_f32_16x16x32_bf16 v[34:37], v[180:183], v[208:211], v[6:9]
	s_nop 2
	v_mov_b32_e32 v8, v1
	s_waitcnt vmcnt(0)
	v_mfma_f32_16x16x32_bf16 v[30:33], v[224:227], v[176:179], v[70:73]
	s_barrier
; __device__ __forceinline__ int get_tid512() { int t = threadIdx.x; asm volatile("" : "+v"(t)); return t; }
; __device__ __forceinline__ unsigned pack2(float a, float b) { unsigned r; asm("v_cvt_pk_bf16_f32 %0, %1, %2" : "=v"(r) : "v"(a), "v"(b)); return r; }
; template <bool SWAP, class Epi, bool THIN = false> ...
;     ...
;     const int te = get_tid512();
;     const int fr_e = te & 15, fq_e = (te & 63) >> 4, wr_e = te >> 7, wc_e = (te >> 6) & 1;
;     const int sub = 2 * mt + (wr_e >> 1);
;     const int g = sub / tpg, ti = sub - g * tpg;
;     const int rig0 = ti * step - halo;
;     const int rw = (wr_e & 1) * 64;
;     ...
;     } else {
;       bf16_t* Zw = (bf16_t*)smem + ((wr_e >> 1) * 2 + wc_e) * (128 * 132);
;       const int nt2w = nt * 2 + wc_e;
; #pragma unroll
;       for (int n = 0; n < 8; ++n) {
;         const int cl = n * 16 + fq_e * 4;
;         f32x4 b4 = {0.f, 0.f, 0.f, 0.f};
;         if (epi.pre_bias) b4 = *(const f32x4*)(epi.pre_bias + epi.norig(nt2w, cl));
; #pragma unroll
;         for (int m = 0; m < 4; ++m) {
;           const int rl = rw + m * 16 + fr_e;
;           const int pos = rig0 + rl;
;           const bool ok = pos >= 0 && pos < grows;
;           f32x4 vv = acc[m][n] + b4;
;           if (!ok) vv = (f32x4){0.f, 0.f, 0.f, 0.f};
;           uint2 u; u.x = pack2(vv[0], vv[1]); u.y = pack2(vv[2], vv[3]);
;           *(uint2*)(Zw + rl * 132 + cl) = u;
;         }
;       }
	v_mfma_f32_16x16x32_bf16 v[22:25], v[224:227], v[204:207], v[18:21]
	s_nop 0
	v_ashrrev_i32_e32 v71, 8, v8
	v_add_u32_e32 v6, s4, v71
	v_mul_hi_i32 v7, v6, s26
	v_lshrrev_b32_e32 v9, 31, v7
	v_ashrrev_i32_e32 v7, 3, v7
	v_add_u32_e32 v70, v7, v9
	v_and_b32_e32 v73, 15, v8
	v_mad_u64_u32 v[6:7], s[4:5], v70, s27, v[6:7]
	v_lshrrev_b32_e32 v75, 1, v8
	v_bfe_u32 v74, v8, 6, 1
	v_mul_lo_u32 v72, v6, s28
	v_and_or_b32 v73, v75, 64, v73
	v_add_u32_e32 v98, v72, v73
	v_lshl_or_b32 v74, v71, 1, v74
	v_mul_lo_u32 v74, v74, s29
	v_add_u32_e32 v99, -1, v98
	v_mfma_f32_16x16x32_bf16 v[18:21], v[224:227], v[208:211], v[2:5]
	v_add_f32_e64 v76, v126, 0
	v_add_f32_e64 v77, v127, 0
	v_cmp_gt_u32_e32 vcc, s30, v99
	s_lshl_b32 s24, s6, 7
	v_mfma_f32_16x16x32_bf16 v[2:5], v[228:231], v[208:211], v[86:89]
	v_add_f32_e64 v84, v84, 0
	v_add_f32_e64 v85, v85, 0
	v_pk_add_f32 v[82:83], v[82:83], 0 op_sel_hi:[1,0]
	v_pk_add_f32 v[66:67], v[66:67], 0 op_sel_hi:[1,0]
	v_and_or_b32 v86, v75, 24, v74
	v_pk_add_f32 v[74:75], v[128:129], 0 op_sel_hi:[1,0]
	v_add_u32_e32 v88, 15, v98
	v_cndmask_b32_e32 v87, 0, v74, vcc
	v_cndmask_b32_e32 v75, 0, v75, vcc
	v_cndmask_b32_e32 v74, 0, v76, vcc
	v_cndmask_b32_e32 v76, 0, v77, vcc
	v_cvt_pk_bf16_f32 v74, v74, v76
	v_cvt_pk_bf16_f32 v75, v87, v75
	v_mad_u32_u24 v73, v73, s31, v86
	v_pk_add_f32 v[76:77], v[112:113], 0 op_sel_hi:[1,0]
	v_pk_add_f32 v[86:87], v[110:111], 0 op_sel_hi:[1,0]
	v_cmp_gt_u32_e64 s[4:5], s30, v88
	v_mfma_f32_16x16x32_bf16 v[26:29], v[224:227], v[200:203], v[192:195]
	v_add_f32_e64 v62, v62, 0
	v_add_f32_e64 v63, v63, 0
	v_cndmask_b32_e64 v88, 0, v76, s[4:5]
	v_cndmask_b32_e64 v76, 0, v86, s[4:5]
	v_cndmask_b32_e64 v86, 0, v87, s[4:5]
	v_cvt_pk_bf16_f32 v76, v76, v86
	v_add_u32_e32 v86, 31, v98
	v_cndmask_b32_e64 v77, 0, v77, s[4:5]
	v_cmp_gt_u32_e64 s[6:7], s30, v86
	v_cvt_pk_bf16_f32 v77, v88, v77
	v_add_u32_e32 v88, 47, v98
	v_pk_add_f32 v[86:87], v[172:173], 0 op_sel_hi:[1,0]
	v_cndmask_b32_e64 v84, 0, v84, s[6:7]
	v_cndmask_b32_e64 v85, 0, v85, s[6:7]
	v_cndmask_b32_e64 v82, 0, v82, s[6:7]
	v_cndmask_b32_e64 v83, 0, v83, s[6:7]
	v_cvt_pk_bf16_f32 v82, v82, v83
	v_cvt_pk_bf16_f32 v83, v84, v85
	v_pk_add_f32 v[84:85], v[174:175], 0 op_sel_hi:[1,0]
	v_cmp_gt_u32_e64 s[8:9], s30, v88
	v_mfma_f32_16x16x32_bf16 v[14:17], v[228:231], v[176:179], v[160:163]
	v_add_f32_e64 v28, v28, 0
	v_add_f32_e64 v29, v29, 0
	v_cndmask_b32_e64 v88, 0, v84, s[8:9]
	v_cndmask_b32_e64 v85, 0, v85, s[8:9]
	v_cndmask_b32_e64 v84, 0, v86, s[8:9]
	v_cndmask_b32_e64 v86, 0, v87, s[8:9]
	v_cvt_pk_bf16_f32 v84, v84, v86
	v_cvt_pk_bf16_f32 v85, v88, v85
	v_pk_add_f32 v[86:87], v[124:125], 0 op_sel_hi:[1,0]
	v_pk_add_f32 v[88:89], v[122:123], 0 op_sel_hi:[1,0]
	v_cndmask_b32_e32 v98, 0, v86, vcc
	v_cndmask_b32_e32 v87, 0, v87, vcc
	v_cndmask_b32_e32 v86, 0, v88, vcc
	v_cndmask_b32_e32 v88, 0, v89, vcc
	v_cvt_pk_bf16_f32 v86, v86, v88
	v_cvt_pk_bf16_f32 v87, v98, v87
	ds_write2_b64 v73, v[74:75], v[86:87] offset1:4
	v_pk_add_f32 v[74:75], v[108:109], 0 op_sel_hi:[1,0]
	v_pk_add_f32 v[86:87], v[106:107], 0 op_sel_hi:[1,0]
	v_cndmask_b32_e64 v88, 0, v74, s[4:5]
	v_cndmask_b32_e64 v75, 0, v75, s[4:5]
	v_cndmask_b32_e64 v74, 0, v86, s[4:5]
	v_cndmask_b32_e64 v86, 0, v87, s[4:5]
	v_cvt_pk_bf16_f32 v74, v74, v86
	v_cvt_pk_bf16_f32 v75, v88, v75
	v_add_u32_e32 v86, 0x1000, v73
	ds_write2_b64 v86, v[76:77], v[74:75] offset0:16 offset1:20
	v_pk_add_f32 v[74:75], v[80:81], 0 op_sel_hi:[1,0]
	v_pk_add_f32 v[76:77], v[78:79], 0 op_sel_hi:[1,0]
	v_cndmask_b32_e64 v78, 0, v74, s[6:7]
	v_cndmask_b32_e64 v75, 0, v75, s[6:7]
	v_cndmask_b32_e64 v74, 0, v76, s[6:7]
	v_cndmask_b32_e64 v76, 0, v77, s[6:7]
	v_cvt_pk_bf16_f32 v74, v74, v76
	v_cvt_pk_bf16_f32 v75, v78, v75
	v_add_u32_e32 v87, 0x2000, v73
	ds_write2_b64 v87, v[82:83], v[74:75] offset0:32 offset1:36
	v_pk_add_f32 v[74:75], v[186:187], 0 op_sel_hi:[1,0]
	v_pk_add_f32 v[76:77], v[184:185], 0 op_sel_hi:[1,0]
	v_cndmask_b32_e64 v78, 0, v74, s[8:9]
	v_cndmask_b32_e64 v75, 0, v75, s[8:9]
	v_cndmask_b32_e64 v74, 0, v76, s[8:9]
	v_cndmask_b32_e64 v76, 0, v77, s[8:9]
	v_cvt_pk_bf16_f32 v74, v74, v76
	v_cvt_pk_bf16_f32 v75, v78, v75
	v_add_u32_e32 v88, 0x3000, v73
	ds_write2_b64 v88, v[84:85], v[74:75] offset0:48 offset1:52
	v_pk_add_f32 v[74:75], v[120:121], 0 op_sel_hi:[1,0]
	v_pk_add_f32 v[76:77], v[118:119], 0 op_sel_hi:[1,0]
	v_cndmask_b32_e32 v78, 0, v74, vcc
	v_cndmask_b32_e32 v75, 0, v75, vcc
	v_cndmask_b32_e32 v74, 0, v76, vcc
	v_cndmask_b32_e32 v76, 0, v77, vcc
	v_cvt_pk_bf16_f32 v74, v74, v76
	v_cvt_pk_bf16_f32 v75, v78, v75
	v_pk_add_f32 v[76:77], v[96:97], 0 op_sel_hi:[1,0]
	v_pk_add_f32 v[78:79], v[94:95], 0 op_sel_hi:[1,0]
	v_cndmask_b32_e64 v80, 0, v76, s[4:5]
	v_cndmask_b32_e64 v77, 0, v77, s[4:5]
	v_cndmask_b32_e64 v76, 0, v78, s[4:5]
	v_cndmask_b32_e64 v78, 0, v79, s[4:5]
	v_cvt_pk_bf16_f32 v76, v76, v78
	v_cvt_pk_bf16_f32 v77, v80, v77
	v_pk_add_f32 v[78:79], v[214:215], 0 op_sel_hi:[1,0]
	v_pk_add_f32 v[80:81], v[212:213], 0 op_sel_hi:[1,0]
	v_cndmask_b32_e64 v82, 0, v78, s[6:7]
	v_cndmask_b32_e64 v79, 0, v79, s[6:7]
	v_cndmask_b32_e64 v78, 0, v80, s[6:7]
	v_cndmask_b32_e64 v80, 0, v81, s[6:7]
	v_cvt_pk_bf16_f32 v78, v78, v80
	v_cvt_pk_bf16_f32 v79, v82, v79
	v_pk_add_f32 v[80:81], v[222:223], 0 op_sel_hi:[1,0]
	v_pk_add_f32 v[82:83], v[220:221], 0 op_sel_hi:[1,0]
	v_cndmask_b32_e64 v84, 0, v80, s[8:9]
	v_cndmask_b32_e64 v81, 0, v81, s[8:9]
	v_cndmask_b32_e64 v80, 0, v82, s[8:9]
	v_cndmask_b32_e64 v82, 0, v83, s[8:9]
	v_cvt_pk_bf16_f32 v80, v80, v82
	v_cvt_pk_bf16_f32 v81, v84, v81
	v_pk_add_f32 v[82:83], v[116:117], 0 op_sel_hi:[1,0]
	v_pk_add_f32 v[84:85], v[114:115], 0 op_sel_hi:[1,0]
; __device__ __forceinline__ unsigned pack2(float a, float b) { unsigned r; asm("v_cvt_pk_bf16_f32 %0, %1, %2" : "=v"(r) : "v"(a), "v"(b)); return r; }
; template <bool SWAP, class Epi, bool THIN = false> ...
;     ...
;     } else {
;       bf16_t* Zw = (bf16_t*)smem + ((wr_e >> 1) * 2 + wc_e) * (128 * 132);
;       const int nt2w = nt * 2 + wc_e;
; #pragma unroll
;       for (int n = 0; n < 8; ++n) {
;         const int cl = n * 16 + fq_e * 4;
;         f32x4 b4 = {0.f, 0.f, 0.f, 0.f};
;         if (epi.pre_bias) b4 = *(const f32x4*)(epi.pre_bias + epi.norig(nt2w, cl));
; #pragma unroll
;         for (int m = 0; m < 4; ++m) {
;           const int rl = rw + m * 16 + fr_e;
;           const int pos = rig0 + rl;
;           const bool ok = pos >= 0 && pos < grows;
;           f32x4 vv = acc[m][n] + b4;
;           if (!ok) vv = (f32x4){0.f, 0.f, 0.f, 0.f};
;           uint2 u; u.x = pack2(vv[0], vv[1]); u.y = pack2(vv[2], vv[3]);
;           *(uint2*)(Zw + rl * 132 + cl) = u;
;         }
;       }
	v_cndmask_b32_e32 v89, 0, v82, vcc
	v_cndmask_b32_e32 v83, 0, v83, vcc
	v_cndmask_b32_e32 v82, 0, v84, vcc
	v_mfma_f32_16x16x32_bf16 v[10:13], v[228:231], v[200:203], v[164:167]
	v_cndmask_b32_e32 v84, 0, v85, vcc
	v_cvt_pk_bf16_f32 v82, v82, v84
	v_cvt_pk_bf16_f32 v83, v89, v83
	v_mfma_f32_16x16x32_bf16 v[6:9], v[228:231], v[204:207], v[168:171]
	ds_write2_b64 v73, v[74:75], v[82:83] offset0:8 offset1:12
	v_pk_add_f32 v[74:75], v[92:93], 0 op_sel_hi:[1,0]
	v_pk_add_f32 v[82:83], v[90:91], 0 op_sel_hi:[1,0]
	v_cndmask_b32_e64 v84, 0, v74, s[4:5]
	v_cndmask_b32_e64 v75, 0, v75, s[4:5]
	v_cndmask_b32_e64 v74, 0, v82, s[4:5]
	v_cndmask_b32_e64 v82, 0, v83, s[4:5]
	v_cvt_pk_bf16_f32 v74, v74, v82
	v_cvt_pk_bf16_f32 v75, v84, v75
	v_pk_add_f32 v[26:27], v[26:27], 0 op_sel_hi:[1,0]
	ds_write2_b64 v86, v[76:77], v[74:75] offset0:24 offset1:28
	v_pk_add_f32 v[74:75], v[218:219], 0 op_sel_hi:[1,0]
	v_pk_add_f32 v[76:77], v[216:217], 0 op_sel_hi:[1,0]
	v_pk_add_f32 v[58:59], v[58:59], 0 op_sel_hi:[1,0]
	v_pk_add_f32 v[54:55], v[54:55], 0 op_sel_hi:[1,0]
	v_pk_add_f32 v[50:51], v[50:51], 0 op_sel_hi:[1,0]
	v_pk_add_f32 v[46:47], v[46:47], 0 op_sel_hi:[1,0]
	v_pk_add_f32 v[42:43], v[42:43], 0 op_sel_hi:[1,0]
	v_pk_add_f32 v[38:39], v[38:39], 0 op_sel_hi:[1,0]
	v_pk_add_f32 v[34:35], v[34:35], 0 op_sel_hi:[1,0]
	v_pk_add_f32 v[30:31], v[30:31], 0 op_sel_hi:[1,0]
	v_cndmask_b32_e64 v28, 0, v28, s[4:5]
	v_cndmask_b32_e64 v26, 0, v26, s[4:5]
	v_cndmask_b32_e64 v27, 0, v27, s[4:5]
	v_pk_add_f32 v[22:23], v[22:23], 0 op_sel_hi:[1,0]
	v_pk_add_f32 v[18:19], v[18:19], 0 op_sel_hi:[1,0]
	v_pk_add_f32 v[14:15], v[14:15], 0 op_sel_hi:[1,0]
	v_pk_add_f32 v[10:11], v[10:11], 0 op_sel_hi:[1,0]
	v_pk_add_f32 v[6:7], v[6:7], 0 op_sel_hi:[1,0]
	v_pk_add_f32 v[2:3], v[2:3], 0 op_sel_hi:[1,0]
	v_cndmask_b32_e64 v82, 0, v74, s[6:7]
	v_cndmask_b32_e64 v75, 0, v75, s[6:7]
	v_cndmask_b32_e64 v74, 0, v76, s[6:7]
	v_pk_add_f32 v[68:69], v[68:69], 0 op_sel_hi:[1,0]
	v_cndmask_b32_e64 v66, 0, v66, s[8:9]
	v_cndmask_b32_e64 v67, 0, v67, s[8:9]
	v_pk_add_f32 v[64:65], v[64:65], 0 op_sel_hi:[1,0]
	v_cndmask_b32_e32 v62, 0, v62, vcc
	v_cndmask_b32_e32 v63, 0, v63, vcc
	v_pk_add_f32 v[60:61], v[60:61], 0 op_sel_hi:[1,0]
	v_cndmask_b32_e64 v58, 0, v58, s[4:5]
	v_cndmask_b32_e64 v59, 0, v59, s[4:5]
	v_pk_add_f32 v[56:57], v[56:57], 0 op_sel_hi:[1,0]
	v_cndmask_b32_e64 v54, 0, v54, s[6:7]
	v_cndmask_b32_e64 v55, 0, v55, s[6:7]
	v_pk_add_f32 v[52:53], v[52:53], 0 op_sel_hi:[1,0]
	v_cndmask_b32_e64 v50, 0, v50, s[8:9]
	v_cndmask_b32_e64 v51, 0, v51, s[8:9]
	v_pk_add_f32 v[48:49], v[48:49], 0 op_sel_hi:[1,0]
	v_cndmask_b32_e32 v46, 0, v46, vcc
	v_cndmask_b32_e32 v47, 0, v47, vcc
	v_pk_add_f32 v[44:45], v[44:45], 0 op_sel_hi:[1,0]
	v_cndmask_b32_e64 v42, 0, v42, s[4:5]
	v_cndmask_b32_e64 v43, 0, v43, s[4:5]
	v_pk_add_f32 v[40:41], v[40:41], 0 op_sel_hi:[1,0]
	v_cndmask_b32_e64 v38, 0, v38, s[6:7]
	v_cndmask_b32_e64 v39, 0, v39, s[6:7]
	v_pk_add_f32 v[36:37], v[36:37], 0 op_sel_hi:[1,0]
	v_cndmask_b32_e64 v34, 0, v34, s[8:9]
	v_cndmask_b32_e64 v35, 0, v35, s[8:9]
	v_pk_add_f32 v[32:33], v[32:33], 0 op_sel_hi:[1,0]
	v_cndmask_b32_e32 v30, 0, v30, vcc
	v_cndmask_b32_e32 v31, 0, v31, vcc
	v_cndmask_b32_e64 v29, 0, v29, s[4:5]
	v_cvt_pk_bf16_f32 v26, v26, v27
	v_cvt_pk_bf16_f32 v27, v28, v29
	v_pk_add_f32 v[24:25], v[24:25], 0 op_sel_hi:[1,0]
	v_cndmask_b32_e64 v22, 0, v22, s[6:7]
	v_cndmask_b32_e64 v23, 0, v23, s[6:7]
	v_pk_add_f32 v[20:21], v[20:21], 0 op_sel_hi:[1,0]
	v_cndmask_b32_e64 v18, 0, v18, s[8:9]
	v_cndmask_b32_e64 v19, 0, v19, s[8:9]
	v_pk_add_f32 v[16:17], v[16:17], 0 op_sel_hi:[1,0]
	v_cndmask_b32_e32 v14, 0, v14, vcc
	v_cndmask_b32_e32 v15, 0, v15, vcc
	v_pk_add_f32 v[12:13], v[12:13], 0 op_sel_hi:[1,0]
	v_cndmask_b32_e64 v10, 0, v10, s[4:5]
	v_cndmask_b32_e64 v11, 0, v11, s[4:5]
	v_pk_add_f32 v[8:9], v[8:9], 0 op_sel_hi:[1,0]
	v_cndmask_b32_e64 v6, 0, v6, s[6:7]
	v_cndmask_b32_e64 v7, 0, v7, s[6:7]
	v_pk_add_f32 v[4:5], v[4:5], 0 op_sel_hi:[1,0]
	v_cndmask_b32_e64 v2, 0, v2, s[8:9]
	v_cndmask_b32_e64 v3, 0, v3, s[8:9]
	v_mov_b32_e32 v28, v142
	v_cndmask_b32_e64 v76, 0, v77, s[6:7]
	v_cvt_pk_bf16_f32 v74, v74, v76
	v_cvt_pk_bf16_f32 v75, v82, v75
	ds_write2_b64 v87, v[78:79], v[74:75] offset0:40 offset1:44
	v_cndmask_b32_e64 v68, 0, v68, s[8:9]
	v_cndmask_b32_e64 v69, 0, v69, s[8:9]
	v_cvt_pk_bf16_f32 v66, v66, v67
	v_cvt_pk_bf16_f32 v67, v68, v69
	ds_write2_b64 v88, v[80:81], v[66:67] offset0:56 offset1:60
	v_cndmask_b32_e32 v64, 0, v64, vcc
	v_cndmask_b32_e32 v65, 0, v65, vcc
	v_cvt_pk_bf16_f32 v62, v62, v63
	v_cvt_pk_bf16_f32 v63, v64, v65
	v_cndmask_b32_e64 v60, 0, v60, s[4:5]
	v_cndmask_b32_e64 v61, 0, v61, s[4:5]
	v_cvt_pk_bf16_f32 v58, v58, v59
	v_cvt_pk_bf16_f32 v59, v60, v61
	v_cndmask_b32_e64 v56, 0, v56, s[6:7]
; __device__ __forceinline__ int get_tid() { int t = threadIdx.x & 255; asm volatile("" : "+v"(t)); return t; }
; __device__ __forceinline__ unsigned pack2(float a, float b) { unsigned r; asm("v_cvt_pk_bf16_f32 %0, %1, %2" : "=v"(r) : "v"(a), "v"(b)); return r; }
;   template <class F>
;   __device__ __forceinline__ void finish(const bf16_t* Z, int g, int rig0, int nt, F&& pre) const {
;     typedef f32x2_t f32x2;
;     const int tid = get_tid();
;     if (MODE == 0 || nt < 8) {
;       if (MODE == 0) {
;         const int f2 = (tid & 31) * 2, q8 = tid >> 5;
;         const int q0 = 1 + 16 * q8, q1 = (q0 + 16 < 127) ? q0 + 16 : 127;
;         const int na = norig(nt, f2), ng = norig(nt, 64 + f2);
;         const f32x2 a0 = *(const f32x2*)(cw + na), a1 = *(const f32x2*)(cw + NC + na), a2 = *(const f32x2*)(cw + 2 * NC + na), ab = *(const f32x2*)(cb + na);
;         const f32x2 g0 = *(const f32x2*)(cw + ng), g1 = *(const f32x2*)(cw + NC + ng), g2 = *(const f32x2*)(cw + 2 * NC + ng), gb = *(const f32x2*)(cb + ng);
;         pre();
;         f32x2 am = ldz(Z, q0 - 1, f2), ac = ldz(Z, q0, f2);
;         f32x2 gm = ldz(Z, q0 - 1, 64 + f2), gc = ldz(Z, q0, 64 + f2);
; template <bool SWAP, class Epi, bool THIN = false> ...
;     ...
;     } else {
;       bf16_t* Zw = (bf16_t*)smem + ((wr_e >> 1) * 2 + wc_e) * (128 * 132);
;       const int nt2w = nt * 2 + wc_e;
; #pragma unroll
;       for (int n = 0; n < 8; ++n) {
;         const int cl = n * 16 + fq_e * 4;
;         f32x4 b4 = {0.f, 0.f, 0.f, 0.f};
;         if (epi.pre_bias) b4 = *(const f32x4*)(epi.pre_bias + epi.norig(nt2w, cl));
; #pragma unroll
;         for (int m = 0; m < 4; ++m) {
;           const int rl = rw + m * 16 + fr_e;
;           const int pos = rig0 + rl;
;           const bool ok = pos >= 0 && pos < grows;
;           f32x4 vv = acc[m][n] + b4;
;           if (!ok) vv = (f32x4){0.f, 0.f, 0.f, 0.f};
;           uint2 u; u.x = pack2(vv[0], vv[1]); u.y = pack2(vv[2], vv[3]);
;           *(uint2*)(Zw + rl * 132 + cl) = u;
;         }
;       }
;       __syncthreads();
;       {
;         auto no_pre = []() {};
;         const bf16_t* Zr = (const bf16_t*)smem + ((wr_e >> 1) * 2) * (128 * 132);
;         epi.finish(Zr, g, rig0, nt * 2, no_pre);
	v_cndmask_b32_e64 v57, 0, v57, s[6:7]
	v_cvt_pk_bf16_f32 v54, v54, v55
	v_cvt_pk_bf16_f32 v55, v56, v57
	v_cndmask_b32_e64 v52, 0, v52, s[8:9]
	v_cndmask_b32_e64 v53, 0, v53, s[8:9]
	v_cvt_pk_bf16_f32 v50, v50, v51
	v_cvt_pk_bf16_f32 v51, v52, v53
	v_cndmask_b32_e32 v48, 0, v48, vcc
	v_cndmask_b32_e32 v49, 0, v49, vcc
	v_cvt_pk_bf16_f32 v46, v46, v47
	v_cvt_pk_bf16_f32 v47, v48, v49
	ds_write2_b64 v73, v[62:63], v[46:47] offset0:16 offset1:20
	v_cndmask_b32_e64 v44, 0, v44, s[4:5]
	v_cndmask_b32_e64 v45, 0, v45, s[4:5]
	v_cvt_pk_bf16_f32 v42, v42, v43
	v_cvt_pk_bf16_f32 v43, v44, v45
	ds_write2_b64 v86, v[58:59], v[42:43] offset0:32 offset1:36
	v_cndmask_b32_e64 v40, 0, v40, s[6:7]
	v_cndmask_b32_e64 v41, 0, v41, s[6:7]
	v_cvt_pk_bf16_f32 v38, v38, v39
	v_cvt_pk_bf16_f32 v39, v40, v41
	ds_write2_b64 v87, v[54:55], v[38:39] offset0:48 offset1:52
	v_cndmask_b32_e64 v36, 0, v36, s[8:9]
	v_cndmask_b32_e64 v37, 0, v37, s[8:9]
	v_cvt_pk_bf16_f32 v34, v34, v35
	v_cvt_pk_bf16_f32 v35, v36, v37
	ds_write2_b64 v88, v[50:51], v[34:35] offset0:64 offset1:68
	v_cndmask_b32_e32 v32, 0, v32, vcc
	v_cndmask_b32_e32 v33, 0, v33, vcc
	v_cvt_pk_bf16_f32 v30, v30, v31
	v_cvt_pk_bf16_f32 v31, v32, v33
	v_cndmask_b32_e64 v24, 0, v24, s[6:7]
	v_cndmask_b32_e64 v25, 0, v25, s[6:7]
	v_cvt_pk_bf16_f32 v22, v22, v23
	v_cvt_pk_bf16_f32 v23, v24, v25
	v_cndmask_b32_e64 v20, 0, v20, s[8:9]
	v_cndmask_b32_e64 v21, 0, v21, s[8:9]
	v_cvt_pk_bf16_f32 v18, v18, v19
	v_cvt_pk_bf16_f32 v19, v20, v21
	v_cndmask_b32_e32 v16, 0, v16, vcc
	v_cndmask_b32_e32 v17, 0, v17, vcc
	v_cvt_pk_bf16_f32 v14, v14, v15
	v_cvt_pk_bf16_f32 v15, v16, v17
	ds_write2_b64 v73, v[30:31], v[14:15] offset0:24 offset1:28
	v_cndmask_b32_e64 v12, 0, v12, s[4:5]
	v_cndmask_b32_e64 v13, 0, v13, s[4:5]
	v_cvt_pk_bf16_f32 v10, v10, v11
	v_cvt_pk_bf16_f32 v11, v12, v13
	ds_write2_b64 v86, v[26:27], v[10:11] offset0:40 offset1:44
	v_cndmask_b32_e64 v8, 0, v8, s[6:7]
	v_cndmask_b32_e64 v9, 0, v9, s[6:7]
	v_cvt_pk_bf16_f32 v6, v6, v7
	v_cvt_pk_bf16_f32 v7, v8, v9
	ds_write2_b64 v87, v[22:23], v[6:7] offset0:56 offset1:60
	v_cndmask_b32_e64 v4, 0, v4, s[8:9]
	v_cndmask_b32_e64 v5, 0, v5, s[8:9]
	v_cvt_pk_bf16_f32 v2, v2, v3
	v_cvt_pk_bf16_f32 v3, v4, v5
	ds_write2_b64 v88, v[18:19], v[2:3] offset0:72 offset1:76
	s_waitcnt lgkmcnt(0)
	s_barrier
	s_nop 0
	v_ashrrev_i32_e32 v29, 1, v28
	v_and_b32_e32 v38, -16, v29
	v_min_i32_e32 v2, 0x6e, v38
	v_or_b32_e32 v20, 1, v38
	v_add_u32_e32 v3, 17, v2
	v_cmp_ge_i32_e32 vcc, v20, v3
	s_and_saveexec_b64 s[4:5], vcc
	s_xor_b64 s[4:5], exec, s[4:5]
	s_ashr_i32 s25, s24, 31
	s_or_saveexec_b64 s[4:5], s[4:5]
	v_mul_i32_i24_e32 v2, 0x10800, v71
	v_mov_b64_e32 v[22:23], s[24:25]
	v_ashrrev_i32_e32 v71, 31, v70
	s_xor_b64 exec, exec, s[4:5]
	s_cbranch_execz .LBB0_2345
	v_lshlrev_b32_e32 v4, 1, v28
	v_and_b32_e32 v21, 62, v4
	v_or_b32_e32 v4, s24, v21
	s_add_i32 s6, s24, 0xb00
	v_ashrrev_i32_e32 v5, 31, v4
	v_or_b32_e32 v12, s6, v21
	v_lshlrev_b64 v[10:11], 2, v[4:5]
	v_lshl_add_u64 v[14:15], s[12:13], 0, v[10:11]
	v_lshl_add_u64 v[18:19], s[22:23], 0, v[10:11]
	v_ashrrev_i32_e32 v13, 31, v12
	v_lshl_add_u64 v[16:17], s[20:21], 0, v[10:11]
	global_load_dwordx2 v[4:5], v[14:15], off
	global_load_dwordx2 v[6:7], v[16:17], off
	global_load_dwordx2 v[8:9], v[18:19], off
	v_lshlrev_b64 v[18:19], 2, v[12:13]
	v_lshl_add_u64 v[10:11], s[14:15], 0, v[10:11]
	v_lshl_add_u64 v[22:23], s[12:13], 0, v[18:19]
	global_load_dwordx2 v[10:11], v[10:11], off
	v_lshl_add_u64 v[24:25], s[20:21], 0, v[18:19]
	v_lshl_add_u64 v[26:27], s[22:23], 0, v[18:19]
	global_load_dwordx2 v[12:13], v[22:23], off
	global_load_dwordx2 v[14:15], v[24:25], off
	global_load_dwordx2 v[16:17], v[26:27], off
	v_lshl_add_u64 v[18:19], s[14:15], 0, v[18:19]
	global_load_dwordx2 v[18:19], v[18:19], off
	v_lshlrev_b32_e32 v136, 1, v21
	v_mul_lo_u32 v22, v38, s31
	v_mul_lo_u32 v20, v20, s31
	v_add3_u32 v22, v2, v22, v136
	v_add3_u32 v20, v2, v20, v136
	ds_read2_b32 v[22:23], v22 offset1:32
	ds_read2_b32 v[20:21], v20 offset1:32
	s_ashr_i32 s25, s24, 31
	s_lshl_b64 s[6:7], s[24:25], 1
	s_add_u32 s6, s10, s6
	s_addc_u32 s7, s11, s7
	v_lshrrev_b32_e32 v29, 4, v29
	v_and_b32_e32 v28, 31, v28
	s_waitcnt lgkmcnt(1)
	v_lshlrev_b32_e32 v32, 16, v23
	v_and_b32_e32 v33, 0xffff0000, v23
	v_lshlrev_b32_e32 v34, 16, v22
	v_and_b32_e32 v35, 0xffff0000, v22
	v_lshl_add_u64 v[22:23], s[6:7], 0, v[136:137]
	v_mad_u64_u32 v[30:31], s[6:7], v29, s33, v[2:3]
	v_lshlrev_b32_e32 v28, 2, v28
	s_waitcnt lgkmcnt(0)
	v_lshlrev_b32_e32 v24, 16, v21
	v_and_b32_e32 v25, 0xffff0000, v21
	v_lshlrev_b32_e32 v26, 16, v20
	v_and_b32_e32 v27, 0xffff0000, v20
	v_lshlrev_b64 v[20:21], 11, v[70:71]
	v_add3_u32 v39, v30, v28, s34
	s_mov_b64 s[6:7], 0
	s_waitcnt vmcnt(0)
	s_branch .LBB0_2340

; template <bool SWAP, class Epi, bool THIN = false> ...
;     ...
;     for (int st = 0; st < ns; ++st) {
;       asm volatile("s_waitcnt vmcnt(0)" ::: "memory");
;       __builtin_amdgcn_s_barrier();
;       asm volatile("" ::: "memory");
;       if (st + 1 < ns) {
;         char* nb = smem + ((st + 1) & 1) * 65536;
;         const int ko = (st + 1) * 64;
; #pragma unroll
;         for (int i = 0; i < 4; ++i) { GLDS16(A + (size_t)(ap[i] + ko), nb + tid * 16 + i * 8192); GLDS16(Bt + (size_t)(bp[i] + ko), nb + 32768 + tid * 16 + i * 8192); }
;       }
;       const char* sa = smem + (st & 1) * 65536 + (wr * 64 + fr) * 128;
;       const char* sb = smem + (st & 1) * 65536 + 32768 + (wc * 128 + fr) * 128;
;       if constexpr (THIN) {
;         if (wc == 0) {
; #pragma unroll
;           for (int ks = 0; ks < 2; ++ks) {
;             bf16x8 af[4], bf[2];
; #pragma unroll
;             for (int m = 0; m < 4; ++m) af[m] = *(const bf16x8*)(sa + m * 2048 + (((ks * 4 + fq) ^ swz) << 4));
; #pragma unroll
;             for (int n = 0; n < 2; ++n) bf[n] = *(const bf16x8*)(sb + n * 2048 + (((ks * 4 + fq) ^ swz) << 4));
; #pragma unroll
;             for (int m = 0; m < 4; ++m)
; #pragma unroll
;               for (int n = 0; n < 2; ++n)
;                 acc[m][n] = SWAP ? __builtin_amdgcn_mfma_f32_16x16x32_bf16(bf[n], af[m], acc[m][n], 0, 0, 0)
;                                  : __builtin_amdgcn_mfma_f32_16x16x32_bf16(af[m], bf[n], acc[m][n], 0, 0, 0);
;           }
;         }
;       } else {
;       bf16x8 afA[4], afB[4], bfb[2][2];
; #pragma unroll
;       for (int m = 0; m < 4; ++m) afA[m] = *(const bf16x8*)(sa + m * 2048 + ((fq ^ swz) << 4));
; #pragma unroll
;       for (int n = 0; n < 2; ++n) bfb[0][n] = *(const bf16x8*)(sb + n * 2048 + ((fq ^ swz) << 4));
; #pragma unroll
;       for (int gq = 0; gq < 8; ++gq) {
;         const int ks = gq >> 2, nh = gq & 3;
;         if (gq < 7) {
;           const int ks2 = (gq + 1) >> 2, nh2 = (gq + 1) & 3;
; #pragma unroll
;           for (int n = 0; n < 2; ++n) bfb[(gq + 1) & 1][n] = *(const bf16x8*)(sb + (nh2 * 2 + n) * 2048 + (((ks2 * 4 + fq) ^ swz) << 4));
;         }
;         if (gq == 3) {
; #pragma unroll
;           for (int m = 0; m < 4; ++m) afB[m] = *(const bf16x8*)(sa + m * 2048 + (((4 + fq) ^ swz) << 4));
;         }
;         __builtin_amdgcn_sched_barrier(0);
; #pragma unroll
.LBB0_2429:
	s_add_i32 s9, s7, 0x10000
	s_and_b32 s8, s9, 0x10000
	v_add_u32_e32 v139, s8, v144
	s_nop 0
	v_readfirstlane_b32 s10, v139
	s_waitcnt vmcnt(0)
	s_barrier
	s_and_b32 s7, s7, 0x10000
	v_add_u32_e32 v130, s7, v145
	v_add_u32_e32 v139, v130, v147
	ds_read_b128 v[168:171], v139
	ds_read_b128 v[172:175], v139 offset:2048
	ds_read_b128 v[176:179], v139 offset:4096
	ds_read_b128 v[180:183], v139 offset:6144
	v_or_b32_e32 v139, s7, v146
	v_add_u32_e32 v141, v139, v147
	ds_read_b128 v[184:187], v141 offset:32768
	ds_read_b128 v[188:191], v141 offset:34816
	ds_read_b128 v[192:195], v141 offset:36864
	ds_read_b128 v[196:199], v141 offset:38912
	v_add_u32_e32 v130, v130, v148
	s_waitcnt lgkmcnt(3)
	v_mfma_f32_16x16x32_bf16 v[126:129], v[184:187], v[168:171], v[126:129]
	s_mov_b32 m0, s10
	v_mfma_f32_16x16x32_bf16 v[110:113], v[184:187], v[172:175], v[110:113]
	global_load_lds_dwordx4 v138, s[22:23]
	v_add_u32_e32 v138, 0x80, v138
	v_mfma_f32_16x16x32_bf16 v[82:85], v[184:187], v[176:179], v[82:85]
	v_mfma_f32_16x16x32_bf16 v[50:53], v[184:187], v[180:183], v[50:53]
	ds_read_b128 v[184:187], v141 offset:40960
	ds_read_b128 v[200:203], v141 offset:43008
	s_waitcnt lgkmcnt(4)
	v_mfma_f32_16x16x32_bf16 v[122:125], v[188:191], v[168:171], v[122:125]
	s_add_u32 m0, s10, 0x8000
	v_mfma_f32_16x16x32_bf16 v[106:109], v[188:191], v[172:175], v[106:109]
	global_load_lds_dwordx4 v137, s[18:19]
	v_add_u32_e32 v137, 0x80, v137
	v_mfma_f32_16x16x32_bf16 v[78:81], v[188:191], v[176:179], v[78:81]
	v_mfma_f32_16x16x32_bf16 v[38:41], v[188:191], v[180:183], v[38:41]
	s_waitcnt lgkmcnt(3)
	v_mfma_f32_16x16x32_bf16 v[118:121], v[192:195], v[168:171], v[118:121]
	s_add_u32 m0, s10, 0x2000
	v_mfma_f32_16x16x32_bf16 v[94:97], v[192:195], v[172:175], v[94:97]
	global_load_lds_dwordx4 v136, s[22:23]
	v_add_u32_e32 v136, 0x80, v136
	v_mfma_f32_16x16x32_bf16 v[58:61], v[192:195], v[176:179], v[58:61]
	v_mfma_f32_16x16x32_bf16 v[26:29], v[192:195], v[180:183], v[26:29]
	ds_read_b128 v[188:191], v141 offset:45056
	ds_read_b128 v[192:195], v141 offset:47104
	s_waitcnt lgkmcnt(4)
	v_mfma_f32_16x16x32_bf16 v[114:117], v[196:199], v[168:171], v[114:117]
	s_add_u32 m0, s10, 0xa000
	v_mfma_f32_16x16x32_bf16 v[86:89], v[196:199], v[172:175], v[86:89]
	global_load_lds_dwordx4 v135, s[18:19]
	v_add_u32_e32 v135, 0x80, v135
	v_mfma_f32_16x16x32_bf16 v[54:57], v[196:199], v[176:179], v[54:57]
	v_mfma_f32_16x16x32_bf16 v[22:25], v[196:199], v[180:183], v[22:25]
	v_add_u32_e32 v139, v139, v148
	s_waitcnt lgkmcnt(3)
	v_mfma_f32_16x16x32_bf16 v[102:105], v[184:187], v[168:171], v[102:105]
	ds_read_b128 v[196:199], v139 offset:32768
	ds_read_b128 v[204:207], v139 offset:34816
	s_add_u32 m0, s10, 0x4000
	v_mfma_f32_16x16x32_bf16 v[74:77], v[184:187], v[172:175], v[74:77]
	global_load_lds_dwordx4 v134, s[22:23]
	v_add_u32_e32 v134, 0x80, v134
	v_mfma_f32_16x16x32_bf16 v[46:49], v[184:187], v[176:179], v[46:49]
	v_mfma_f32_16x16x32_bf16 v[10:13], v[184:187], v[180:183], v[10:13]
	ds_read_b128 v[184:187], v130
	ds_read_b128 v[208:211], v130 offset:2048
	ds_read_b128 v[212:215], v130 offset:4096
	ds_read_b128 v[216:219], v130 offset:6144
	s_waitcnt lgkmcnt(8)
	v_mfma_f32_16x16x32_bf16 v[98:101], v[200:203], v[168:171], v[98:101]
	s_add_u32 m0, s10, 0xc000
	v_mfma_f32_16x16x32_bf16 v[66:69], v[200:203], v[172:175], v[66:69]
	global_load_lds_dwordx4 v133, s[18:19]
	v_add_u32_e32 v133, 0x80, v133
	v_mfma_f32_16x16x32_bf16 v[34:37], v[200:203], v[176:179], v[34:37]
	v_mfma_f32_16x16x32_bf16 v[6:9], v[200:203], v[180:183], v[6:9]
	s_waitcnt lgkmcnt(7)
	v_mfma_f32_16x16x32_bf16 v[70:73], v[188:191], v[168:171], v[70:73]
	s_add_u32 m0, s10, 0x6000
	s_waitcnt lgkmcnt(6)
	v_mfma_f32_16x16x32_bf16 v[62:65], v[192:195], v[168:171], v[62:65]
	global_load_lds_dwordx4 v132, s[22:23]
	v_add_u32_e32 v132, 0x80, v132
	v_mfma_f32_16x16x32_bf16 v[42:45], v[188:191], v[172:175], v[42:45]
	v_mfma_f32_16x16x32_bf16 v[30:33], v[192:195], v[172:175], v[30:33]
	ds_read_b128 v[168:171], v139 offset:36864
	ds_read_b128 v[172:175], v139 offset:38912
	v_mfma_f32_16x16x32_bf16 v[18:21], v[188:191], v[176:179], v[18:21]
	s_add_u32 m0, s10, 0xe000
	v_mfma_f32_16x16x32_bf16 v[14:17], v[192:195], v[176:179], v[14:17]
	global_load_lds_dwordx4 v140, s[18:19]
	v_add_u32_e32 v140, 0x80, v140
	v_mfma_f32_16x16x32_bf16 v[2:5], v[188:191], v[180:183], v[2:5]
	v_mfma_f32_16x16x32_bf16 v[90:93], v[192:195], v[180:183], v[90:93]
	ds_read_b128 v[176:179], v139 offset:40960
	ds_read_b128 v[180:183], v139 offset:43008
	s_waitcnt lgkmcnt(7)
	v_mfma_f32_16x16x32_bf16 v[126:129], v[196:199], v[184:187], v[126:129]
	v_mfma_f32_16x16x32_bf16 v[122:125], v[204:207], v[184:187], v[122:125]
	s_waitcnt lgkmcnt(6)
	v_mfma_f32_16x16x32_bf16 v[110:113], v[196:199], v[208:211], v[110:113]
	v_mfma_f32_16x16x32_bf16 v[106:109], v[204:207], v[208:211], v[106:109]
	s_waitcnt lgkmcnt(5)
	v_mfma_f32_16x16x32_bf16 v[82:85], v[196:199], v[212:215], v[82:85]
	v_mfma_f32_16x16x32_bf16 v[78:81], v[204:207], v[212:215], v[78:81]
	s_waitcnt lgkmcnt(4)
	v_mfma_f32_16x16x32_bf16 v[50:53], v[196:199], v[216:219], v[50:53]
	v_mfma_f32_16x16x32_bf16 v[38:41], v[204:207], v[216:219], v[38:41]
	s_waitcnt lgkmcnt(3)
	v_mfma_f32_16x16x32_bf16 v[118:121], v[168:171], v[184:187], v[118:121]
	v_mfma_f32_16x16x32_bf16 v[94:97], v[168:171], v[208:211], v[94:97]
	v_mfma_f32_16x16x32_bf16 v[58:61], v[168:171], v[212:215], v[58:61]
	v_mfma_f32_16x16x32_bf16 v[26:29], v[168:171], v[216:219], v[26:29]
	ds_read_b128 v[168:171], v139 offset:45056
	ds_read_b128 v[188:191], v139 offset:47104
	s_waitcnt lgkmcnt(4)
; template <bool SWAP, class Epi, bool THIN = false> ...
;     ...
;     for (int st = 0; st < ns; ++st) {
;       asm volatile("s_waitcnt vmcnt(0)" ::: "memory");
;       __builtin_amdgcn_s_barrier();
;       asm volatile("" ::: "memory");
;       if (st + 1 < ns) {
;         char* nb = smem + ((st + 1) & 1) * 65536;
;         const int ko = (st + 1) * 64;
; #pragma unroll
;         for (int i = 0; i < 4; ++i) { GLDS16(A + (size_t)(ap[i] + ko), nb + tid * 16 + i * 8192); GLDS16(Bt + (size_t)(bp[i] + ko), nb + 32768 + tid * 16 + i * 8192); }
;       }
;       const char* sa = smem + (st & 1) * 65536 + (wr * 64 + fr) * 128;
;       const char* sb = smem + (st & 1) * 65536 + 32768 + (wc * 128 + fr) * 128;
;       if constexpr (THIN) {
;         if (wc == 0) {
; #pragma unroll
;           for (int ks = 0; ks < 2; ++ks) {
;             bf16x8 af[4], bf[2];
; #pragma unroll
;             for (int m = 0; m < 4; ++m) af[m] = *(const bf16x8*)(sa + m * 2048 + (((ks * 4 + fq) ^ swz) << 4));
; #pragma unroll
;             for (int n = 0; n < 2; ++n) bf[n] = *(const bf16x8*)(sb + n * 2048 + (((ks * 4 + fq) ^ swz) << 4));
; #pragma unroll
;             for (int m = 0; m < 4; ++m)
; #pragma unroll
;               for (int n = 0; n < 2; ++n)
;                 acc[m][n] = SWAP ? __builtin_amdgcn_mfma_f32_16x16x32_bf16(bf[n], af[m], acc[m][n], 0, 0, 0)
;                                  : __builtin_amdgcn_mfma_f32_16x16x32_bf16(af[m], bf[n], acc[m][n], 0, 0, 0);
;           }
;         }
;       } else {
;       bf16x8 afA[4], afB[4], bfb[2][2];
; #pragma unroll
;       for (int m = 0; m < 4; ++m) afA[m] = *(const bf16x8*)(sa + m * 2048 + ((fq ^ swz) << 4));
; #pragma unroll
;       for (int n = 0; n < 2; ++n) bfb[0][n] = *(const bf16x8*)(sb + n * 2048 + ((fq ^ swz) << 4));
; #pragma unroll
;       for (int gq = 0; gq < 8; ++gq) {
;         const int ks = gq >> 2, nh = gq & 3;
;         if (gq < 7) {
;           const int ks2 = (gq + 1) >> 2, nh2 = (gq + 1) & 3;
; #pragma unroll
;           for (int n = 0; n < 2; ++n) bfb[(gq + 1) & 1][n] = *(const bf16x8*)(sb + (nh2 * 2 + n) * 2048 + (((ks2 * 4 + fq) ^ swz) << 4));
;         }
;         if (gq == 3) {
; #pragma unroll
;           for (int m = 0; m < 4; ++m) afB[m] = *(const bf16x8*)(sa + m * 2048 + (((4 + fq) ^ swz) << 4));
;         }
;         __builtin_amdgcn_sched_barrier(0);
; #pragma unroll
	v_mfma_f32_16x16x32_bf16 v[114:117], v[172:175], v[184:187], v[114:117]
	v_mfma_f32_16x16x32_bf16 v[86:89], v[172:175], v[208:211], v[86:89]
	v_mfma_f32_16x16x32_bf16 v[54:57], v[172:175], v[212:215], v[54:57]
	v_mfma_f32_16x16x32_bf16 v[22:25], v[172:175], v[216:219], v[22:25]
	s_waitcnt lgkmcnt(3)
	v_mfma_f32_16x16x32_bf16 v[102:105], v[176:179], v[184:187], v[102:105]
	s_waitcnt lgkmcnt(2)
	v_mfma_f32_16x16x32_bf16 v[98:101], v[180:183], v[184:187], v[98:101]
	v_mfma_f32_16x16x32_bf16 v[74:77], v[176:179], v[208:211], v[74:77]
	v_mfma_f32_16x16x32_bf16 v[66:69], v[180:183], v[208:211], v[66:69]
	v_mfma_f32_16x16x32_bf16 v[46:49], v[176:179], v[212:215], v[46:49]
	v_mfma_f32_16x16x32_bf16 v[34:37], v[180:183], v[212:215], v[34:37]
	v_mfma_f32_16x16x32_bf16 v[10:13], v[176:179], v[216:219], v[10:13]
	v_mfma_f32_16x16x32_bf16 v[6:9], v[180:183], v[216:219], v[6:9]
	s_waitcnt lgkmcnt(1)
	v_mfma_f32_16x16x32_bf16 v[70:73], v[168:171], v[184:187], v[70:73]
	s_add_i32 s6, s6, 64
	s_cmpk_eq_i32 s6, 0xac0
	s_mov_b32 s7, s9
	s_waitcnt lgkmcnt(0)
	v_mfma_f32_16x16x32_bf16 v[62:65], v[188:191], v[184:187], v[62:65]
	v_mfma_f32_16x16x32_bf16 v[42:45], v[168:171], v[208:211], v[42:45]
	v_mfma_f32_16x16x32_bf16 v[30:33], v[188:191], v[208:211], v[30:33]
	v_mfma_f32_16x16x32_bf16 v[18:21], v[168:171], v[212:215], v[18:21]
	v_mfma_f32_16x16x32_bf16 v[14:17], v[188:191], v[212:215], v[14:17]
	v_mfma_f32_16x16x32_bf16 v[2:5], v[168:171], v[216:219], v[2:5]
	v_mfma_f32_16x16x32_bf16 v[90:93], v[188:191], v[216:219], v[90:93]
	s_cbranch_scc0 .LBB0_2429
	v_add_u32_e32 v130, s8, v145
	s_waitcnt vmcnt(0)
	s_barrier
	v_add_u32_e32 v140, v130, v147
	ds_read_b128 v[132:135], v140
	ds_read_b128 v[136:139], v140 offset:2048
	ds_read_b128 v[168:171], v140 offset:4096
	ds_read_b128 v[172:175], v140 offset:6144
	v_add_u32_e32 v140, s8, v146
	v_add_u32_e32 v141, v140, v147
	ds_read_b128 v[176:179], v141 offset:32768
	ds_read_b128 v[180:183], v141 offset:34816
	ds_read_b128 v[184:187], v141 offset:36864
	ds_read_b128 v[188:191], v141 offset:38912
	v_add_u32_e32 v130, v130, v148
	s_waitcnt lgkmcnt(0)
	v_mfma_f32_16x16x32_bf16 v[126:129], v[176:179], v[132:135], v[126:129]
	v_mfma_f32_16x16x32_bf16 v[110:113], v[176:179], v[136:139], v[110:113]
	v_mfma_f32_16x16x32_bf16 v[82:85], v[176:179], v[168:171], v[82:85]
	v_mfma_f32_16x16x32_bf16 v[50:53], v[176:179], v[172:175], v[50:53]
	ds_read_b128 v[176:179], v141 offset:40960
	ds_read_b128 v[192:195], v141 offset:43008
	v_mfma_f32_16x16x32_bf16 v[122:125], v[180:183], v[132:135], v[122:125]
	v_mfma_f32_16x16x32_bf16 v[106:109], v[180:183], v[136:139], v[106:109]
	v_mfma_f32_16x16x32_bf16 v[78:81], v[180:183], v[168:171], v[78:81]
	v_mfma_f32_16x16x32_bf16 v[38:41], v[180:183], v[172:175], v[38:41]
	v_mfma_f32_16x16x32_bf16 v[118:121], v[184:187], v[132:135], v[118:121]
	v_mfma_f32_16x16x32_bf16 v[180:183], v[184:187], v[136:139], v[94:97]
	v_mfma_f32_16x16x32_bf16 v[200:203], v[184:187], v[168:171], v[58:61]
	v_mfma_f32_16x16x32_bf16 v[204:207], v[188:191], v[168:171], v[54:57]
	v_mfma_f32_16x16x32_bf16 v[184:187], v[184:187], v[172:175], v[26:29]
	s_nop 2
	ds_read_b128 v[26:29], v141 offset:45056
	ds_read_b128 v[54:57], v141 offset:47104
	v_mfma_f32_16x16x32_bf16 v[114:117], v[188:191], v[132:135], v[114:117]
	v_mfma_f32_16x16x32_bf16 v[196:199], v[188:191], v[136:139], v[86:89]
	v_mfma_f32_16x16x32_bf16 v[188:191], v[188:191], v[172:175], v[22:25]
	v_add_u32_e32 v140, v140, v148
	s_waitcnt lgkmcnt(0)
	v_mfma_f32_16x16x32_bf16 v[102:105], v[176:179], v[132:135], v[102:105]
	ds_read_b128 v[22:25], v140 offset:32768
	ds_read_b128 v[86:89], v140 offset:34816
	v_mfma_f32_16x16x32_bf16 v[74:77], v[176:179], v[136:139], v[74:77]
	v_mfma_f32_16x16x32_bf16 v[46:49], v[176:179], v[168:171], v[46:49]
	v_mfma_f32_16x16x32_bf16 v[10:13], v[176:179], v[172:175], v[10:13]
	ds_read_b128 v[176:179], v130
	ds_read_b128 v[208:211], v130 offset:2048
	ds_read_b128 v[212:215], v130 offset:4096
	ds_read_b128 v[216:219], v130 offset:6144
	v_mfma_f32_16x16x32_bf16 v[98:101], v[192:195], v[132:135], v[98:101]
	v_mfma_f32_16x16x32_bf16 v[66:69], v[192:195], v[136:139], v[66:69]
	v_mfma_f32_16x16x32_bf16 v[34:37], v[192:195], v[168:171], v[34:37]
	v_mfma_f32_16x16x32_bf16 v[6:9], v[192:195], v[172:175], v[6:9]
	v_mfma_f32_16x16x32_bf16 v[220:223], v[26:29], v[168:171], v[18:21]
	v_mfma_f32_16x16x32_bf16 v[168:171], v[54:57], v[168:171], v[14:17]
	s_nop 2
	ds_read_b128 v[14:17], v140 offset:36864
	ds_read_b128 v[18:21], v140 offset:38912
	v_mfma_f32_16x16x32_bf16 v[70:73], v[26:29], v[132:135], v[70:73]
	v_mfma_f32_16x16x32_bf16 v[132:135], v[54:57], v[132:135], v[62:65]
	v_mfma_f32_16x16x32_bf16 v[192:195], v[26:29], v[136:139], v[42:45]
	v_mfma_f32_16x16x32_bf16 v[136:139], v[54:57], v[136:139], v[30:33]
	v_mfma_f32_16x16x32_bf16 v[2:5], v[26:29], v[172:175], v[2:5]
	v_mfma_f32_16x16x32_bf16 v[172:175], v[54:57], v[172:175], v[90:93]
	ds_read_b128 v[224:227], v140 offset:40960
	ds_read_b128 v[228:231], v140 offset:43008
	s_waitcnt lgkmcnt(0)
	v_mfma_f32_16x16x32_bf16 v[126:129], v[22:25], v[176:179], v[126:129]
	v_mfma_f32_16x16x32_bf16 v[122:125], v[86:89], v[176:179], v[122:125]
	v_mfma_f32_16x16x32_bf16 v[94:97], v[22:25], v[208:211], v[110:113]
	v_mfma_f32_16x16x32_bf16 v[90:93], v[86:89], v[208:211], v[106:109]
	v_mfma_f32_16x16x32_bf16 v[62:65], v[22:25], v[212:215], v[82:85]
	v_mfma_f32_16x16x32_bf16 v[58:61], v[86:89], v[212:215], v[78:81]
	v_mfma_f32_16x16x32_bf16 v[30:33], v[22:25], v[216:219], v[50:53]
	v_mfma_f32_16x16x32_bf16 v[26:29], v[86:89], v[216:219], v[38:41]
	v_mfma_f32_16x16x32_bf16 v[86:89], v[14:17], v[208:211], v[180:183]
	v_mfma_f32_16x16x32_bf16 v[22:25], v[14:17], v[216:219], v[184:187]
	s_nop 1
	ds_read_b128 v[180:183], v140 offset:45056
	ds_read_b128 v[184:187], v140 offset:47104
	v_mfma_f32_16x16x32_bf16 v[118:121], v[14:17], v[176:179], v[118:121]
	v_mfma_f32_16x16x32_bf16 v[114:117], v[18:21], v[176:179], v[114:117]
	v_mfma_f32_16x16x32_bf16 v[82:85], v[18:21], v[208:211], v[196:199]
	v_mfma_f32_16x16x32_bf16 v[54:57], v[14:17], v[212:215], v[200:203]
	v_mfma_f32_16x16x32_bf16 v[50:53], v[18:21], v[212:215], v[204:207]
	v_mfma_f32_16x16x32_bf16 v[18:21], v[18:21], v[216:219], v[188:191]
	v_mfma_f32_16x16x32_bf16 v[110:113], v[224:227], v[176:179], v[102:105]
	v_mfma_f32_16x16x32_bf16 v[106:109], v[228:231], v[176:179], v[98:101]
	v_mfma_f32_16x16x32_bf16 v[78:81], v[224:227], v[208:211], v[74:77]
	v_mfma_f32_16x16x32_bf16 v[74:77], v[228:231], v[208:211], v[66:69]
	v_mfma_f32_16x16x32_bf16 v[46:49], v[224:227], v[212:215], v[46:49]
	v_mfma_f32_16x16x32_bf16 v[42:45], v[228:231], v[212:215], v[34:37]
	v_mfma_f32_16x16x32_bf16 v[14:17], v[224:227], v[216:219], v[10:13]
	v_mfma_f32_16x16x32_bf16 v[10:13], v[228:231], v[216:219], v[6:9]
	v_mov_b32_e32 v130, v1
	s_waitcnt vmcnt(0) lgkmcnt(0)
	s_barrier
; __device__ __forceinline__ int get_tid512() { int t = threadIdx.x; asm volatile("" : "+v"(t)); return t; }
; __device__ __forceinline__ unsigned pack2(float a, float b) { unsigned r; asm("v_cvt_pk_bf16_f32 %0, %1, %2" : "=v"(r) : "v"(a), "v"(b)); return r; }
; __device__ __forceinline__ float bf2f(bf16_t h) { return __uint_as_float(((unsigned)h) << 16); }
;   __device__ __forceinline__ void c4(int g, int rig, int col, f32x4 v) const {
;     const size_t o = ((size_t)g * 2048 + rig) * 1024 + col;
;     f32x4 bs;
;     if (BASE_F32) bs = __builtin_nontemporal_load((const f32x4*)((const float*)base + o));
;     else {
;       const uint2 u = *(const uint2*)((const bf16_t*)base + o);
;       bs[0] = bf2f((bf16_t)(u.x & 0xffff)); bs[1] = bf2f((bf16_t)(u.x >> 16)); bs[2] = bf2f((bf16_t)(u.y & 0xffff)); bs[3] = bf2f((bf16_t)(u.y >> 16));
;     }
;     const f32x4 gt = *(const f32x4*)(gate + (size_t)g * 6144 + col);
;     f32x4 bi = {0.f, 0.f, 0.f, 0.f};
;     if (bias) bi = *(const f32x4*)(bias + col);
;     f32x4 r;
; #pragma unroll
;     for (int j = 0; j < 4; ++j) r[j] = bs[j] + gt[j] * (v[j] + bi[j]);
;     uint2 w; w.x = pack2(r[0], r[1]); w.y = pack2(r[2], r[3]);
;     *(uint2*)(X16 + o) = w;
; template <bool SWAP, class Epi, bool THIN = false> ...
;     ...
;     const int te = get_tid512();
;     const int fr_e = te & 15, fq_e = (te & 63) >> 4, wr_e = te >> 7, wc_e = (te >> 6) & 1;
;     const int sub = 2 * mt + (wr_e >> 1);
;     const int g = sub / tpg, ti = sub - g * tpg;
;     const int rig0 = ti * step - halo;
;     const int rw = (wr_e & 1) * 64;
;     if constexpr (Epi::KIND == 0) {
; #pragma unroll
;       for (int m = 0; m < 4; ++m) {
;         const int rig = rig0 + rw + m * 16 + fr_e;
;         if constexpr (Epi::ROWSUM) {
;           float ss = 0.f;
; #pragma unroll
;           for (int n = 0; n < 8; ++n) {
;             const int col = nt * 256 + wc_e * 128 + n * 16 + fq_e * 4;
;             if (col < N) ss += epi.c4(g, rig, col, acc[m][n]);
;           }
;           ss += __shfl_xor(ss, 16); ss += __shfl_xor(ss, 32);
;           if (fq_e == 0) epi.rowsum(g, rig, nt * 2 + wc_e, ss);
;         } else {
; #pragma unroll
;           for (int n = 0; n < 8; ++n) {
;             const int col = nt * 256 + wc_e * 128 + n * 16 + fq_e * 4;
;             if (col < N) epi.c4(g, rig, col, acc[m][n]);
	v_mfma_f32_16x16x32_bf16 v[98:101], v[184:187], v[176:179], v[132:135]
	v_ashrrev_i32_e32 v7, 8, v130
	v_add_u32_e32 v7, s5, v7
	v_ashrrev_i32_e32 v8, 31, v7
	v_lshrrev_b32_e32 v8, 28, v8
	v_add_u32_e32 v8, v7, v8
	v_ashrrev_i32_e32 v134, 4, v8
	v_lshlrev_b32_e32 v8, 11, v134
	v_lshlrev_b32_e32 v7, 7, v7
	v_sub_u32_e32 v7, v7, v8
	v_lshrrev_b32_e32 v8, 1, v130
	v_and_b32_e32 v6, 15, v130
	v_and_b32_e32 v8, 64, v8
	v_mfma_f32_16x16x32_bf16 v[66:69], v[184:187], v[208:211], v[136:139]
	v_ashrrev_i32_e32 v135, 31, v134
	s_nop 1
	v_or3_b32 v136, v7, v8, v6
	v_lshlrev_b32_e32 v6, 1, v130
	v_and_b32_e32 v132, 0x80, v6
	v_mfma_f32_16x16x32_bf16 v[6:9], v[180:183], v[216:219], v[2:5]
	v_ashrrev_i32_e32 v137, 31, v136
	v_lshlrev_b64 v[138:139], 21, v[134:135]
	v_lshlrev_b64 v[140:141], 10, v[136:137]
	v_lshrrev_b32_e32 v2, 2, v130
	v_and_b32_e32 v2, 12, v2
	v_mfma_f32_16x16x32_bf16 v[102:105], v[180:183], v[176:179], v[70:73]
	v_or3_b32 v132, v2, v132, s4
	v_mad_i64_i32 v[134:135], s[4:5], v134, s31, 0
	v_mfma_f32_16x16x32_bf16 v[70:73], v[180:183], v[208:211], v[192:195]
	v_lshl_add_u64 v[140:141], v[140:141], 0, v[138:139]
	v_cmp_gt_i32_e32 vcc, s34, v132
	v_ashrrev_i32_e32 v133, 31, v132
	v_mfma_f32_16x16x32_bf16 v[38:41], v[180:183], v[212:215], v[220:223]
	v_lshl_add_u64 v[134:135], s[24:25], 0, v[134:135]
	v_lshl_add_u64 v[140:141], v[140:141], 1, s[20:21]
	v_mfma_f32_16x16x32_bf16 v[34:37], v[184:187], v[212:215], v[168:171]
	v_mfma_f32_16x16x32_bf16 v[2:5], v[184:187], v[216:219], v[172:175]
	s_and_saveexec_b64 s[4:5], vcc
	s_cbranch_execz .LBB0_2432
	s_nop 0
	v_lshl_add_u64 v[172:173], v[132:133], 1, v[140:141]
	global_load_dwordx2 v[174:175], v[172:173], off
	v_lshl_add_u64 v[168:169], v[132:133], 2, v[134:135]
	global_load_dwordx4 v[168:171], v[168:169], off
	v_add_f32_e32 v126, 0, v126
	v_add_f32_e32 v127, 0, v127
	v_add_f32_e32 v128, 0, v128
	v_add_f32_e32 v129, 0, v129
	s_waitcnt vmcnt(1)
	v_lshlrev_b32_e32 v130, 16, v174
	v_and_b32_e32 v137, 0xffff0000, v174
	v_lshlrev_b32_e32 v167, 16, v175
	v_and_b32_e32 v174, 0xffff0000, v175
	s_waitcnt vmcnt(0)
	v_fmac_f32_e32 v130, v126, v168
	v_fmac_f32_e32 v137, v127, v169
	v_fmac_f32_e32 v167, v128, v170
	v_fmac_f32_e32 v174, v129, v171
	v_cvt_pk_bf16_f32 v126, v130, v137
	v_cvt_pk_bf16_f32 v127, v167, v174
	global_store_dwordx2 v[172:173], v[126:127], off

; template <bool SWAP, class Epi, bool THIN = false> ...
;     ...
;     for (int st = 0; st < ns; ++st) {
;       asm volatile("s_waitcnt vmcnt(0)" ::: "memory");
;       __builtin_amdgcn_s_barrier();
;       asm volatile("" ::: "memory");
;       if (st + 1 < ns) {
;         char* nb = smem + ((st + 1) & 1) * 65536;
;         const int ko = (st + 1) * 64;
; #pragma unroll
;         for (int i = 0; i < 4; ++i) { GLDS16(A + (size_t)(ap[i] + ko), nb + tid * 16 + i * 8192); GLDS16(Bt + (size_t)(bp[i] + ko), nb + 32768 + tid * 16 + i * 8192); }
;       }
;       const char* sa = smem + (st & 1) * 65536 + (wr * 64 + fr) * 128;
;       const char* sb = smem + (st & 1) * 65536 + 32768 + (wc * 128 + fr) * 128;
;       if constexpr (THIN) {
;         if (wc == 0) {
; #pragma unroll
;           for (int ks = 0; ks < 2; ++ks) {
;             bf16x8 af[4], bf[2];
; #pragma unroll
;             for (int m = 0; m < 4; ++m) af[m] = *(const bf16x8*)(sa + m * 2048 + (((ks * 4 + fq) ^ swz) << 4));
; #pragma unroll
;             for (int n = 0; n < 2; ++n) bf[n] = *(const bf16x8*)(sb + n * 2048 + (((ks * 4 + fq) ^ swz) << 4));
; #pragma unroll
;             for (int m = 0; m < 4; ++m)
; #pragma unroll
;               for (int n = 0; n < 2; ++n)
;                 acc[m][n] = SWAP ? __builtin_amdgcn_mfma_f32_16x16x32_bf16(bf[n], af[m], acc[m][n], 0, 0, 0)
;                                  : __builtin_amdgcn_mfma_f32_16x16x32_bf16(af[m], bf[n], acc[m][n], 0, 0, 0);
;           }
;         }
;       } else {
;       bf16x8 afA[4], afB[4], bfb[2][2];
; #pragma unroll
;       for (int m = 0; m < 4; ++m) afA[m] = *(const bf16x8*)(sa + m * 2048 + ((fq ^ swz) << 4));
; #pragma unroll
;       for (int n = 0; n < 2; ++n) bfb[0][n] = *(const bf16x8*)(sb + n * 2048 + ((fq ^ swz) << 4));
; #pragma unroll
;       for (int gq = 0; gq < 8; ++gq) {
;         const int ks = gq >> 2, nh = gq & 3;
;         if (gq < 7) {
;           const int ks2 = (gq + 1) >> 2, nh2 = (gq + 1) & 3;
; #pragma unroll
;           for (int n = 0; n < 2; ++n) bfb[(gq + 1) & 1][n] = *(const bf16x8*)(sb + (nh2 * 2 + n) * 2048 + (((ks2 * 4 + fq) ^ swz) << 4));
;         }
;         if (gq == 3) {
; #pragma unroll
;           for (int m = 0; m < 4; ++m) afB[m] = *(const bf16x8*)(sa + m * 2048 + (((4 + fq) ^ swz) << 4));
;         }
;         __builtin_amdgcn_sched_barrier(0);
; #pragma unroll
.LBB0_2643:
	s_add_i32 s8, s7, 0x10000
	s_and_b32 s9, s8, 0x10000
	v_add_u32_e32 v167, s9, v142
	s_nop 0
	v_readfirstlane_b32 s9, v167
	s_waitcnt vmcnt(0)
	s_barrier
	s_and_b32 s7, s7, 0x10000
	v_add_u32_e32 v130, s7, v143
	v_add_u32_e32 v167, v130, v145
	ds_read_b128 v[168:171], v167
	ds_read_b128 v[172:175], v167 offset:2048
	ds_read_b128 v[176:179], v167 offset:4096
	ds_read_b128 v[180:183], v167 offset:6144
	v_or_b32_e32 v167, s7, v144
	v_add_u32_e32 v204, v167, v145
	ds_read_b128 v[184:187], v204 offset:32768
	ds_read_b128 v[188:191], v204 offset:34816
	ds_read_b128 v[192:195], v204 offset:36864
	ds_read_b128 v[196:199], v204 offset:38912
	v_add_u32_e32 v130, v130, v146
	s_waitcnt lgkmcnt(3)
	v_mfma_f32_16x16x32_bf16 v[126:129], v[184:187], v[168:171], v[126:129]
	s_mov_b32 m0, s9
	v_mfma_f32_16x16x32_bf16 v[110:113], v[184:187], v[172:175], v[110:113]
	global_load_lds_dwordx4 v139, s[18:19]
	v_add_u32_e32 v139, 0x80, v139
	v_mfma_f32_16x16x32_bf16 v[82:85], v[184:187], v[176:179], v[82:85]
	v_mfma_f32_16x16x32_bf16 v[50:53], v[184:187], v[180:183], v[50:53]
	ds_read_b128 v[184:187], v204 offset:40960
	ds_read_b128 v[200:203], v204 offset:43008
	s_waitcnt lgkmcnt(4)
	v_mfma_f32_16x16x32_bf16 v[122:125], v[188:191], v[168:171], v[122:125]
	s_add_u32 m0, s9, 0x8000
	v_mfma_f32_16x16x32_bf16 v[106:109], v[188:191], v[172:175], v[106:109]
	global_load_lds_dwordx4 v138, s[24:25]
	v_add_u32_e32 v138, 0x80, v138
	v_mfma_f32_16x16x32_bf16 v[78:81], v[188:191], v[176:179], v[78:81]
	v_mfma_f32_16x16x32_bf16 v[42:45], v[188:191], v[180:183], v[42:45]
	s_waitcnt lgkmcnt(3)
	v_mfma_f32_16x16x32_bf16 v[118:121], v[192:195], v[168:171], v[118:121]
	s_add_u32 m0, s9, 0x2000
	v_mfma_f32_16x16x32_bf16 v[94:97], v[192:195], v[172:175], v[94:97]
	global_load_lds_dwordx4 v137, s[18:19]
	v_add_u32_e32 v137, 0x80, v137
	v_mfma_f32_16x16x32_bf16 v[58:61], v[192:195], v[176:179], v[58:61]
	v_mfma_f32_16x16x32_bf16 v[26:29], v[192:195], v[180:183], v[26:29]
	ds_read_b128 v[188:191], v204 offset:45056
	ds_read_b128 v[192:195], v204 offset:47104
	s_waitcnt lgkmcnt(4)
	v_mfma_f32_16x16x32_bf16 v[114:117], v[196:199], v[168:171], v[114:117]
	s_add_u32 m0, s9, 0xa000
	v_mfma_f32_16x16x32_bf16 v[86:89], v[196:199], v[172:175], v[86:89]
	global_load_lds_dwordx4 v136, s[24:25]
	v_add_u32_e32 v136, 0x80, v136
	v_mfma_f32_16x16x32_bf16 v[54:57], v[196:199], v[176:179], v[54:57]
	v_mfma_f32_16x16x32_bf16 v[22:25], v[196:199], v[180:183], v[22:25]
	v_add_u32_e32 v167, v167, v146
	s_waitcnt lgkmcnt(3)
	v_mfma_f32_16x16x32_bf16 v[102:105], v[184:187], v[168:171], v[102:105]
	ds_read_b128 v[196:199], v167 offset:32768
	ds_read_b128 v[204:207], v167 offset:34816
	s_add_u32 m0, s9, 0x4000
	v_mfma_f32_16x16x32_bf16 v[74:77], v[184:187], v[172:175], v[74:77]
	global_load_lds_dwordx4 v135, s[18:19]
	v_add_u32_e32 v135, 0x80, v135
	v_mfma_f32_16x16x32_bf16 v[46:49], v[184:187], v[176:179], v[46:49]
	v_mfma_f32_16x16x32_bf16 v[10:13], v[184:187], v[180:183], v[10:13]
	ds_read_b128 v[184:187], v130
	ds_read_b128 v[208:211], v130 offset:2048
	ds_read_b128 v[212:215], v130 offset:4096
	ds_read_b128 v[216:219], v130 offset:6144
	s_waitcnt lgkmcnt(8)
	v_mfma_f32_16x16x32_bf16 v[98:101], v[200:203], v[168:171], v[98:101]
	s_add_u32 m0, s9, 0xc000
	v_mfma_f32_16x16x32_bf16 v[66:69], v[200:203], v[172:175], v[66:69]
	global_load_lds_dwordx4 v134, s[24:25]
	v_add_u32_e32 v134, 0x80, v134
	v_mfma_f32_16x16x32_bf16 v[30:33], v[200:203], v[176:179], v[30:33]
	v_mfma_f32_16x16x32_bf16 v[6:9], v[200:203], v[180:183], v[6:9]
	s_waitcnt lgkmcnt(7)
	v_mfma_f32_16x16x32_bf16 v[70:73], v[188:191], v[168:171], v[70:73]
	s_add_u32 m0, s9, 0x6000
	s_waitcnt lgkmcnt(6)
	v_mfma_f32_16x16x32_bf16 v[62:65], v[192:195], v[168:171], v[62:65]
	global_load_lds_dwordx4 v133, s[18:19]
	v_add_u32_e32 v133, 0x80, v133
	v_mfma_f32_16x16x32_bf16 v[38:41], v[188:191], v[172:175], v[38:41]
	v_mfma_f32_16x16x32_bf16 v[34:37], v[192:195], v[172:175], v[34:37]
	ds_read_b128 v[168:171], v167 offset:36864
	ds_read_b128 v[172:175], v167 offset:38912
	v_mfma_f32_16x16x32_bf16 v[18:21], v[188:191], v[176:179], v[18:21]
	s_add_u32 m0, s9, 0xe000
	v_mfma_f32_16x16x32_bf16 v[14:17], v[192:195], v[176:179], v[14:17]
	global_load_lds_dwordx4 v132, s[24:25]
	v_add_u32_e32 v132, 0x80, v132
	v_mfma_f32_16x16x32_bf16 v[2:5], v[188:191], v[180:183], v[2:5]
	v_mfma_f32_16x16x32_bf16 v[90:93], v[192:195], v[180:183], v[90:93]
	ds_read_b128 v[176:179], v167 offset:40960
	ds_read_b128 v[180:183], v167 offset:43008
	s_waitcnt lgkmcnt(7)
	v_mfma_f32_16x16x32_bf16 v[126:129], v[196:199], v[184:187], v[126:129]
	v_mfma_f32_16x16x32_bf16 v[122:125], v[204:207], v[184:187], v[122:125]
	s_waitcnt lgkmcnt(6)
	v_mfma_f32_16x16x32_bf16 v[110:113], v[196:199], v[208:211], v[110:113]
	v_mfma_f32_16x16x32_bf16 v[106:109], v[204:207], v[208:211], v[106:109]
	s_waitcnt lgkmcnt(5)
	v_mfma_f32_16x16x32_bf16 v[82:85], v[196:199], v[212:215], v[82:85]
	v_mfma_f32_16x16x32_bf16 v[78:81], v[204:207], v[212:215], v[78:81]
	s_waitcnt lgkmcnt(4)
	v_mfma_f32_16x16x32_bf16 v[50:53], v[196:199], v[216:219], v[50:53]
	v_mfma_f32_16x16x32_bf16 v[42:45], v[204:207], v[216:219], v[42:45]
	s_waitcnt lgkmcnt(3)
	v_mfma_f32_16x16x32_bf16 v[118:121], v[168:171], v[184:187], v[118:121]
	v_mfma_f32_16x16x32_bf16 v[94:97], v[168:171], v[208:211], v[94:97]
	v_mfma_f32_16x16x32_bf16 v[58:61], v[168:171], v[212:215], v[58:61]
	v_mfma_f32_16x16x32_bf16 v[26:29], v[168:171], v[216:219], v[26:29]
	ds_read_b128 v[168:171], v167 offset:45056
	ds_read_b128 v[188:191], v167 offset:47104
	s_waitcnt lgkmcnt(4)
; template <bool SWAP, class Epi, bool THIN = false> ...
;     ...
;     for (int st = 0; st < ns; ++st) {
;       asm volatile("s_waitcnt vmcnt(0)" ::: "memory");
;       __builtin_amdgcn_s_barrier();
;       asm volatile("" ::: "memory");
;       if (st + 1 < ns) {
;         char* nb = smem + ((st + 1) & 1) * 65536;
;         const int ko = (st + 1) * 64;
; #pragma unroll
;         for (int i = 0; i < 4; ++i) { GLDS16(A + (size_t)(ap[i] + ko), nb + tid * 16 + i * 8192); GLDS16(Bt + (size_t)(bp[i] + ko), nb + 32768 + tid * 16 + i * 8192); }
;       }
;       const char* sa = smem + (st & 1) * 65536 + (wr * 64 + fr) * 128;
;       const char* sb = smem + (st & 1) * 65536 + 32768 + (wc * 128 + fr) * 128;
;       if constexpr (THIN) {
;         if (wc == 0) {
; #pragma unroll
;           for (int ks = 0; ks < 2; ++ks) {
;             bf16x8 af[4], bf[2];
; #pragma unroll
;             for (int m = 0; m < 4; ++m) af[m] = *(const bf16x8*)(sa + m * 2048 + (((ks * 4 + fq) ^ swz) << 4));
; #pragma unroll
;             for (int n = 0; n < 2; ++n) bf[n] = *(const bf16x8*)(sb + n * 2048 + (((ks * 4 + fq) ^ swz) << 4));
; #pragma unroll
;             for (int m = 0; m < 4; ++m)
; #pragma unroll
;               for (int n = 0; n < 2; ++n)
;                 acc[m][n] = SWAP ? __builtin_amdgcn_mfma_f32_16x16x32_bf16(bf[n], af[m], acc[m][n], 0, 0, 0)
;                                  : __builtin_amdgcn_mfma_f32_16x16x32_bf16(af[m], bf[n], acc[m][n], 0, 0, 0);
;           }
;         }
;       } else {
;       bf16x8 afA[4], afB[4], bfb[2][2];
; #pragma unroll
;       for (int m = 0; m < 4; ++m) afA[m] = *(const bf16x8*)(sa + m * 2048 + ((fq ^ swz) << 4));
; #pragma unroll
;       for (int n = 0; n < 2; ++n) bfb[0][n] = *(const bf16x8*)(sb + n * 2048 + ((fq ^ swz) << 4));
; #pragma unroll
;       for (int gq = 0; gq < 8; ++gq) {
;         const int ks = gq >> 2, nh = gq & 3;
;         if (gq < 7) {
;           const int ks2 = (gq + 1) >> 2, nh2 = (gq + 1) & 3;
; #pragma unroll
;           for (int n = 0; n < 2; ++n) bfb[(gq + 1) & 1][n] = *(const bf16x8*)(sb + (nh2 * 2 + n) * 2048 + (((ks2 * 4 + fq) ^ swz) << 4));
;         }
;         if (gq == 3) {
; #pragma unroll
;           for (int m = 0; m < 4; ++m) afB[m] = *(const bf16x8*)(sa + m * 2048 + (((4 + fq) ^ swz) << 4));
;         }
;         __builtin_amdgcn_sched_barrier(0);
; #pragma unroll
	v_mfma_f32_16x16x32_bf16 v[114:117], v[172:175], v[184:187], v[114:117]
	v_mfma_f32_16x16x32_bf16 v[86:89], v[172:175], v[208:211], v[86:89]
	v_mfma_f32_16x16x32_bf16 v[54:57], v[172:175], v[212:215], v[54:57]
	v_mfma_f32_16x16x32_bf16 v[22:25], v[172:175], v[216:219], v[22:25]
	s_waitcnt lgkmcnt(3)
	v_mfma_f32_16x16x32_bf16 v[102:105], v[176:179], v[184:187], v[102:105]
	s_waitcnt lgkmcnt(2)
	v_mfma_f32_16x16x32_bf16 v[98:101], v[180:183], v[184:187], v[98:101]
	v_mfma_f32_16x16x32_bf16 v[74:77], v[176:179], v[208:211], v[74:77]
	v_mfma_f32_16x16x32_bf16 v[66:69], v[180:183], v[208:211], v[66:69]
	v_mfma_f32_16x16x32_bf16 v[46:49], v[176:179], v[212:215], v[46:49]
	v_mfma_f32_16x16x32_bf16 v[30:33], v[180:183], v[212:215], v[30:33]
	v_mfma_f32_16x16x32_bf16 v[10:13], v[176:179], v[216:219], v[10:13]
	v_mfma_f32_16x16x32_bf16 v[6:9], v[180:183], v[216:219], v[6:9]
	s_waitcnt lgkmcnt(1)
	v_mfma_f32_16x16x32_bf16 v[70:73], v[168:171], v[184:187], v[70:73]
	s_add_i32 s6, s6, 64
	s_cmpk_eq_i32 s6, 0x3c0
	s_mov_b32 s7, s8
	s_waitcnt lgkmcnt(0)
	v_mfma_f32_16x16x32_bf16 v[62:65], v[188:191], v[184:187], v[62:65]
	v_mfma_f32_16x16x32_bf16 v[38:41], v[168:171], v[208:211], v[38:41]
	v_mfma_f32_16x16x32_bf16 v[34:37], v[188:191], v[208:211], v[34:37]
	v_mfma_f32_16x16x32_bf16 v[18:21], v[168:171], v[212:215], v[18:21]
	v_mfma_f32_16x16x32_bf16 v[14:17], v[188:191], v[212:215], v[14:17]
	v_mfma_f32_16x16x32_bf16 v[2:5], v[168:171], v[216:219], v[2:5]
	v_mfma_f32_16x16x32_bf16 v[90:93], v[188:191], v[216:219], v[90:93]
	s_cbranch_scc0 .LBB0_2643
	s_waitcnt vmcnt(0)
	s_barrier
	v_add_u32_e32 v130, v157, v145
	ds_read_b128 v[132:135], v130
	ds_read_b128 v[136:139], v130 offset:2048
	ds_read_b128 v[168:171], v130 offset:4096
	ds_read_b128 v[172:175], v130 offset:6144
	v_add_u32_e32 v130, v158, v145
	ds_read_b128 v[176:179], v130
	ds_read_b128 v[180:183], v130 offset:2048
	ds_read_b128 v[184:187], v130 offset:4096
	ds_read_b128 v[188:191], v130 offset:6144
	s_waitcnt lgkmcnt(0)
	v_mfma_f32_16x16x32_bf16 v[126:129], v[176:179], v[132:135], v[126:129]
	v_mfma_f32_16x16x32_bf16 v[110:113], v[176:179], v[136:139], v[110:113]
	v_mfma_f32_16x16x32_bf16 v[82:85], v[176:179], v[168:171], v[82:85]
	v_mfma_f32_16x16x32_bf16 v[50:53], v[176:179], v[172:175], v[50:53]
	ds_read_b128 v[176:179], v130 offset:8192
	ds_read_b128 v[192:195], v130 offset:10240
	v_mfma_f32_16x16x32_bf16 v[122:125], v[180:183], v[132:135], v[122:125]
	v_mfma_f32_16x16x32_bf16 v[106:109], v[180:183], v[136:139], v[106:109]
	v_mfma_f32_16x16x32_bf16 v[78:81], v[180:183], v[168:171], v[78:81]
	v_mfma_f32_16x16x32_bf16 v[42:45], v[180:183], v[172:175], v[42:45]
	v_mfma_f32_16x16x32_bf16 v[118:121], v[184:187], v[132:135], v[118:121]
	v_mfma_f32_16x16x32_bf16 v[180:183], v[184:187], v[136:139], v[94:97]
	v_mfma_f32_16x16x32_bf16 v[200:203], v[184:187], v[168:171], v[58:61]
	v_mfma_f32_16x16x32_bf16 v[204:207], v[188:191], v[168:171], v[54:57]
	v_mfma_f32_16x16x32_bf16 v[184:187], v[184:187], v[172:175], v[26:29]
	s_nop 2
	ds_read_b128 v[26:29], v130 offset:12288
	ds_read_b128 v[54:57], v130 offset:14336
	v_mfma_f32_16x16x32_bf16 v[114:117], v[188:191], v[132:135], v[114:117]
	v_mfma_f32_16x16x32_bf16 v[196:199], v[188:191], v[136:139], v[86:89]
	v_mfma_f32_16x16x32_bf16 v[188:191], v[188:191], v[172:175], v[22:25]
	v_add_u32_e32 v130, v158, v146
	s_waitcnt lgkmcnt(0)
	v_mfma_f32_16x16x32_bf16 v[208:211], v[192:195], v[168:171], v[30:33]
	ds_read_b128 v[22:25], v130
	ds_read_b128 v[86:89], v130 offset:2048
	s_nop 0
	v_add_u32_e32 v30, v157, v146
	v_mfma_f32_16x16x32_bf16 v[102:105], v[176:179], v[132:135], v[102:105]
	v_mfma_f32_16x16x32_bf16 v[74:77], v[176:179], v[136:139], v[74:77]
	v_mfma_f32_16x16x32_bf16 v[46:49], v[176:179], v[168:171], v[46:49]
	v_mfma_f32_16x16x32_bf16 v[10:13], v[176:179], v[172:175], v[10:13]
	ds_read_b128 v[176:179], v30
	ds_read_b128 v[212:215], v30 offset:2048
	ds_read_b128 v[216:219], v30 offset:4096
	ds_read_b128 v[220:223], v30 offset:6144
	v_mfma_f32_16x16x32_bf16 v[98:101], v[192:195], v[132:135], v[98:101]
	v_mfma_f32_16x16x32_bf16 v[66:69], v[192:195], v[136:139], v[66:69]
	v_mfma_f32_16x16x32_bf16 v[6:9], v[192:195], v[172:175], v[6:9]
	v_mfma_f32_16x16x32_bf16 v[224:227], v[26:29], v[136:139], v[38:41]
	v_mfma_f32_16x16x32_bf16 v[34:37], v[54:57], v[136:139], v[34:37]
	v_mfma_f32_16x16x32_bf16 v[136:139], v[26:29], v[168:171], v[18:21]
	v_mfma_f32_16x16x32_bf16 v[168:171], v[54:57], v[168:171], v[14:17]
	s_nop 2
	ds_read_b128 v[14:17], v130 offset:4096
	ds_read_b128 v[18:21], v130 offset:6144
	v_mfma_f32_16x16x32_bf16 v[192:195], v[26:29], v[132:135], v[70:73]
	v_mfma_f32_16x16x32_bf16 v[132:135], v[54:57], v[132:135], v[62:65]
	v_mfma_f32_16x16x32_bf16 v[2:5], v[26:29], v[172:175], v[2:5]
	v_mfma_f32_16x16x32_bf16 v[172:175], v[54:57], v[172:175], v[90:93]
	ds_read_b128 v[228:231], v130 offset:8192
	ds_read_b128 v[232:235], v130 offset:10240
	s_waitcnt lgkmcnt(0)
	v_mfma_f32_16x16x32_bf16 v[126:129], v[22:25], v[176:179], v[126:129]
	v_mfma_f32_16x16x32_bf16 v[122:125], v[86:89], v[176:179], v[122:125]
	v_mfma_f32_16x16x32_bf16 v[94:97], v[22:25], v[212:215], v[110:113]
	v_mfma_f32_16x16x32_bf16 v[90:93], v[86:89], v[212:215], v[106:109]
	v_mfma_f32_16x16x32_bf16 v[62:65], v[22:25], v[216:219], v[82:85]
	v_mfma_f32_16x16x32_bf16 v[58:61], v[86:89], v[216:219], v[78:81]
	v_mfma_f32_16x16x32_bf16 v[30:33], v[22:25], v[220:223], v[50:53]
	v_mfma_f32_16x16x32_bf16 v[26:29], v[86:89], v[220:223], v[42:45]
	v_mfma_f32_16x16x32_bf16 v[86:89], v[14:17], v[212:215], v[180:183]
	v_mfma_f32_16x16x32_bf16 v[22:25], v[14:17], v[220:223], v[184:187]
	s_nop 1
	ds_read_b128 v[180:183], v130 offset:12288
	ds_read_b128 v[184:187], v130 offset:14336
	v_mfma_f32_16x16x32_bf16 v[118:121], v[14:17], v[176:179], v[118:121]
	v_mfma_f32_16x16x32_bf16 v[114:117], v[18:21], v[176:179], v[114:117]
	v_mfma_f32_16x16x32_bf16 v[82:85], v[18:21], v[212:215], v[196:199]
	v_mfma_f32_16x16x32_bf16 v[54:57], v[14:17], v[216:219], v[200:203]
	v_mfma_f32_16x16x32_bf16 v[50:53], v[18:21], v[216:219], v[204:207]
	v_mfma_f32_16x16x32_bf16 v[18:21], v[18:21], v[220:223], v[188:191]
	v_mfma_f32_16x16x32_bf16 v[110:113], v[228:231], v[176:179], v[102:105]
	v_mfma_f32_16x16x32_bf16 v[106:109], v[232:235], v[176:179], v[98:101]
	v_mfma_f32_16x16x32_bf16 v[78:81], v[228:231], v[212:215], v[74:77]
	v_mfma_f32_16x16x32_bf16 v[70:73], v[232:235], v[212:215], v[66:69]
	v_mfma_f32_16x16x32_bf16 v[46:49], v[228:231], v[216:219], v[46:49]
	v_mfma_f32_16x16x32_bf16 v[38:41], v[232:235], v[216:219], v[208:211]
	v_mfma_f32_16x16x32_bf16 v[14:17], v[228:231], v[220:223], v[10:13]
	v_mfma_f32_16x16x32_bf16 v[6:9], v[232:235], v[220:223], v[6:9]
	v_mov_b32_e32 v130, v1
	s_waitcnt vmcnt(0) lgkmcnt(0)
	s_barrier
; __device__ __forceinline__ int get_tid512() { int t = threadIdx.x; asm volatile("" : "+v"(t)); return t; }
; __device__ __forceinline__ unsigned pack2(float a, float b) { unsigned r; asm("v_cvt_pk_bf16_f32 %0, %1, %2" : "=v"(r) : "v"(a), "v"(b)); return r; }
;   __device__ __forceinline__ void c4(int g, int rig, int col, f32x4 v) const {
;     const size_t row = (size_t)g * 2048 + rig;
;     const f32x4 b4 = *(const f32x4*)(bias + col);
;     uint2 u; u.x = pack2(v[0] + b4[0], v[1] + b4[1]); u.y = pack2(v[2] + b4[2], v[3] + b4[3]);
;     *(uint2*)(out + row * ld + col) = u;
;   }
; template <bool SWAP, class Epi, bool THIN = false> ...
;     ...
;     const int te = get_tid512();
;     const int fr_e = te & 15, fq_e = (te & 63) >> 4, wr_e = te >> 7, wc_e = (te >> 6) & 1;
;     const int sub = 2 * mt + (wr_e >> 1);
;     const int g = sub / tpg, ti = sub - g * tpg;
;     const int rig0 = ti * step - halo;
;     const int rw = (wr_e & 1) * 64;
;     if constexpr (Epi::KIND == 0) {
; #pragma unroll
;       for (int m = 0; m < 4; ++m) {
;         const int rig = rig0 + rw + m * 16 + fr_e;
;         if constexpr (Epi::ROWSUM) {
;           float ss = 0.f;
; #pragma unroll
;           for (int n = 0; n < 8; ++n) {
;             const int col = nt * 256 + wc_e * 128 + n * 16 + fq_e * 4;
;             if (col < N) ss += epi.c4(g, rig, col, acc[m][n]);
;           }
;           ss += __shfl_xor(ss, 16); ss += __shfl_xor(ss, 32);
;           if (fq_e == 0) epi.rowsum(g, rig, nt * 2 + wc_e, ss);
;         } else {
; #pragma unroll
;           for (int n = 0; n < 8; ++n) {
;             const int col = nt * 256 + wc_e * 128 + n * 16 + fq_e * 4;
;             if (col < N) epi.c4(g, rig, col, acc[m][n]);
	v_mfma_f32_16x16x32_bf16 v[102:105], v[180:183], v[176:179], v[192:195]
	v_ashrrev_i32_e32 v11, 8, v130
	v_add_u32_e32 v11, s5, v11
	v_ashrrev_i32_e32 v12, 31, v11
	v_lshrrev_b32_e32 v12, 28, v12
	v_add_u32_e32 v12, v11, v12
	v_mfma_f32_16x16x32_bf16 v[98:101], v[184:187], v[176:179], v[132:135]
	v_ashrrev_i32_e32 v176, 4, v12
	v_lshlrev_b32_e32 v12, 11, v176
	v_lshlrev_b32_e32 v11, 7, v11
	v_sub_u32_e32 v11, v11, v12
	v_lshrrev_b32_e32 v12, 1, v130
	v_and_b32_e32 v10, 15, v130
	v_and_b32_e32 v12, 64, v12
	v_or3_b32 v134, v11, v12, v10
	v_lshlrev_b32_e32 v10, 1, v130
	v_and_b32_e32 v132, 0x80, v10
	v_mfma_f32_16x16x32_bf16 v[10:13], v[180:183], v[220:223], v[2:5]
	v_ashrrev_i32_e32 v177, 31, v176
	v_ashrrev_i32_e32 v135, 31, v134
	s_nop 0
	v_lshrrev_b32_e32 v2, 2, v130
	v_and_b32_e32 v2, 12, v2
	v_mfma_f32_16x16x32_bf16 v[74:77], v[180:183], v[212:215], v[224:227]
	v_or3_b32 v132, v2, v132, s4
	v_cmp_gt_i32_e32 vcc, s31, v132
	v_ashrrev_i32_e32 v133, 31, v132
	v_mfma_f32_16x16x32_bf16 v[66:69], v[184:187], v[212:215], v[34:37]
	v_mfma_f32_16x16x32_bf16 v[42:45], v[180:183], v[216:219], v[136:139]
	v_mfma_f32_16x16x32_bf16 v[34:37], v[184:187], v[216:219], v[168:171]
	s_nop 1
	v_lshlrev_b64 v[136:137], 11, v[176:177]
	v_lshl_add_u64 v[138:139], v[136:137], 0, v[134:135]
	v_lshlrev_b64 v[138:139], 11, v[138:139]
	v_mfma_f32_16x16x32_bf16 v[2:5], v[184:187], v[220:223], v[172:175]
	v_lshl_add_u64 v[138:139], s[20:21], 0, v[138:139]
	s_and_saveexec_b64 s[4:5], vcc
	s_cbranch_execz .LBB0_2646
	v_lshl_add_u64 v[168:169], v[132:133], 2, s[22:23]
	global_load_dwordx4 v[168:171], v[168:169], off
	s_waitcnt vmcnt(0)
	v_add_f32_e32 v126, v126, v168
	v_add_f32_e32 v127, v127, v169
	v_add_f32_e32 v128, v128, v170
	v_add_f32_e32 v129, v129, v171
	v_cvt_pk_bf16_f32 v126, v126, v127
	v_cvt_pk_bf16_f32 v127, v128, v129
	v_lshl_add_u64 v[128:129], v[132:133], 1, v[138:139]
	global_store_dwordx2 v[128:129], v[126:127], off

; template <bool SWAP, class Epi, bool THIN = false> ...
;     ...
;     for (int st = 0; st < ns; ++st) {
;       asm volatile("s_waitcnt vmcnt(0)" ::: "memory");
;       __builtin_amdgcn_s_barrier();
;       asm volatile("" ::: "memory");
;       if (st + 1 < ns) {
;         char* nb = smem + ((st + 1) & 1) * 65536;
;         const int ko = (st + 1) * 64;
; #pragma unroll
;         for (int i = 0; i < 4; ++i) { GLDS16(A + (size_t)(ap[i] + ko), nb + tid * 16 + i * 8192); GLDS16(Bt + (size_t)(bp[i] + ko), nb + 32768 + tid * 16 + i * 8192); }
;       }
;       const char* sa = smem + (st & 1) * 65536 + (wr * 64 + fr) * 128;
;       const char* sb = smem + (st & 1) * 65536 + 32768 + (wc * 128 + fr) * 128;
;       if constexpr (THIN) {
;         if (wc == 0) {
; #pragma unroll
;           for (int ks = 0; ks < 2; ++ks) {
;             bf16x8 af[4], bf[2];
; #pragma unroll
;             for (int m = 0; m < 4; ++m) af[m] = *(const bf16x8*)(sa + m * 2048 + (((ks * 4 + fq) ^ swz) << 4));
; #pragma unroll
;             for (int n = 0; n < 2; ++n) bf[n] = *(const bf16x8*)(sb + n * 2048 + (((ks * 4 + fq) ^ swz) << 4));
; #pragma unroll
;             for (int m = 0; m < 4; ++m)
; #pragma unroll
;               for (int n = 0; n < 2; ++n)
;                 acc[m][n] = SWAP ? __builtin_amdgcn_mfma_f32_16x16x32_bf16(bf[n], af[m], acc[m][n], 0, 0, 0)
;                                  : __builtin_amdgcn_mfma_f32_16x16x32_bf16(af[m], bf[n], acc[m][n], 0, 0, 0);
;           }
;         }
;       } else {
;       bf16x8 afA[4], afB[4], bfb[2][2];
; #pragma unroll
;       for (int m = 0; m < 4; ++m) afA[m] = *(const bf16x8*)(sa + m * 2048 + ((fq ^ swz) << 4));
; #pragma unroll
;       for (int n = 0; n < 2; ++n) bfb[0][n] = *(const bf16x8*)(sb + n * 2048 + ((fq ^ swz) << 4));
; #pragma unroll
;       for (int gq = 0; gq < 8; ++gq) {
;         const int ks = gq >> 2, nh = gq & 3;
;         if (gq < 7) {
;           const int ks2 = (gq + 1) >> 2, nh2 = (gq + 1) & 3;
; #pragma unroll
;           for (int n = 0; n < 2; ++n) bfb[(gq + 1) & 1][n] = *(const bf16x8*)(sb + (nh2 * 2 + n) * 2048 + (((ks2 * 4 + fq) ^ swz) << 4));
;         }
;         if (gq == 3) {
; #pragma unroll
;           for (int m = 0; m < 4; ++m) afB[m] = *(const bf16x8*)(sa + m * 2048 + (((4 + fq) ^ swz) << 4));
;         }
;         __builtin_amdgcn_sched_barrier(0);
; #pragma unroll
.LBB0_2714:
	s_add_i32 s8, s7, 0x10000
	s_and_b32 s9, s8, 0x10000
	v_add_u32_e32 v167, s9, v138
	s_nop 0
	v_readfirstlane_b32 s9, v167
	s_waitcnt vmcnt(0)
	s_barrier
	s_and_b32 s7, s7, 0x10000
	v_add_u32_e32 v130, s7, v139
	v_add_u32_e32 v167, v130, v141
	ds_read_b128 v[168:171], v167
	ds_read_b128 v[172:175], v167 offset:2048
	ds_read_b128 v[176:179], v167 offset:4096
	ds_read_b128 v[180:183], v167 offset:6144
	v_or_b32_e32 v167, s7, v140
	v_add_u32_e32 v204, v167, v141
	ds_read_b128 v[184:187], v204 offset:32768
	ds_read_b128 v[188:191], v204 offset:34816
	ds_read_b128 v[192:195], v204 offset:36864
	ds_read_b128 v[196:199], v204 offset:38912
	v_add_u32_e32 v130, v130, v142
	s_waitcnt lgkmcnt(3)
	v_mfma_f32_16x16x32_bf16 v[126:129], v[168:171], v[184:187], v[126:129]
	s_mov_b32 m0, s9
	v_mfma_f32_16x16x32_bf16 v[110:113], v[172:175], v[184:187], v[110:113]
	global_load_lds_dwordx4 v166, s[18:19]
	v_add_u32_e32 v166, 0x80, v166
	v_mfma_f32_16x16x32_bf16 v[82:85], v[176:179], v[184:187], v[82:85]
	v_mfma_f32_16x16x32_bf16 v[50:53], v[180:183], v[184:187], v[50:53]
	ds_read_b128 v[184:187], v204 offset:40960
	ds_read_b128 v[200:203], v204 offset:43008
	s_waitcnt lgkmcnt(4)
	v_mfma_f32_16x16x32_bf16 v[122:125], v[168:171], v[188:191], v[122:125]
	s_add_u32 m0, s9, 0x8000
	v_mfma_f32_16x16x32_bf16 v[106:109], v[172:175], v[188:191], v[106:109]
	global_load_lds_dwordx4 v165, s[24:25]
	v_add_u32_e32 v165, 0x80, v165
	v_mfma_f32_16x16x32_bf16 v[78:81], v[176:179], v[188:191], v[78:81]
	v_mfma_f32_16x16x32_bf16 v[42:45], v[180:183], v[188:191], v[42:45]
	s_waitcnt lgkmcnt(3)
	v_mfma_f32_16x16x32_bf16 v[118:121], v[168:171], v[192:195], v[118:121]
	s_add_u32 m0, s9, 0x2000
	v_mfma_f32_16x16x32_bf16 v[94:97], v[172:175], v[192:195], v[94:97]
	global_load_lds_dwordx4 v164, s[18:19]
	v_add_u32_e32 v164, 0x80, v164
	v_mfma_f32_16x16x32_bf16 v[58:61], v[176:179], v[192:195], v[58:61]
	v_mfma_f32_16x16x32_bf16 v[26:29], v[180:183], v[192:195], v[26:29]
	ds_read_b128 v[188:191], v204 offset:45056
	ds_read_b128 v[192:195], v204 offset:47104
	s_waitcnt lgkmcnt(4)
	v_mfma_f32_16x16x32_bf16 v[114:117], v[168:171], v[196:199], v[114:117]
	s_add_u32 m0, s9, 0xa000
	v_mfma_f32_16x16x32_bf16 v[86:89], v[172:175], v[196:199], v[86:89]
	global_load_lds_dwordx4 v163, s[24:25]
	v_add_u32_e32 v163, 0x80, v163
	v_mfma_f32_16x16x32_bf16 v[54:57], v[176:179], v[196:199], v[54:57]
	v_mfma_f32_16x16x32_bf16 v[22:25], v[180:183], v[196:199], v[22:25]
	v_add_u32_e32 v167, v167, v142
	s_waitcnt lgkmcnt(3)
	v_mfma_f32_16x16x32_bf16 v[102:105], v[168:171], v[184:187], v[102:105]
	ds_read_b128 v[196:199], v167 offset:32768
	ds_read_b128 v[204:207], v167 offset:34816
	s_add_u32 m0, s9, 0x4000
	v_mfma_f32_16x16x32_bf16 v[74:77], v[172:175], v[184:187], v[74:77]
	global_load_lds_dwordx4 v135, s[18:19]
	v_add_u32_e32 v135, 0x80, v135
	v_mfma_f32_16x16x32_bf16 v[46:49], v[176:179], v[184:187], v[46:49]
	v_mfma_f32_16x16x32_bf16 v[10:13], v[180:183], v[184:187], v[10:13]
	ds_read_b128 v[184:187], v130
	ds_read_b128 v[208:211], v130 offset:2048
	ds_read_b128 v[212:215], v130 offset:4096
	ds_read_b128 v[216:219], v130 offset:6144
	s_waitcnt lgkmcnt(8)
	v_mfma_f32_16x16x32_bf16 v[98:101], v[168:171], v[200:203], v[98:101]
	s_add_u32 m0, s9, 0xc000
	v_mfma_f32_16x16x32_bf16 v[66:69], v[172:175], v[200:203], v[66:69]
	global_load_lds_dwordx4 v134, s[24:25]
	v_add_u32_e32 v134, 0x80, v134
	v_mfma_f32_16x16x32_bf16 v[30:33], v[176:179], v[200:203], v[30:33]
	v_mfma_f32_16x16x32_bf16 v[6:9], v[180:183], v[200:203], v[6:9]
	s_waitcnt lgkmcnt(7)
	v_mfma_f32_16x16x32_bf16 v[70:73], v[168:171], v[188:191], v[70:73]
	s_add_u32 m0, s9, 0x6000
	s_waitcnt lgkmcnt(6)
	v_mfma_f32_16x16x32_bf16 v[62:65], v[168:171], v[192:195], v[62:65]
	global_load_lds_dwordx4 v133, s[18:19]
	v_add_u32_e32 v133, 0x80, v133
	v_mfma_f32_16x16x32_bf16 v[38:41], v[172:175], v[188:191], v[38:41]
	v_mfma_f32_16x16x32_bf16 v[34:37], v[172:175], v[192:195], v[34:37]
	ds_read_b128 v[168:171], v167 offset:36864
	ds_read_b128 v[172:175], v167 offset:38912
	v_mfma_f32_16x16x32_bf16 v[18:21], v[176:179], v[188:191], v[18:21]
	s_add_u32 m0, s9, 0xe000
	v_mfma_f32_16x16x32_bf16 v[14:17], v[176:179], v[192:195], v[14:17]
	global_load_lds_dwordx4 v132, s[24:25]
	v_add_u32_e32 v132, 0x80, v132
	v_mfma_f32_16x16x32_bf16 v[2:5], v[180:183], v[188:191], v[2:5]
	v_mfma_f32_16x16x32_bf16 v[90:93], v[180:183], v[192:195], v[90:93]
	ds_read_b128 v[176:179], v167 offset:40960
	ds_read_b128 v[180:183], v167 offset:43008
	s_waitcnt lgkmcnt(7)
	v_mfma_f32_16x16x32_bf16 v[126:129], v[184:187], v[196:199], v[126:129]
	v_mfma_f32_16x16x32_bf16 v[122:125], v[184:187], v[204:207], v[122:125]
	s_waitcnt lgkmcnt(6)
	v_mfma_f32_16x16x32_bf16 v[110:113], v[208:211], v[196:199], v[110:113]
	v_mfma_f32_16x16x32_bf16 v[106:109], v[208:211], v[204:207], v[106:109]
	s_waitcnt lgkmcnt(5)
	v_mfma_f32_16x16x32_bf16 v[82:85], v[212:215], v[196:199], v[82:85]
	v_mfma_f32_16x16x32_bf16 v[78:81], v[212:215], v[204:207], v[78:81]
	s_waitcnt lgkmcnt(4)
	v_mfma_f32_16x16x32_bf16 v[50:53], v[216:219], v[196:199], v[50:53]
	v_mfma_f32_16x16x32_bf16 v[42:45], v[216:219], v[204:207], v[42:45]
	s_waitcnt lgkmcnt(3)
	v_mfma_f32_16x16x32_bf16 v[118:121], v[184:187], v[168:171], v[118:121]
	v_mfma_f32_16x16x32_bf16 v[94:97], v[208:211], v[168:171], v[94:97]
	v_mfma_f32_16x16x32_bf16 v[58:61], v[212:215], v[168:171], v[58:61]
	v_mfma_f32_16x16x32_bf16 v[26:29], v[216:219], v[168:171], v[26:29]
	ds_read_b128 v[168:171], v167 offset:45056
	ds_read_b128 v[188:191], v167 offset:47104
	s_waitcnt lgkmcnt(4)
; template <bool SWAP, class Epi, bool THIN = false> ...
;     ...
;     for (int st = 0; st < ns; ++st) {
;       asm volatile("s_waitcnt vmcnt(0)" ::: "memory");
;       __builtin_amdgcn_s_barrier();
;       asm volatile("" ::: "memory");
;       if (st + 1 < ns) {
;         char* nb = smem + ((st + 1) & 1) * 65536;
;         const int ko = (st + 1) * 64;
; #pragma unroll
;         for (int i = 0; i < 4; ++i) { GLDS16(A + (size_t)(ap[i] + ko), nb + tid * 16 + i * 8192); GLDS16(Bt + (size_t)(bp[i] + ko), nb + 32768 + tid * 16 + i * 8192); }
;       }
;       const char* sa = smem + (st & 1) * 65536 + (wr * 64 + fr) * 128;
;       const char* sb = smem + (st & 1) * 65536 + 32768 + (wc * 128 + fr) * 128;
;       if constexpr (THIN) {
;         if (wc == 0) {
; #pragma unroll
;           for (int ks = 0; ks < 2; ++ks) {
;             bf16x8 af[4], bf[2];
; #pragma unroll
;             for (int m = 0; m < 4; ++m) af[m] = *(const bf16x8*)(sa + m * 2048 + (((ks * 4 + fq) ^ swz) << 4));
; #pragma unroll
;             for (int n = 0; n < 2; ++n) bf[n] = *(const bf16x8*)(sb + n * 2048 + (((ks * 4 + fq) ^ swz) << 4));
; #pragma unroll
;             for (int m = 0; m < 4; ++m)
; #pragma unroll
;               for (int n = 0; n < 2; ++n)
;                 acc[m][n] = SWAP ? __builtin_amdgcn_mfma_f32_16x16x32_bf16(bf[n], af[m], acc[m][n], 0, 0, 0)
;                                  : __builtin_amdgcn_mfma_f32_16x16x32_bf16(af[m], bf[n], acc[m][n], 0, 0, 0);
;           }
;         }
;       } else {
;       bf16x8 afA[4], afB[4], bfb[2][2];
; #pragma unroll
;       for (int m = 0; m < 4; ++m) afA[m] = *(const bf16x8*)(sa + m * 2048 + ((fq ^ swz) << 4));
; #pragma unroll
;       for (int n = 0; n < 2; ++n) bfb[0][n] = *(const bf16x8*)(sb + n * 2048 + ((fq ^ swz) << 4));
; #pragma unroll
;       for (int gq = 0; gq < 8; ++gq) {
;         const int ks = gq >> 2, nh = gq & 3;
;         if (gq < 7) {
;           const int ks2 = (gq + 1) >> 2, nh2 = (gq + 1) & 3;
; #pragma unroll
;           for (int n = 0; n < 2; ++n) bfb[(gq + 1) & 1][n] = *(const bf16x8*)(sb + (nh2 * 2 + n) * 2048 + (((ks2 * 4 + fq) ^ swz) << 4));
;         }
;         if (gq == 3) {
; #pragma unroll
;           for (int m = 0; m < 4; ++m) afB[m] = *(const bf16x8*)(sa + m * 2048 + (((4 + fq) ^ swz) << 4));
;         }
;         __builtin_amdgcn_sched_barrier(0);
; #pragma unroll
	v_mfma_f32_16x16x32_bf16 v[114:117], v[184:187], v[172:175], v[114:117]
	v_mfma_f32_16x16x32_bf16 v[86:89], v[208:211], v[172:175], v[86:89]
	v_mfma_f32_16x16x32_bf16 v[54:57], v[212:215], v[172:175], v[54:57]
	v_mfma_f32_16x16x32_bf16 v[22:25], v[216:219], v[172:175], v[22:25]
	s_waitcnt lgkmcnt(3)
	v_mfma_f32_16x16x32_bf16 v[102:105], v[184:187], v[176:179], v[102:105]
	s_waitcnt lgkmcnt(2)
	v_mfma_f32_16x16x32_bf16 v[98:101], v[184:187], v[180:183], v[98:101]
	v_mfma_f32_16x16x32_bf16 v[74:77], v[208:211], v[176:179], v[74:77]
	v_mfma_f32_16x16x32_bf16 v[66:69], v[208:211], v[180:183], v[66:69]
	v_mfma_f32_16x16x32_bf16 v[46:49], v[212:215], v[176:179], v[46:49]
	v_mfma_f32_16x16x32_bf16 v[30:33], v[212:215], v[180:183], v[30:33]
	v_mfma_f32_16x16x32_bf16 v[10:13], v[216:219], v[176:179], v[10:13]
	v_mfma_f32_16x16x32_bf16 v[6:9], v[216:219], v[180:183], v[6:9]
	s_waitcnt lgkmcnt(1)
	v_mfma_f32_16x16x32_bf16 v[70:73], v[184:187], v[168:171], v[70:73]
	s_add_i32 s6, s6, 64
	s_cmpk_eq_i32 s6, 0x3c0
	s_mov_b32 s7, s8
	s_waitcnt lgkmcnt(0)
	v_mfma_f32_16x16x32_bf16 v[62:65], v[184:187], v[188:191], v[62:65]
	v_mfma_f32_16x16x32_bf16 v[38:41], v[208:211], v[168:171], v[38:41]
	v_mfma_f32_16x16x32_bf16 v[34:37], v[208:211], v[188:191], v[34:37]
	v_mfma_f32_16x16x32_bf16 v[18:21], v[212:215], v[168:171], v[18:21]
	v_mfma_f32_16x16x32_bf16 v[14:17], v[212:215], v[188:191], v[14:17]
	v_mfma_f32_16x16x32_bf16 v[2:5], v[216:219], v[168:171], v[2:5]
	v_mfma_f32_16x16x32_bf16 v[90:93], v[216:219], v[188:191], v[90:93]
	s_cbranch_scc0 .LBB0_2714
	s_waitcnt vmcnt(0)
	s_barrier
	v_add_u32_e32 v130, v153, v141
	ds_read_b128 v[132:135], v130
	ds_read_b128 v[164:167], v130 offset:2048
	ds_read_b128 v[168:171], v130 offset:4096
	ds_read_b128 v[172:175], v130 offset:6144
	v_add_u32_e32 v130, v154, v141
	ds_read_b128 v[176:179], v130
	ds_read_b128 v[180:183], v130 offset:2048
	ds_read_b128 v[184:187], v130 offset:4096
	ds_read_b128 v[188:191], v130 offset:6144
	s_waitcnt lgkmcnt(0)
	v_mfma_f32_16x16x32_bf16 v[126:129], v[132:135], v[176:179], v[126:129]
	v_mfma_f32_16x16x32_bf16 v[110:113], v[164:167], v[176:179], v[110:113]
	v_mfma_f32_16x16x32_bf16 v[82:85], v[168:171], v[176:179], v[82:85]
	v_mfma_f32_16x16x32_bf16 v[50:53], v[172:175], v[176:179], v[50:53]
	ds_read_b128 v[176:179], v130 offset:8192
	ds_read_b128 v[192:195], v130 offset:10240
	v_mfma_f32_16x16x32_bf16 v[122:125], v[132:135], v[180:183], v[122:125]
	v_mfma_f32_16x16x32_bf16 v[106:109], v[164:167], v[180:183], v[106:109]
	v_mfma_f32_16x16x32_bf16 v[78:81], v[168:171], v[180:183], v[78:81]
	v_mfma_f32_16x16x32_bf16 v[42:45], v[172:175], v[180:183], v[42:45]
	v_mfma_f32_16x16x32_bf16 v[118:121], v[132:135], v[184:187], v[118:121]
	v_mfma_f32_16x16x32_bf16 v[180:183], v[164:167], v[184:187], v[94:97]
	v_mfma_f32_16x16x32_bf16 v[200:203], v[168:171], v[184:187], v[58:61]
	v_mfma_f32_16x16x32_bf16 v[204:207], v[168:171], v[188:191], v[54:57]
	v_mfma_f32_16x16x32_bf16 v[184:187], v[172:175], v[184:187], v[26:29]
	s_nop 2
	ds_read_b128 v[26:29], v130 offset:12288
	ds_read_b128 v[54:57], v130 offset:14336
	v_mfma_f32_16x16x32_bf16 v[114:117], v[132:135], v[188:191], v[114:117]
	v_mfma_f32_16x16x32_bf16 v[196:199], v[164:167], v[188:191], v[86:89]
	v_mfma_f32_16x16x32_bf16 v[188:191], v[172:175], v[188:191], v[22:25]
	v_add_u32_e32 v130, v154, v142
	s_waitcnt lgkmcnt(0)
	v_mfma_f32_16x16x32_bf16 v[208:211], v[168:171], v[192:195], v[30:33]
	ds_read_b128 v[22:25], v130
	ds_read_b128 v[86:89], v130 offset:2048
	s_nop 0
	v_add_u32_e32 v30, v153, v142
	v_mfma_f32_16x16x32_bf16 v[102:105], v[132:135], v[176:179], v[102:105]
	v_mfma_f32_16x16x32_bf16 v[74:77], v[164:167], v[176:179], v[74:77]
	v_mfma_f32_16x16x32_bf16 v[46:49], v[168:171], v[176:179], v[46:49]
	v_mfma_f32_16x16x32_bf16 v[10:13], v[172:175], v[176:179], v[10:13]
	ds_read_b128 v[176:179], v30
	ds_read_b128 v[212:215], v30 offset:2048
	ds_read_b128 v[216:219], v30 offset:4096
	ds_read_b128 v[220:223], v30 offset:6144
	v_mfma_f32_16x16x32_bf16 v[98:101], v[132:135], v[192:195], v[98:101]
	v_mfma_f32_16x16x32_bf16 v[66:69], v[164:167], v[192:195], v[66:69]
	v_mfma_f32_16x16x32_bf16 v[6:9], v[172:175], v[192:195], v[6:9]
	v_mfma_f32_16x16x32_bf16 v[192:195], v[164:167], v[26:29], v[38:41]
	v_mfma_f32_16x16x32_bf16 v[34:37], v[164:167], v[54:57], v[34:37]
	v_mfma_f32_16x16x32_bf16 v[164:167], v[168:171], v[26:29], v[18:21]
	v_mfma_f32_16x16x32_bf16 v[168:171], v[168:171], v[54:57], v[14:17]
	s_nop 2
	ds_read_b128 v[14:17], v130 offset:4096
	ds_read_b128 v[18:21], v130 offset:6144
	v_mfma_f32_16x16x32_bf16 v[70:73], v[132:135], v[26:29], v[70:73]
	v_mfma_f32_16x16x32_bf16 v[132:135], v[132:135], v[54:57], v[62:65]
	v_mfma_f32_16x16x32_bf16 v[2:5], v[172:175], v[26:29], v[2:5]
	v_mfma_f32_16x16x32_bf16 v[172:175], v[172:175], v[54:57], v[90:93]
	ds_read_b128 v[224:227], v130 offset:8192
	ds_read_b128 v[228:231], v130 offset:10240
	s_waitcnt lgkmcnt(0)
	v_mfma_f32_16x16x32_bf16 v[126:129], v[176:179], v[22:25], v[126:129]
	v_mfma_f32_16x16x32_bf16 v[122:125], v[176:179], v[86:89], v[122:125]
	v_mfma_f32_16x16x32_bf16 v[94:97], v[212:215], v[22:25], v[110:113]
	v_mfma_f32_16x16x32_bf16 v[90:93], v[212:215], v[86:89], v[106:109]
	v_mfma_f32_16x16x32_bf16 v[62:65], v[216:219], v[22:25], v[82:85]
	v_mfma_f32_16x16x32_bf16 v[58:61], v[216:219], v[86:89], v[78:81]
	v_mfma_f32_16x16x32_bf16 v[30:33], v[220:223], v[22:25], v[50:53]
	v_mfma_f32_16x16x32_bf16 v[26:29], v[220:223], v[86:89], v[42:45]
	v_mfma_f32_16x16x32_bf16 v[86:89], v[212:215], v[14:17], v[180:183]
	v_mfma_f32_16x16x32_bf16 v[22:25], v[220:223], v[14:17], v[184:187]
	s_nop 1
	ds_read_b128 v[180:183], v130 offset:12288
	ds_read_b128 v[184:187], v130 offset:14336
	v_mfma_f32_16x16x32_bf16 v[118:121], v[176:179], v[14:17], v[118:121]
	v_mfma_f32_16x16x32_bf16 v[114:117], v[176:179], v[18:21], v[114:117]
	v_mfma_f32_16x16x32_bf16 v[82:85], v[212:215], v[18:21], v[196:199]
	v_mfma_f32_16x16x32_bf16 v[54:57], v[216:219], v[14:17], v[200:203]
	v_mfma_f32_16x16x32_bf16 v[50:53], v[216:219], v[18:21], v[204:207]
	v_mfma_f32_16x16x32_bf16 v[18:21], v[220:223], v[18:21], v[188:191]
	v_mfma_f32_16x16x32_bf16 v[110:113], v[176:179], v[224:227], v[102:105]
	v_mfma_f32_16x16x32_bf16 v[106:109], v[176:179], v[228:231], v[98:101]
	v_mfma_f32_16x16x32_bf16 v[78:81], v[212:215], v[224:227], v[74:77]
	v_mfma_f32_16x16x32_bf16 v[74:77], v[212:215], v[228:231], v[66:69]
	v_mfma_f32_16x16x32_bf16 v[46:49], v[216:219], v[224:227], v[46:49]
	v_mfma_f32_16x16x32_bf16 v[38:41], v[216:219], v[228:231], v[208:211]
	v_mfma_f32_16x16x32_bf16 v[14:17], v[220:223], v[224:227], v[10:13]
	v_mfma_f32_16x16x32_bf16 v[6:9], v[220:223], v[228:231], v[6:9]
	v_mov_b32_e32 v130, v1
	s_waitcnt vmcnt(0) lgkmcnt(0)
	s_barrier
; __device__ __forceinline__ unsigned pack2(float a, float b) { unsigned r; asm("v_cvt_pk_bf16_f32 %0, %1, %2" : "=v"(r) : "v"(a), "v"(b)); return r; }
;   __device__ __forceinline__ void r4(int g, int rig, int col, f32x4 v) const {
;     const float b = bias[col];
;     uint2 u; u.x = pack2(v[0] + b, v[1] + b); u.y = pack2(v[2] + b, v[3] + b);
;     *(uint2*)(out + (size_t)col * 16384 + (size_t)g * 2048 + rig) = u;
;   }
; template <bool SWAP, class Epi, bool THIN = false> ...
;     ...
;     } else if constexpr (Epi::KIND == 1) {
; #pragma unroll
;       for (int m = 0; m < 4; ++m) {
;         const int rig = rig0 + rw + m * 16 + fq_e * 4;
; #pragma unroll
;         for (int n = 0; n < 8; ++n) {
;           const int col = nt * 256 + wc_e * 128 + n * 16 + fr_e;
;           if (col < N) epi.r4(g, rig, col, acc[m][n]);
;         }
;       }
	v_mfma_f32_16x16x32_bf16 v[98:101], v[176:179], v[184:187], v[132:135]
	v_ashrrev_i32_e32 v10, 8, v130
	v_add_u32_e32 v10, s5, v10
	v_ashrrev_i32_e32 v11, 31, v10
	v_lshrrev_b32_e32 v11, 28, v11
	v_add_u32_e32 v11, v10, v11
	v_ashrrev_i32_e32 v132, 4, v11
	v_lshlrev_b32_e32 v11, 11, v132
	v_lshlrev_b32_e32 v10, 7, v10
	v_sub_u32_e32 v10, v10, v11
	v_lshrrev_b32_e32 v11, 1, v130
	v_lshrrev_b32_e32 v12, 2, v130
	v_and_b32_e32 v11, 64, v11
	v_and_b32_e32 v12, 12, v12
	v_mfma_f32_16x16x32_bf16 v[42:45], v[216:219], v[180:183], v[164:167]
	v_and_b32_e32 v133, 15, v130
	s_nop 1
	v_or3_b32 v164, v10, v11, v12
	v_mfma_f32_16x16x32_bf16 v[10:13], v[220:223], v[180:183], v[2:5]
	v_ashrrev_i32_e32 v165, 31, v164
	s_nop 1
	v_lshlrev_b32_e32 v2, 1, v130
	v_and_b32_e32 v2, 0x80, v2
	v_mfma_f32_16x16x32_bf16 v[102:105], v[176:179], v[180:183], v[70:73]
	v_or3_b32 v134, v133, v2, s4
	v_ashrrev_i32_e32 v133, 31, v132
	v_lshlrev_b64 v[132:133], 12, v[132:133]
	v_mfma_f32_16x16x32_bf16 v[70:73], v[212:215], v[180:183], v[192:195]
	v_lshl_add_u64 v[132:133], s[20:21], 0, v[132:133]
	v_lshl_add_u64 v[132:133], v[164:165], 1, v[132:133]
	v_cmp_gt_i32_e32 vcc, s30, v134
	v_mfma_f32_16x16x32_bf16 v[66:69], v[212:215], v[184:187], v[34:37]
	v_ashrrev_i32_e32 v135, 31, v134
	v_mfma_f32_16x16x32_bf16 v[34:37], v[216:219], v[184:187], v[168:171]
	v_mfma_f32_16x16x32_bf16 v[2:5], v[220:223], v[184:187], v[172:175]
	s_and_saveexec_b64 s[4:5], vcc
	s_cbranch_execz .LBB0_2717
	v_lshl_add_u64 v[164:165], v[134:135], 2, s[22:23]
	global_load_dword v130, v[164:165], off
	v_lshlrev_b64 v[164:165], 15, v[134:135]
	s_waitcnt vmcnt(0)
	v_add_f32_e32 v126, v126, v130
	v_add_f32_e32 v127, v127, v130
	v_add_f32_e32 v128, v128, v130
	v_add_f32_e32 v129, v129, v130
	v_cvt_pk_bf16_f32 v126, v126, v127
	v_cvt_pk_bf16_f32 v127, v128, v129
	v_lshl_add_u64 v[128:129], v[132:133], 0, v[164:165]
	global_store_dwordx2 v[128:129], v[126:127], off

; template <bool SWAP, class Epi, bool THIN = false> ...
;     ...
;     for (int st = 0; st < ns; ++st) {
;       asm volatile("s_waitcnt vmcnt(0)" ::: "memory");
;       __builtin_amdgcn_s_barrier();
;       asm volatile("" ::: "memory");
;       if (st + 1 < ns) {
;         char* nb = smem + ((st + 1) & 1) * 65536;
;         const int ko = (st + 1) * 64;
; #pragma unroll
;         for (int i = 0; i < 4; ++i) { GLDS16(A + (size_t)(ap[i] + ko), nb + tid * 16 + i * 8192); GLDS16(Bt + (size_t)(bp[i] + ko), nb + 32768 + tid * 16 + i * 8192); }
;       }
;       const char* sa = smem + (st & 1) * 65536 + (wr * 64 + fr) * 128;
;       const char* sb = smem + (st & 1) * 65536 + 32768 + (wc * 128 + fr) * 128;
;       if constexpr (THIN) {
;         if (wc == 0) {
; #pragma unroll
;           for (int ks = 0; ks < 2; ++ks) {
;             bf16x8 af[4], bf[2];
; #pragma unroll
;             for (int m = 0; m < 4; ++m) af[m] = *(const bf16x8*)(sa + m * 2048 + (((ks * 4 + fq) ^ swz) << 4));
; #pragma unroll
;             for (int n = 0; n < 2; ++n) bf[n] = *(const bf16x8*)(sb + n * 2048 + (((ks * 4 + fq) ^ swz) << 4));
; #pragma unroll
;             for (int m = 0; m < 4; ++m)
; #pragma unroll
;               for (int n = 0; n < 2; ++n)
;                 acc[m][n] = SWAP ? __builtin_amdgcn_mfma_f32_16x16x32_bf16(bf[n], af[m], acc[m][n], 0, 0, 0)
;                                  : __builtin_amdgcn_mfma_f32_16x16x32_bf16(af[m], bf[n], acc[m][n], 0, 0, 0);
;           }
;         }
;       } else {
;       bf16x8 afA[4], afB[4], bfb[2][2];
; #pragma unroll
;       for (int m = 0; m < 4; ++m) afA[m] = *(const bf16x8*)(sa + m * 2048 + ((fq ^ swz) << 4));
; #pragma unroll
;       for (int n = 0; n < 2; ++n) bfb[0][n] = *(const bf16x8*)(sb + n * 2048 + ((fq ^ swz) << 4));
; #pragma unroll
;       for (int gq = 0; gq < 8; ++gq) {
;         const int ks = gq >> 2, nh = gq & 3;
;         if (gq < 7) {
;           const int ks2 = (gq + 1) >> 2, nh2 = (gq + 1) & 3;
; #pragma unroll
;           for (int n = 0; n < 2; ++n) bfb[(gq + 1) & 1][n] = *(const bf16x8*)(sb + (nh2 * 2 + n) * 2048 + (((ks2 * 4 + fq) ^ swz) << 4));
;         }
;         if (gq == 3) {
; #pragma unroll
;           for (int m = 0; m < 4; ++m) afB[m] = *(const bf16x8*)(sa + m * 2048 + (((4 + fq) ^ swz) << 4));
;         }
;         __builtin_amdgcn_sched_barrier(0);
; #pragma unroll
.LBB0_3112:
	s_add_i32 s9, s7, 0x10000
	s_and_b32 s8, s9, 0x10000
	v_add_u32_e32 v142, s8, v156
	s_nop 0
	v_readfirstlane_b32 s10, v142
	s_waitcnt vmcnt(0)
	s_barrier
	s_and_b32 s7, s7, 0x10000
	v_add_u32_e32 v138, s7, v157
	v_add_u32_e32 v152, v138, v159
	ds_read_b128 v[140:143], v152
	ds_read_b128 v[144:147], v152 offset:2048
	ds_read_b128 v[148:151], v152 offset:4096
	ds_read_b128 v[180:183], v152 offset:6144
	v_or_b32_e32 v152, s7, v158
	v_add_u32_e32 v153, v152, v159
	ds_read_b128 v[184:187], v153 offset:32768
	ds_read_b128 v[188:191], v153 offset:34816
	ds_read_b128 v[192:195], v153 offset:36864
	ds_read_b128 v[196:199], v153 offset:38912
	v_add_u32_e32 v138, v138, v160
	s_waitcnt lgkmcnt(3)
	v_mfma_f32_16x16x32_bf16 v[126:129], v[184:187], v[140:143], v[126:129]
	s_mov_b32 m0, s10
	v_mfma_f32_16x16x32_bf16 v[110:113], v[184:187], v[144:147], v[110:113]
	global_load_lds_dwordx4 v137, s[22:23]
	v_add_u32_e32 v137, 0x80, v137
	v_mfma_f32_16x16x32_bf16 v[82:85], v[184:187], v[148:151], v[82:85]
	v_mfma_f32_16x16x32_bf16 v[50:53], v[184:187], v[180:183], v[50:53]
	ds_read_b128 v[184:187], v153 offset:40960
	ds_read_b128 v[200:203], v153 offset:43008
	s_waitcnt lgkmcnt(4)
	v_mfma_f32_16x16x32_bf16 v[122:125], v[188:191], v[140:143], v[122:125]
	s_add_u32 m0, s10, 0x8000
	v_mfma_f32_16x16x32_bf16 v[106:109], v[188:191], v[144:147], v[106:109]
	global_load_lds_dwordx4 v136, s[28:29]
	v_add_u32_e32 v136, 0x80, v136
	v_mfma_f32_16x16x32_bf16 v[78:81], v[188:191], v[148:151], v[78:81]
	v_mfma_f32_16x16x32_bf16 v[38:41], v[188:191], v[180:183], v[38:41]
	s_waitcnt lgkmcnt(3)
	v_mfma_f32_16x16x32_bf16 v[118:121], v[192:195], v[140:143], v[118:121]
	s_add_u32 m0, s10, 0x2000
	v_mfma_f32_16x16x32_bf16 v[94:97], v[192:195], v[144:147], v[94:97]
	global_load_lds_dwordx4 v135, s[22:23]
	v_add_u32_e32 v135, 0x80, v135
	v_mfma_f32_16x16x32_bf16 v[58:61], v[192:195], v[148:151], v[58:61]
	v_mfma_f32_16x16x32_bf16 v[26:29], v[192:195], v[180:183], v[26:29]
	ds_read_b128 v[188:191], v153 offset:45056
	ds_read_b128 v[192:195], v153 offset:47104
	s_waitcnt lgkmcnt(4)
	v_mfma_f32_16x16x32_bf16 v[114:117], v[196:199], v[140:143], v[114:117]
	s_add_u32 m0, s10, 0xa000
	v_mfma_f32_16x16x32_bf16 v[86:89], v[196:199], v[144:147], v[86:89]
	global_load_lds_dwordx4 v134, s[28:29]
	v_add_u32_e32 v134, 0x80, v134
	v_mfma_f32_16x16x32_bf16 v[54:57], v[196:199], v[148:151], v[54:57]
	v_mfma_f32_16x16x32_bf16 v[22:25], v[196:199], v[180:183], v[22:25]
	v_add_u32_e32 v152, v152, v160
	s_waitcnt lgkmcnt(3)
	v_mfma_f32_16x16x32_bf16 v[102:105], v[184:187], v[140:143], v[102:105]
	ds_read_b128 v[196:199], v152 offset:32768
	ds_read_b128 v[204:207], v152 offset:34816
	s_add_u32 m0, s10, 0x4000
	v_mfma_f32_16x16x32_bf16 v[74:77], v[184:187], v[144:147], v[74:77]
	global_load_lds_dwordx4 v133, s[22:23]
	v_add_u32_e32 v133, 0x80, v133
	v_mfma_f32_16x16x32_bf16 v[46:49], v[184:187], v[148:151], v[46:49]
	v_mfma_f32_16x16x32_bf16 v[10:13], v[184:187], v[180:183], v[10:13]
	ds_read_b128 v[184:187], v138
	ds_read_b128 v[208:211], v138 offset:2048
	ds_read_b128 v[212:215], v138 offset:4096
	ds_read_b128 v[216:219], v138 offset:6144
	s_waitcnt lgkmcnt(8)
	v_mfma_f32_16x16x32_bf16 v[98:101], v[200:203], v[140:143], v[98:101]
	s_add_u32 m0, s10, 0xc000
	v_mfma_f32_16x16x32_bf16 v[66:69], v[200:203], v[144:147], v[66:69]
	global_load_lds_dwordx4 v132, s[28:29]
	v_add_u32_e32 v132, 0x80, v132
	v_mfma_f32_16x16x32_bf16 v[34:37], v[200:203], v[148:151], v[34:37]
	v_mfma_f32_16x16x32_bf16 v[6:9], v[200:203], v[180:183], v[6:9]
	s_waitcnt lgkmcnt(7)
	v_mfma_f32_16x16x32_bf16 v[70:73], v[188:191], v[140:143], v[70:73]
	s_add_u32 m0, s10, 0x6000
	s_waitcnt lgkmcnt(6)
	v_mfma_f32_16x16x32_bf16 v[62:65], v[192:195], v[140:143], v[62:65]
	global_load_lds_dwordx4 v131, s[22:23]
	v_add_u32_e32 v131, 0x80, v131
	v_mfma_f32_16x16x32_bf16 v[42:45], v[188:191], v[144:147], v[42:45]
	v_mfma_f32_16x16x32_bf16 v[30:33], v[192:195], v[144:147], v[30:33]
	ds_read_b128 v[140:143], v152 offset:36864
	ds_read_b128 v[144:147], v152 offset:38912
	v_mfma_f32_16x16x32_bf16 v[18:21], v[188:191], v[148:151], v[18:21]
	s_add_u32 m0, s10, 0xe000
	v_mfma_f32_16x16x32_bf16 v[14:17], v[192:195], v[148:151], v[14:17]
	global_load_lds_dwordx4 v130, s[28:29]
	v_add_u32_e32 v130, 0x80, v130
	v_mfma_f32_16x16x32_bf16 v[2:5], v[188:191], v[180:183], v[2:5]
	v_mfma_f32_16x16x32_bf16 v[90:93], v[192:195], v[180:183], v[90:93]
	ds_read_b128 v[148:151], v152 offset:40960
	ds_read_b128 v[180:183], v152 offset:43008
	s_waitcnt lgkmcnt(7)
	v_mfma_f32_16x16x32_bf16 v[126:129], v[196:199], v[184:187], v[126:129]
	v_mfma_f32_16x16x32_bf16 v[122:125], v[204:207], v[184:187], v[122:125]
	s_waitcnt lgkmcnt(6)
	v_mfma_f32_16x16x32_bf16 v[110:113], v[196:199], v[208:211], v[110:113]
	v_mfma_f32_16x16x32_bf16 v[106:109], v[204:207], v[208:211], v[106:109]
	s_waitcnt lgkmcnt(5)
	v_mfma_f32_16x16x32_bf16 v[82:85], v[196:199], v[212:215], v[82:85]
	v_mfma_f32_16x16x32_bf16 v[78:81], v[204:207], v[212:215], v[78:81]
	s_waitcnt lgkmcnt(4)
	v_mfma_f32_16x16x32_bf16 v[50:53], v[196:199], v[216:219], v[50:53]
	v_mfma_f32_16x16x32_bf16 v[38:41], v[204:207], v[216:219], v[38:41]
	s_waitcnt lgkmcnt(3)
	v_mfma_f32_16x16x32_bf16 v[118:121], v[140:143], v[184:187], v[118:121]
	v_mfma_f32_16x16x32_bf16 v[94:97], v[140:143], v[208:211], v[94:97]
	v_mfma_f32_16x16x32_bf16 v[58:61], v[140:143], v[212:215], v[58:61]
	v_mfma_f32_16x16x32_bf16 v[26:29], v[140:143], v[216:219], v[26:29]
	ds_read_b128 v[140:143], v152 offset:45056
	ds_read_b128 v[188:191], v152 offset:47104
	s_waitcnt lgkmcnt(4)
; template <bool SWAP, class Epi, bool THIN = false> ...
;     ...
;     for (int st = 0; st < ns; ++st) {
;       asm volatile("s_waitcnt vmcnt(0)" ::: "memory");
;       __builtin_amdgcn_s_barrier();
;       asm volatile("" ::: "memory");
;       if (st + 1 < ns) {
;         char* nb = smem + ((st + 1) & 1) * 65536;
;         const int ko = (st + 1) * 64;
; #pragma unroll
;         for (int i = 0; i < 4; ++i) { GLDS16(A + (size_t)(ap[i] + ko), nb + tid * 16 + i * 8192); GLDS16(Bt + (size_t)(bp[i] + ko), nb + 32768 + tid * 16 + i * 8192); }
;       }
;       const char* sa = smem + (st & 1) * 65536 + (wr * 64 + fr) * 128;
;       const char* sb = smem + (st & 1) * 65536 + 32768 + (wc * 128 + fr) * 128;
;       if constexpr (THIN) {
;         if (wc == 0) {
; #pragma unroll
;           for (int ks = 0; ks < 2; ++ks) {
;             bf16x8 af[4], bf[2];
; #pragma unroll
;             for (int m = 0; m < 4; ++m) af[m] = *(const bf16x8*)(sa + m * 2048 + (((ks * 4 + fq) ^ swz) << 4));
; #pragma unroll
;             for (int n = 0; n < 2; ++n) bf[n] = *(const bf16x8*)(sb + n * 2048 + (((ks * 4 + fq) ^ swz) << 4));
; #pragma unroll
;             for (int m = 0; m < 4; ++m)
; #pragma unroll
;               for (int n = 0; n < 2; ++n)
;                 acc[m][n] = SWAP ? __builtin_amdgcn_mfma_f32_16x16x32_bf16(bf[n], af[m], acc[m][n], 0, 0, 0)
;                                  : __builtin_amdgcn_mfma_f32_16x16x32_bf16(af[m], bf[n], acc[m][n], 0, 0, 0);
;           }
;         }
;       } else {
;       bf16x8 afA[4], afB[4], bfb[2][2];
; #pragma unroll
;       for (int m = 0; m < 4; ++m) afA[m] = *(const bf16x8*)(sa + m * 2048 + ((fq ^ swz) << 4));
; #pragma unroll
;       for (int n = 0; n < 2; ++n) bfb[0][n] = *(const bf16x8*)(sb + n * 2048 + ((fq ^ swz) << 4));
; #pragma unroll
;       for (int gq = 0; gq < 8; ++gq) {
;         const int ks = gq >> 2, nh = gq & 3;
;         if (gq < 7) {
;           const int ks2 = (gq + 1) >> 2, nh2 = (gq + 1) & 3;
; #pragma unroll
;           for (int n = 0; n < 2; ++n) bfb[(gq + 1) & 1][n] = *(const bf16x8*)(sb + (nh2 * 2 + n) * 2048 + (((ks2 * 4 + fq) ^ swz) << 4));
;         }
;         if (gq == 3) {
; #pragma unroll
;           for (int m = 0; m < 4; ++m) afB[m] = *(const bf16x8*)(sa + m * 2048 + (((4 + fq) ^ swz) << 4));
;         }
;         __builtin_amdgcn_sched_barrier(0);
; #pragma unroll
	v_mfma_f32_16x16x32_bf16 v[114:117], v[144:147], v[184:187], v[114:117]
	v_mfma_f32_16x16x32_bf16 v[86:89], v[144:147], v[208:211], v[86:89]
	v_mfma_f32_16x16x32_bf16 v[54:57], v[144:147], v[212:215], v[54:57]
	v_mfma_f32_16x16x32_bf16 v[22:25], v[144:147], v[216:219], v[22:25]
	s_waitcnt lgkmcnt(3)
	v_mfma_f32_16x16x32_bf16 v[102:105], v[148:151], v[184:187], v[102:105]
	s_waitcnt lgkmcnt(2)
	v_mfma_f32_16x16x32_bf16 v[98:101], v[180:183], v[184:187], v[98:101]
	v_mfma_f32_16x16x32_bf16 v[74:77], v[148:151], v[208:211], v[74:77]
	v_mfma_f32_16x16x32_bf16 v[66:69], v[180:183], v[208:211], v[66:69]
	v_mfma_f32_16x16x32_bf16 v[46:49], v[148:151], v[212:215], v[46:49]
	v_mfma_f32_16x16x32_bf16 v[34:37], v[180:183], v[212:215], v[34:37]
	v_mfma_f32_16x16x32_bf16 v[10:13], v[148:151], v[216:219], v[10:13]
	v_mfma_f32_16x16x32_bf16 v[6:9], v[180:183], v[216:219], v[6:9]
	s_waitcnt lgkmcnt(1)
	v_mfma_f32_16x16x32_bf16 v[70:73], v[140:143], v[184:187], v[70:73]
	s_add_i32 s6, s6, 64
	s_cmpk_eq_i32 s6, 0x3c0
	s_mov_b32 s7, s9
	s_waitcnt lgkmcnt(0)
	v_mfma_f32_16x16x32_bf16 v[62:65], v[188:191], v[184:187], v[62:65]
	v_mfma_f32_16x16x32_bf16 v[42:45], v[140:143], v[208:211], v[42:45]
	v_mfma_f32_16x16x32_bf16 v[30:33], v[188:191], v[208:211], v[30:33]
	v_mfma_f32_16x16x32_bf16 v[18:21], v[140:143], v[212:215], v[18:21]
	v_mfma_f32_16x16x32_bf16 v[14:17], v[188:191], v[212:215], v[14:17]
	v_mfma_f32_16x16x32_bf16 v[2:5], v[140:143], v[216:219], v[2:5]
	v_mfma_f32_16x16x32_bf16 v[90:93], v[188:191], v[216:219], v[90:93]
	s_cbranch_scc0 .LBB0_3112
	v_add_u32_e32 v138, s8, v157
	v_add_u32_e32 v152, s8, v158
	s_waitcnt vmcnt(0)
	s_barrier
	v_add_u32_e32 v144, v138, v159
	v_add_u32_e32 v153, v152, v159
	ds_read_b128 v[130:133], v144
	ds_read_b128 v[134:137], v144 offset:2048
	ds_read_b128 v[140:143], v144 offset:4096
	ds_read_b128 v[144:147], v144 offset:6144
	ds_read_b128 v[148:151], v153 offset:32768
	ds_read_b128 v[180:183], v153 offset:34816
	ds_read_b128 v[184:187], v153 offset:36864
	ds_read_b128 v[188:191], v153 offset:38912
	v_add_u32_e32 v138, v138, v160
	s_waitcnt lgkmcnt(0)
	v_mfma_f32_16x16x32_bf16 v[126:129], v[148:151], v[130:133], v[126:129]
	v_mfma_f32_16x16x32_bf16 v[110:113], v[148:151], v[134:137], v[110:113]
	v_mfma_f32_16x16x32_bf16 v[82:85], v[148:151], v[140:143], v[82:85]
	v_mfma_f32_16x16x32_bf16 v[50:53], v[148:151], v[144:147], v[50:53]
	ds_read_b128 v[148:151], v153 offset:40960
	ds_read_b128 v[192:195], v153 offset:43008
	v_mfma_f32_16x16x32_bf16 v[122:125], v[180:183], v[130:133], v[122:125]
	v_mfma_f32_16x16x32_bf16 v[106:109], v[180:183], v[134:137], v[106:109]
	v_mfma_f32_16x16x32_bf16 v[78:81], v[180:183], v[140:143], v[78:81]
	v_mfma_f32_16x16x32_bf16 v[38:41], v[180:183], v[144:147], v[38:41]
	v_mfma_f32_16x16x32_bf16 v[118:121], v[184:187], v[130:133], v[118:121]
	v_mfma_f32_16x16x32_bf16 v[180:183], v[184:187], v[134:137], v[94:97]
	v_mfma_f32_16x16x32_bf16 v[200:203], v[184:187], v[140:143], v[58:61]
	v_mfma_f32_16x16x32_bf16 v[204:207], v[188:191], v[140:143], v[54:57]
	v_mfma_f32_16x16x32_bf16 v[184:187], v[184:187], v[144:147], v[26:29]
	s_nop 2
	ds_read_b128 v[26:29], v153 offset:45056
	ds_read_b128 v[54:57], v153 offset:47104
	v_mfma_f32_16x16x32_bf16 v[114:117], v[188:191], v[130:133], v[114:117]
	v_mfma_f32_16x16x32_bf16 v[196:199], v[188:191], v[134:137], v[86:89]
	v_mfma_f32_16x16x32_bf16 v[188:191], v[188:191], v[144:147], v[22:25]
	v_add_u32_e32 v152, v152, v160
	s_waitcnt lgkmcnt(0)
	v_mfma_f32_16x16x32_bf16 v[102:105], v[148:151], v[130:133], v[102:105]
	ds_read_b128 v[22:25], v152 offset:32768
	ds_read_b128 v[86:89], v152 offset:34816
	v_mfma_f32_16x16x32_bf16 v[74:77], v[148:151], v[134:137], v[74:77]
	v_mfma_f32_16x16x32_bf16 v[46:49], v[148:151], v[140:143], v[46:49]
	v_mfma_f32_16x16x32_bf16 v[10:13], v[148:151], v[144:147], v[10:13]
	ds_read_b128 v[148:151], v138
	ds_read_b128 v[208:211], v138 offset:2048
	ds_read_b128 v[212:215], v138 offset:4096
	ds_read_b128 v[216:219], v138 offset:6144
	v_mfma_f32_16x16x32_bf16 v[98:101], v[192:195], v[130:133], v[98:101]
	v_mfma_f32_16x16x32_bf16 v[66:69], v[192:195], v[134:137], v[66:69]
	v_mfma_f32_16x16x32_bf16 v[34:37], v[192:195], v[140:143], v[34:37]
	v_mfma_f32_16x16x32_bf16 v[6:9], v[192:195], v[144:147], v[6:9]
	v_mfma_f32_16x16x32_bf16 v[220:223], v[26:29], v[140:143], v[18:21]
	v_mfma_f32_16x16x32_bf16 v[140:143], v[54:57], v[140:143], v[14:17]
	s_nop 2
	ds_read_b128 v[14:17], v152 offset:36864
	ds_read_b128 v[18:21], v152 offset:38912
	v_mfma_f32_16x16x32_bf16 v[70:73], v[26:29], v[130:133], v[70:73]
	v_mfma_f32_16x16x32_bf16 v[2:5], v[26:29], v[144:147], v[2:5]
	v_mfma_f32_16x16x32_bf16 v[130:133], v[54:57], v[130:133], v[62:65]
	v_mfma_f32_16x16x32_bf16 v[192:195], v[26:29], v[134:137], v[42:45]
	v_mfma_f32_16x16x32_bf16 v[134:137], v[54:57], v[134:137], v[30:33]
	v_mfma_f32_16x16x32_bf16 v[224:227], v[54:57], v[144:147], v[90:93]
	ds_read_b128 v[144:147], v152 offset:40960
	ds_read_b128 v[228:231], v152 offset:43008
	s_waitcnt lgkmcnt(0)
	v_mfma_f32_16x16x32_bf16 v[126:129], v[22:25], v[148:151], v[126:129]
	v_mfma_f32_16x16x32_bf16 v[122:125], v[86:89], v[148:151], v[122:125]
	v_mfma_f32_16x16x32_bf16 v[94:97], v[22:25], v[208:211], v[110:113]
	v_mfma_f32_16x16x32_bf16 v[90:93], v[86:89], v[208:211], v[106:109]
	v_mfma_f32_16x16x32_bf16 v[62:65], v[22:25], v[212:215], v[82:85]
	v_mfma_f32_16x16x32_bf16 v[58:61], v[86:89], v[212:215], v[78:81]
	v_mfma_f32_16x16x32_bf16 v[30:33], v[22:25], v[216:219], v[50:53]
	v_mfma_f32_16x16x32_bf16 v[26:29], v[86:89], v[216:219], v[38:41]
	v_mfma_f32_16x16x32_bf16 v[86:89], v[14:17], v[208:211], v[180:183]
	v_mfma_f32_16x16x32_bf16 v[22:25], v[14:17], v[216:219], v[184:187]
	s_nop 1
	ds_read_b128 v[180:183], v152 offset:45056
	ds_read_b128 v[184:187], v152 offset:47104
	v_mfma_f32_16x16x32_bf16 v[118:121], v[14:17], v[148:151], v[118:121]
	v_mfma_f32_16x16x32_bf16 v[114:117], v[18:21], v[148:151], v[114:117]
	v_mfma_f32_16x16x32_bf16 v[82:85], v[18:21], v[208:211], v[196:199]
	v_mfma_f32_16x16x32_bf16 v[54:57], v[14:17], v[212:215], v[200:203]
	v_mfma_f32_16x16x32_bf16 v[50:53], v[18:21], v[212:215], v[204:207]
	v_mfma_f32_16x16x32_bf16 v[18:21], v[18:21], v[216:219], v[188:191]
	v_mfma_f32_16x16x32_bf16 v[110:113], v[144:147], v[148:151], v[102:105]
	v_mfma_f32_16x16x32_bf16 v[106:109], v[228:231], v[148:151], v[98:101]
	v_mfma_f32_16x16x32_bf16 v[78:81], v[144:147], v[208:211], v[74:77]
	v_mfma_f32_16x16x32_bf16 v[74:77], v[228:231], v[208:211], v[66:69]
	v_mfma_f32_16x16x32_bf16 v[46:49], v[144:147], v[212:215], v[46:49]
	v_mfma_f32_16x16x32_bf16 v[42:45], v[228:231], v[212:215], v[34:37]
	v_mfma_f32_16x16x32_bf16 v[14:17], v[144:147], v[216:219], v[10:13]
	v_mfma_f32_16x16x32_bf16 v[10:13], v[228:231], v[216:219], v[6:9]
	v_mov_b32_e32 v138, v1
	s_waitcnt vmcnt(0) lgkmcnt(0)
	s_barrier
; __device__ __forceinline__ int get_tid512() { int t = threadIdx.x; asm volatile("" : "+v"(t)); return t; }
; __device__ __forceinline__ unsigned pack2(float a, float b) { unsigned r; asm("v_cvt_pk_bf16_f32 %0, %1, %2" : "=v"(r) : "v"(a), "v"(b)); return r; }
; __device__ __forceinline__ float bf2f(bf16_t h) { return __uint_as_float(((unsigned)h) << 16); }
;   __device__ __forceinline__ void c4(int g, int rig, int col, f32x4 v) const {
;     const size_t o = ((size_t)g * 2048 + rig) * 1024 + col;
;     f32x4 bs;
;     if (BASE_F32) bs = __builtin_nontemporal_load((const f32x4*)((const float*)base + o));
;     else {
;       const uint2 u = *(const uint2*)((const bf16_t*)base + o);
;       bs[0] = bf2f((bf16_t)(u.x & 0xffff)); bs[1] = bf2f((bf16_t)(u.x >> 16)); bs[2] = bf2f((bf16_t)(u.y & 0xffff)); bs[3] = bf2f((bf16_t)(u.y >> 16));
;     }
;     const f32x4 gt = *(const f32x4*)(gate + (size_t)g * 6144 + col);
;     f32x4 bi = {0.f, 0.f, 0.f, 0.f};
;     if (bias) bi = *(const f32x4*)(bias + col);
;     f32x4 r;
; #pragma unroll
;     for (int j = 0; j < 4; ++j) r[j] = bs[j] + gt[j] * (v[j] + bi[j]);
;     uint2 w; w.x = pack2(r[0], r[1]); w.y = pack2(r[2], r[3]);
;     *(uint2*)(X16 + o) = w;
; template <bool SWAP, class Epi, bool THIN = false> ...
;     ...
;     const int te = get_tid512();
;     const int fr_e = te & 15, fq_e = (te & 63) >> 4, wr_e = te >> 7, wc_e = (te >> 6) & 1;
;     const int sub = 2 * mt + (wr_e >> 1);
;     const int g = sub / tpg, ti = sub - g * tpg;
;     const int rig0 = ti * step - halo;
;     const int rw = (wr_e & 1) * 64;
;     if constexpr (Epi::KIND == 0) {
; #pragma unroll
;       for (int m = 0; m < 4; ++m) {
;         const int rig = rig0 + rw + m * 16 + fr_e;
;         if constexpr (Epi::ROWSUM) {
;           float ss = 0.f;
; #pragma unroll
;           for (int n = 0; n < 8; ++n) {
;             const int col = nt * 256 + wc_e * 128 + n * 16 + fq_e * 4;
;             if (col < N) ss += epi.c4(g, rig, col, acc[m][n]);
;           }
;           ss += __shfl_xor(ss, 16); ss += __shfl_xor(ss, 32);
;           if (fq_e == 0) epi.rowsum(g, rig, nt * 2 + wc_e, ss);
;         } else {
; #pragma unroll
;           for (int n = 0; n < 8; ++n) {
;             const int col = nt * 256 + wc_e * 128 + n * 16 + fq_e * 4;
;             if (col < N) epi.c4(g, rig, col, acc[m][n]);
	v_mfma_f32_16x16x32_bf16 v[98:101], v[184:187], v[148:151], v[130:133]
	v_ashrrev_i32_e32 v7, 8, v138
	v_add_u32_e32 v7, s5, v7
	v_ashrrev_i32_e32 v8, 31, v7
	v_lshrrev_b32_e32 v8, 28, v8
	v_add_u32_e32 v8, v7, v8
	v_ashrrev_i32_e32 v130, 4, v8
	v_lshlrev_b32_e32 v8, 11, v130
	v_lshlrev_b32_e32 v7, 7, v7
	v_sub_u32_e32 v7, v7, v8
	v_lshrrev_b32_e32 v8, 1, v138
	v_and_b32_e32 v6, 15, v138
	v_and_b32_e32 v8, 64, v8
	v_or3_b32 v144, v7, v8, v6
	v_lshlrev_b32_e32 v6, 1, v138
	v_and_b32_e32 v131, 0x80, v6
	v_mfma_f32_16x16x32_bf16 v[6:9], v[180:183], v[216:219], v[2:5]
	v_ashrrev_i32_e32 v145, 31, v144
	v_lshlrev_b64 v[132:133], 10, v[144:145]
	s_nop 0
	v_lshrrev_b32_e32 v2, 2, v138
	v_and_b32_e32 v2, 12, v2
	v_mfma_f32_16x16x32_bf16 v[102:105], v[180:183], v[148:151], v[70:73]
	v_mfma_f32_16x16x32_bf16 v[70:73], v[180:183], v[208:211], v[192:195]
	v_mfma_f32_16x16x32_bf16 v[66:69], v[184:187], v[208:211], v[134:137]
	v_mfma_f32_16x16x32_bf16 v[38:41], v[180:183], v[212:215], v[220:223]
	v_mfma_f32_16x16x32_bf16 v[34:37], v[184:187], v[212:215], v[140:143]
	s_nop 2
	v_or3_b32 v140, v2, v131, s4
	v_mfma_f32_16x16x32_bf16 v[2:5], v[184:187], v[216:219], v[224:227]
	v_ashrrev_i32_e32 v131, 31, v130
	v_lshlrev_b64 v[146:147], 21, v[130:131]
	v_mad_i64_i32 v[130:131], s[4:5], v130, s39, 0
	v_lshl_add_u64 v[132:133], v[132:133], 0, v[146:147]
	v_lshl_add_u64 v[142:143], s[30:31], 0, v[130:131]
	v_cndmask_b32_e64 v130, 0, 1, s[34:35]
	v_cmp_gt_i32_e64 s[6:7], s40, v140
	v_ashrrev_i32_e32 v141, 31, v140
	v_lshl_add_u64 v[148:149], v[132:133], 1, s[24:25]
	v_cmp_ne_u32_e64 s[4:5], 1, v130
	s_and_saveexec_b64 s[8:9], s[6:7]
	s_cbranch_execz .LBB0_3118
	v_lshl_add_u64 v[150:151], v[140:141], 1, v[148:149]
	v_lshl_add_u64 v[130:131], v[140:141], 2, v[142:143]
	global_load_dwordx2 v[152:153], v[150:151], off
	s_and_b64 vcc, exec, s[4:5]
	global_load_dwordx4 v[130:133], v[130:131], off
	s_cbranch_vccnz .LBB0_3116
	v_lshl_add_u64 v[134:135], v[140:141], 2, s[26:27]
	global_load_dwordx4 v[134:137], v[134:135], off
	s_branch .LBB0_3117

; template <bool SWAP, class Epi, bool THIN = false> ...
;     ...
;     for (int st = 0; st < ns; ++st) {
;       asm volatile("s_waitcnt vmcnt(0)" ::: "memory");
;       __builtin_amdgcn_s_barrier();
;       asm volatile("" ::: "memory");
;       if (st + 1 < ns) {
;         char* nb = smem + ((st + 1) & 1) * 65536;
;         const int ko = (st + 1) * 64;
; #pragma unroll
;         for (int i = 0; i < 4; ++i) { GLDS16(A + (size_t)(ap[i] + ko), nb + tid * 16 + i * 8192); GLDS16(Bt + (size_t)(bp[i] + ko), nb + 32768 + tid * 16 + i * 8192); }
;       }
;       const char* sa = smem + (st & 1) * 65536 + (wr * 64 + fr) * 128;
;       const char* sb = smem + (st & 1) * 65536 + 32768 + (wc * 128 + fr) * 128;
;       if constexpr (THIN) {
;         if (wc == 0) {
; #pragma unroll
;           for (int ks = 0; ks < 2; ++ks) {
;             bf16x8 af[4], bf[2];
; #pragma unroll
;             for (int m = 0; m < 4; ++m) af[m] = *(const bf16x8*)(sa + m * 2048 + (((ks * 4 + fq) ^ swz) << 4));
; #pragma unroll
;             for (int n = 0; n < 2; ++n) bf[n] = *(const bf16x8*)(sb + n * 2048 + (((ks * 4 + fq) ^ swz) << 4));
; #pragma unroll
;             for (int m = 0; m < 4; ++m)
; #pragma unroll
;               for (int n = 0; n < 2; ++n)
;                 acc[m][n] = SWAP ? __builtin_amdgcn_mfma_f32_16x16x32_bf16(bf[n], af[m], acc[m][n], 0, 0, 0)
;                                  : __builtin_amdgcn_mfma_f32_16x16x32_bf16(af[m], bf[n], acc[m][n], 0, 0, 0);
;           }
;         }
;       } else {
;       bf16x8 afA[4], afB[4], bfb[2][2];
; #pragma unroll
;       for (int m = 0; m < 4; ++m) afA[m] = *(const bf16x8*)(sa + m * 2048 + ((fq ^ swz) << 4));
; #pragma unroll
;       for (int n = 0; n < 2; ++n) bfb[0][n] = *(const bf16x8*)(sb + n * 2048 + ((fq ^ swz) << 4));
; #pragma unroll
;       for (int gq = 0; gq < 8; ++gq) {
;         const int ks = gq >> 2, nh = gq & 3;
;         if (gq < 7) {
;           const int ks2 = (gq + 1) >> 2, nh2 = (gq + 1) & 3;
; #pragma unroll
;           for (int n = 0; n < 2; ++n) bfb[(gq + 1) & 1][n] = *(const bf16x8*)(sb + (nh2 * 2 + n) * 2048 + (((ks2 * 4 + fq) ^ swz) << 4));
;         }
;         if (gq == 3) {
; #pragma unroll
;           for (int m = 0; m < 4; ++m) afB[m] = *(const bf16x8*)(sa + m * 2048 + (((4 + fq) ^ swz) << 4));
;         }
;         __builtin_amdgcn_sched_barrier(0);
; #pragma unroll
.LBB0_3424:
	s_add_i32 s8, s7, 0x10000
	s_and_b32 s9, s8, 0x10000
	v_add_u32_e32 v170, s9, v135
	s_nop 0
	v_readfirstlane_b32 s9, v170
	s_waitcnt vmcnt(0)
	s_barrier
	s_and_b32 s7, s7, 0x10000
	v_or_b32_e32 v204, s7, v139
	v_add_u32_e32 v205, v204, v140
	v_add_u32_e32 v136, s7, v138
	v_add_u32_e32 v180, v136, v140
	ds_read_b128 v[168:171], v180
	ds_read_b128 v[172:175], v180 offset:2048
	ds_read_b128 v[176:179], v180 offset:4096
	ds_read_b128 v[180:183], v180 offset:6144
	ds_read_b128 v[184:187], v205 offset:32768
	ds_read_b128 v[188:191], v205 offset:34816
	ds_read_b128 v[192:195], v205 offset:36864
	ds_read_b128 v[196:199], v205 offset:38912
	v_add_u32_e32 v136, v136, v141
	s_waitcnt lgkmcnt(3)
	v_mfma_f32_16x16x32_bf16 v[126:129], v[184:187], v[168:171], v[126:129]
	s_mov_b32 m0, s9
	v_mfma_f32_16x16x32_bf16 v[110:113], v[184:187], v[172:175], v[110:113]
	global_load_lds_dwordx4 v167, s[14:15]
	v_add_u32_e32 v167, 0x80, v167
	v_mfma_f32_16x16x32_bf16 v[82:85], v[184:187], v[176:179], v[82:85]
	v_mfma_f32_16x16x32_bf16 v[50:53], v[184:187], v[180:183], v[50:53]
	ds_read_b128 v[184:187], v205 offset:40960
	ds_read_b128 v[200:203], v205 offset:43008
	s_waitcnt lgkmcnt(4)
	v_mfma_f32_16x16x32_bf16 v[122:125], v[188:191], v[168:171], v[122:125]
	s_add_u32 m0, s9, 0x8000
	v_mfma_f32_16x16x32_bf16 v[106:109], v[188:191], v[172:175], v[106:109]
	global_load_lds_dwordx4 v166, s[10:11]
	v_add_u32_e32 v166, 0x80, v166
	v_mfma_f32_16x16x32_bf16 v[78:81], v[188:191], v[176:179], v[78:81]
	v_mfma_f32_16x16x32_bf16 v[42:45], v[188:191], v[180:183], v[42:45]
	s_waitcnt lgkmcnt(3)
	v_mfma_f32_16x16x32_bf16 v[118:121], v[192:195], v[168:171], v[118:121]
	s_add_u32 m0, s9, 0x2000
	v_mfma_f32_16x16x32_bf16 v[94:97], v[192:195], v[172:175], v[94:97]
	global_load_lds_dwordx4 v165, s[14:15]
	v_add_u32_e32 v165, 0x80, v165
	v_mfma_f32_16x16x32_bf16 v[58:61], v[192:195], v[176:179], v[58:61]
	v_mfma_f32_16x16x32_bf16 v[26:29], v[192:195], v[180:183], v[26:29]
	ds_read_b128 v[188:191], v205 offset:45056
	ds_read_b128 v[192:195], v205 offset:47104
	s_waitcnt lgkmcnt(4)
	v_mfma_f32_16x16x32_bf16 v[114:117], v[196:199], v[168:171], v[114:117]
	s_add_u32 m0, s9, 0xa000
	v_mfma_f32_16x16x32_bf16 v[90:93], v[196:199], v[172:175], v[90:93]
	global_load_lds_dwordx4 v164, s[10:11]
	v_add_u32_e32 v164, 0x80, v164
	v_mfma_f32_16x16x32_bf16 v[54:57], v[196:199], v[176:179], v[54:57]
	v_mfma_f32_16x16x32_bf16 v[22:25], v[196:199], v[180:183], v[22:25]
	v_add_u32_e32 v220, v204, v141
	s_waitcnt lgkmcnt(3)
	v_mfma_f32_16x16x32_bf16 v[102:105], v[184:187], v[168:171], v[102:105]
	ds_read_b128 v[196:199], v220 offset:32768
	ds_read_b128 v[204:207], v220 offset:34816
	s_add_u32 m0, s9, 0x4000
	v_mfma_f32_16x16x32_bf16 v[74:77], v[184:187], v[172:175], v[74:77]
	global_load_lds_dwordx4 v163, s[14:15]
	v_add_u32_e32 v163, 0x80, v163
	v_mfma_f32_16x16x32_bf16 v[46:49], v[184:187], v[176:179], v[46:49]
	v_mfma_f32_16x16x32_bf16 v[10:13], v[184:187], v[180:183], v[10:13]
	ds_read_b128 v[184:187], v136
	ds_read_b128 v[208:211], v136 offset:2048
	ds_read_b128 v[212:215], v136 offset:4096
	ds_read_b128 v[216:219], v136 offset:6144
	s_waitcnt lgkmcnt(8)
	v_mfma_f32_16x16x32_bf16 v[98:101], v[200:203], v[168:171], v[98:101]
	s_add_u32 m0, s9, 0xc000
	v_mfma_f32_16x16x32_bf16 v[66:69], v[200:203], v[172:175], v[66:69]
	global_load_lds_dwordx4 v162, s[10:11]
	v_add_u32_e32 v162, 0x80, v162
	v_mfma_f32_16x16x32_bf16 v[30:33], v[200:203], v[176:179], v[30:33]
	v_mfma_f32_16x16x32_bf16 v[6:9], v[200:203], v[180:183], v[6:9]
	s_waitcnt lgkmcnt(7)
	v_mfma_f32_16x16x32_bf16 v[70:73], v[188:191], v[168:171], v[70:73]
	s_add_u32 m0, s9, 0x6000
	s_waitcnt lgkmcnt(6)
	v_mfma_f32_16x16x32_bf16 v[62:65], v[192:195], v[168:171], v[62:65]
	global_load_lds_dwordx4 v161, s[14:15]
	v_add_u32_e32 v161, 0x80, v161
	v_mfma_f32_16x16x32_bf16 v[38:41], v[188:191], v[172:175], v[38:41]
	v_mfma_f32_16x16x32_bf16 v[34:37], v[192:195], v[172:175], v[34:37]
	ds_read_b128 v[168:171], v220 offset:36864
	ds_read_b128 v[172:175], v220 offset:38912
	v_mfma_f32_16x16x32_bf16 v[18:21], v[188:191], v[176:179], v[18:21]
	s_add_u32 m0, s9, 0xe000
	v_mfma_f32_16x16x32_bf16 v[14:17], v[192:195], v[176:179], v[14:17]
	global_load_lds_dwordx4 v160, s[10:11]
	v_add_u32_e32 v160, 0x80, v160
	v_mfma_f32_16x16x32_bf16 v[2:5], v[188:191], v[180:183], v[2:5]
	v_mfma_f32_16x16x32_bf16 v[86:89], v[192:195], v[180:183], v[86:89]
	ds_read_b128 v[176:179], v220 offset:40960
	ds_read_b128 v[180:183], v220 offset:43008
	s_waitcnt lgkmcnt(7)
	v_mfma_f32_16x16x32_bf16 v[126:129], v[196:199], v[184:187], v[126:129]
	v_mfma_f32_16x16x32_bf16 v[122:125], v[204:207], v[184:187], v[122:125]
	s_waitcnt lgkmcnt(6)
	v_mfma_f32_16x16x32_bf16 v[110:113], v[196:199], v[208:211], v[110:113]
	v_mfma_f32_16x16x32_bf16 v[106:109], v[204:207], v[208:211], v[106:109]
	s_waitcnt lgkmcnt(5)
	v_mfma_f32_16x16x32_bf16 v[82:85], v[196:199], v[212:215], v[82:85]
	v_mfma_f32_16x16x32_bf16 v[78:81], v[204:207], v[212:215], v[78:81]
	s_waitcnt lgkmcnt(4)
	v_mfma_f32_16x16x32_bf16 v[50:53], v[196:199], v[216:219], v[50:53]
	v_mfma_f32_16x16x32_bf16 v[42:45], v[204:207], v[216:219], v[42:45]
	s_waitcnt lgkmcnt(3)
	v_mfma_f32_16x16x32_bf16 v[118:121], v[168:171], v[184:187], v[118:121]
	v_mfma_f32_16x16x32_bf16 v[94:97], v[168:171], v[208:211], v[94:97]
	v_mfma_f32_16x16x32_bf16 v[58:61], v[168:171], v[212:215], v[58:61]
	v_mfma_f32_16x16x32_bf16 v[26:29], v[168:171], v[216:219], v[26:29]
	ds_read_b128 v[168:171], v220 offset:45056
	ds_read_b128 v[188:191], v220 offset:47104
	s_waitcnt lgkmcnt(4)
; template <bool SWAP, class Epi, bool THIN = false> ...
;     ...
;     for (int st = 0; st < ns; ++st) {
;       asm volatile("s_waitcnt vmcnt(0)" ::: "memory");
;       __builtin_amdgcn_s_barrier();
;       asm volatile("" ::: "memory");
;       if (st + 1 < ns) {
;         char* nb = smem + ((st + 1) & 1) * 65536;
;         const int ko = (st + 1) * 64;
; #pragma unroll
;         for (int i = 0; i < 4; ++i) { GLDS16(A + (size_t)(ap[i] + ko), nb + tid * 16 + i * 8192); GLDS16(Bt + (size_t)(bp[i] + ko), nb + 32768 + tid * 16 + i * 8192); }
;       }
;       const char* sa = smem + (st & 1) * 65536 + (wr * 64 + fr) * 128;
;       const char* sb = smem + (st & 1) * 65536 + 32768 + (wc * 128 + fr) * 128;
;       if constexpr (THIN) {
;         if (wc == 0) {
; #pragma unroll
;           for (int ks = 0; ks < 2; ++ks) {
;             bf16x8 af[4], bf[2];
; #pragma unroll
;             for (int m = 0; m < 4; ++m) af[m] = *(const bf16x8*)(sa + m * 2048 + (((ks * 4 + fq) ^ swz) << 4));
; #pragma unroll
;             for (int n = 0; n < 2; ++n) bf[n] = *(const bf16x8*)(sb + n * 2048 + (((ks * 4 + fq) ^ swz) << 4));
; #pragma unroll
;             for (int m = 0; m < 4; ++m)
; #pragma unroll
;               for (int n = 0; n < 2; ++n)
;                 acc[m][n] = SWAP ? __builtin_amdgcn_mfma_f32_16x16x32_bf16(bf[n], af[m], acc[m][n], 0, 0, 0)
;                                  : __builtin_amdgcn_mfma_f32_16x16x32_bf16(af[m], bf[n], acc[m][n], 0, 0, 0);
;           }
;         }
;       } else {
;       bf16x8 afA[4], afB[4], bfb[2][2];
; #pragma unroll
;       for (int m = 0; m < 4; ++m) afA[m] = *(const bf16x8*)(sa + m * 2048 + ((fq ^ swz) << 4));
; #pragma unroll
;       for (int n = 0; n < 2; ++n) bfb[0][n] = *(const bf16x8*)(sb + n * 2048 + ((fq ^ swz) << 4));
; #pragma unroll
;       for (int gq = 0; gq < 8; ++gq) {
;         const int ks = gq >> 2, nh = gq & 3;
;         if (gq < 7) {
;           const int ks2 = (gq + 1) >> 2, nh2 = (gq + 1) & 3;
; #pragma unroll
;           for (int n = 0; n < 2; ++n) bfb[(gq + 1) & 1][n] = *(const bf16x8*)(sb + (nh2 * 2 + n) * 2048 + (((ks2 * 4 + fq) ^ swz) << 4));
;         }
;         if (gq == 3) {
; #pragma unroll
;           for (int m = 0; m < 4; ++m) afB[m] = *(const bf16x8*)(sa + m * 2048 + (((4 + fq) ^ swz) << 4));
;         }
;         __builtin_amdgcn_sched_barrier(0);
; #pragma unroll
	v_mfma_f32_16x16x32_bf16 v[114:117], v[172:175], v[184:187], v[114:117]
	v_mfma_f32_16x16x32_bf16 v[90:93], v[172:175], v[208:211], v[90:93]
	v_mfma_f32_16x16x32_bf16 v[54:57], v[172:175], v[212:215], v[54:57]
	v_mfma_f32_16x16x32_bf16 v[22:25], v[172:175], v[216:219], v[22:25]
	s_waitcnt lgkmcnt(3)
	v_mfma_f32_16x16x32_bf16 v[102:105], v[176:179], v[184:187], v[102:105]
	s_waitcnt lgkmcnt(2)
	v_mfma_f32_16x16x32_bf16 v[98:101], v[180:183], v[184:187], v[98:101]
	v_mfma_f32_16x16x32_bf16 v[74:77], v[176:179], v[208:211], v[74:77]
	v_mfma_f32_16x16x32_bf16 v[66:69], v[180:183], v[208:211], v[66:69]
	v_mfma_f32_16x16x32_bf16 v[46:49], v[176:179], v[212:215], v[46:49]
	v_mfma_f32_16x16x32_bf16 v[30:33], v[180:183], v[212:215], v[30:33]
	v_mfma_f32_16x16x32_bf16 v[10:13], v[176:179], v[216:219], v[10:13]
	v_mfma_f32_16x16x32_bf16 v[6:9], v[180:183], v[216:219], v[6:9]
	s_waitcnt lgkmcnt(1)
	v_mfma_f32_16x16x32_bf16 v[70:73], v[168:171], v[184:187], v[70:73]
	s_add_i32 s5, s5, 64
	s_cmpk_eq_i32 s5, 0x3c0
	s_mov_b32 s7, s8
	s_waitcnt lgkmcnt(0)
	v_mfma_f32_16x16x32_bf16 v[62:65], v[188:191], v[184:187], v[62:65]
	v_mfma_f32_16x16x32_bf16 v[38:41], v[168:171], v[208:211], v[38:41]
	v_mfma_f32_16x16x32_bf16 v[34:37], v[188:191], v[208:211], v[34:37]
	v_mfma_f32_16x16x32_bf16 v[18:21], v[168:171], v[212:215], v[18:21]
	v_mfma_f32_16x16x32_bf16 v[14:17], v[188:191], v[212:215], v[14:17]
	v_mfma_f32_16x16x32_bf16 v[2:5], v[168:171], v[216:219], v[2:5]
	v_mfma_f32_16x16x32_bf16 v[86:89], v[188:191], v[216:219], v[86:89]
	s_cbranch_scc0 .LBB0_3424
	s_waitcnt vmcnt(0)
	s_barrier
	v_add_u32_e32 v136, v150, v140
	ds_read_b128 v[160:163], v136
	ds_read_b128 v[164:167], v136 offset:2048
	ds_read_b128 v[168:171], v136 offset:4096
	ds_read_b128 v[172:175], v136 offset:6144
	v_add_u32_e32 v136, v151, v140
	ds_read_b128 v[176:179], v136
	ds_read_b128 v[180:183], v136 offset:2048
	ds_read_b128 v[184:187], v136 offset:4096
	ds_read_b128 v[188:191], v136 offset:6144
	s_waitcnt lgkmcnt(0)
	v_mfma_f32_16x16x32_bf16 v[126:129], v[176:179], v[160:163], v[126:129]
	v_mfma_f32_16x16x32_bf16 v[110:113], v[176:179], v[164:167], v[110:113]
	v_mfma_f32_16x16x32_bf16 v[82:85], v[176:179], v[168:171], v[82:85]
	v_mfma_f32_16x16x32_bf16 v[50:53], v[176:179], v[172:175], v[50:53]
	ds_read_b128 v[176:179], v136 offset:8192
	ds_read_b128 v[192:195], v136 offset:10240
	v_mfma_f32_16x16x32_bf16 v[122:125], v[180:183], v[160:163], v[122:125]
	v_mfma_f32_16x16x32_bf16 v[106:109], v[180:183], v[164:167], v[106:109]
	v_mfma_f32_16x16x32_bf16 v[78:81], v[180:183], v[168:171], v[78:81]
	v_mfma_f32_16x16x32_bf16 v[42:45], v[180:183], v[172:175], v[42:45]
	v_mfma_f32_16x16x32_bf16 v[118:121], v[184:187], v[160:163], v[118:121]
	v_mfma_f32_16x16x32_bf16 v[94:97], v[184:187], v[164:167], v[94:97]
	v_mfma_f32_16x16x32_bf16 v[58:61], v[184:187], v[168:171], v[58:61]
	v_mfma_f32_16x16x32_bf16 v[26:29], v[184:187], v[172:175], v[26:29]
	ds_read_b128 v[180:183], v136 offset:12288
	ds_read_b128 v[184:187], v136 offset:14336
	v_mfma_f32_16x16x32_bf16 v[114:117], v[188:191], v[160:163], v[114:117]
	v_mfma_f32_16x16x32_bf16 v[90:93], v[188:191], v[164:167], v[90:93]
	v_mfma_f32_16x16x32_bf16 v[54:57], v[188:191], v[168:171], v[54:57]
	v_mfma_f32_16x16x32_bf16 v[22:25], v[188:191], v[172:175], v[22:25]
	v_add_u32_e32 v136, v151, v141
	v_add_u32_e32 v208, v150, v141
	s_waitcnt lgkmcnt(0)
	v_mfma_f32_16x16x32_bf16 v[102:105], v[176:179], v[160:163], v[102:105]
	v_mfma_f32_16x16x32_bf16 v[74:77], v[176:179], v[164:167], v[74:77]
	v_mfma_f32_16x16x32_bf16 v[188:191], v[192:195], v[164:167], v[66:69]
	v_mfma_f32_16x16x32_bf16 v[196:199], v[176:179], v[168:171], v[46:49]
	s_nop 2
	ds_read_b128 v[46:49], v136
	ds_read_b128 v[66:69], v136 offset:2048
	v_mfma_f32_16x16x32_bf16 v[10:13], v[176:179], v[172:175], v[10:13]
	ds_read_b128 v[176:179], v208
	ds_read_b128 v[200:203], v208 offset:2048
	ds_read_b128 v[204:207], v208 offset:4096
	ds_read_b128 v[208:211], v208 offset:6144
	v_mfma_f32_16x16x32_bf16 v[98:101], v[192:195], v[160:163], v[98:101]
	v_mfma_f32_16x16x32_bf16 v[30:33], v[192:195], v[168:171], v[30:33]
	v_mfma_f32_16x16x32_bf16 v[6:9], v[192:195], v[172:175], v[6:9]
	v_mfma_f32_16x16x32_bf16 v[192:195], v[180:183], v[164:167], v[38:41]
	v_mfma_f32_16x16x32_bf16 v[164:167], v[184:187], v[164:167], v[34:37]
	v_mfma_f32_16x16x32_bf16 v[18:21], v[180:183], v[168:171], v[18:21]
	v_mfma_f32_16x16x32_bf16 v[168:171], v[184:187], v[168:171], v[14:17]
	s_nop 2
	ds_read_b128 v[14:17], v136 offset:4096
	ds_read_b128 v[34:37], v136 offset:6144
	v_mfma_f32_16x16x32_bf16 v[70:73], v[180:183], v[160:163], v[70:73]
	v_mfma_f32_16x16x32_bf16 v[2:5], v[180:183], v[172:175], v[2:5]
	v_mfma_f32_16x16x32_bf16 v[160:163], v[184:187], v[160:163], v[62:65]
	v_mfma_f32_16x16x32_bf16 v[86:89], v[184:187], v[172:175], v[86:89]
	s_waitcnt lgkmcnt(0)
	v_mfma_f32_16x16x32_bf16 v[172:175], v[46:49], v[208:211], v[50:53]
	s_nop 2
	ds_read_b128 v[50:53], v136 offset:8192
	ds_read_b128 v[180:183], v136 offset:10240
	v_mfma_f32_16x16x32_bf16 v[126:129], v[46:49], v[176:179], v[126:129]
	v_mfma_f32_16x16x32_bf16 v[122:125], v[66:69], v[176:179], v[122:125]
	v_mfma_f32_16x16x32_bf16 v[110:113], v[46:49], v[200:203], v[110:113]
	v_mfma_f32_16x16x32_bf16 v[106:109], v[66:69], v[200:203], v[106:109]
	v_mfma_f32_16x16x32_bf16 v[82:85], v[46:49], v[204:207], v[82:85]
	v_mfma_f32_16x16x32_bf16 v[78:81], v[66:69], v[204:207], v[78:81]
	v_mfma_f32_16x16x32_bf16 v[184:187], v[66:69], v[208:211], v[42:45]
	ds_read_b128 v[224:227], v136 offset:12288
	ds_read_b128 v[228:231], v136 offset:14336
	v_mfma_f32_16x16x32_bf16 v[118:121], v[14:17], v[176:179], v[118:121]
	v_mfma_f32_16x16x32_bf16 v[114:117], v[34:37], v[176:179], v[114:117]
	v_mfma_f32_16x16x32_bf16 v[94:97], v[14:17], v[200:203], v[94:97]
	v_mfma_f32_16x16x32_bf16 v[90:93], v[34:37], v[200:203], v[90:93]
	v_mfma_f32_16x16x32_bf16 v[212:215], v[14:17], v[204:207], v[58:61]
	v_mfma_f32_16x16x32_bf16 v[216:219], v[34:37], v[204:207], v[54:57]
	v_mfma_f32_16x16x32_bf16 v[220:223], v[14:17], v[208:211], v[26:29]
	v_mfma_f32_16x16x32_bf16 v[66:69], v[34:37], v[208:211], v[22:25]
	s_waitcnt lgkmcnt(0)
	v_mfma_f32_16x16x32_bf16 v[38:41], v[180:183], v[204:207], v[30:33]
	v_mfma_f32_16x16x32_bf16 v[62:65], v[50:53], v[176:179], v[102:105]
	v_mfma_f32_16x16x32_bf16 v[46:49], v[180:183], v[176:179], v[98:101]
	v_mfma_f32_16x16x32_bf16 v[58:61], v[50:53], v[200:203], v[74:77]
	v_mfma_f32_16x16x32_bf16 v[42:45], v[180:183], v[200:203], v[188:191]
	v_mfma_f32_16x16x32_bf16 v[54:57], v[50:53], v[204:207], v[196:199]
	v_mfma_f32_16x16x32_bf16 v[50:53], v[50:53], v[208:211], v[10:13]
	v_mfma_f32_16x16x32_bf16 v[34:37], v[180:183], v[208:211], v[6:9]
	s_nop 2
	v_mov_b32_e32 v8, v1
	s_waitcnt vmcnt(0)
	s_barrier
; __device__ __forceinline__ int get_tid512() { int t = threadIdx.x; asm volatile("" : "+v"(t)); return t; }
; __device__ __forceinline__ unsigned pack2(float a, float b) { unsigned r; asm("v_cvt_pk_bf16_f32 %0, %1, %2" : "=v"(r) : "v"(a), "v"(b)); return r; }
; template <bool SWAP, class Epi, bool THIN = false> ...
;     ...
;     const int te = get_tid512();
;     const int fr_e = te & 15, fq_e = (te & 63) >> 4, wr_e = te >> 7, wc_e = (te >> 6) & 1;
;     const int sub = 2 * mt + (wr_e >> 1);
;     const int g = sub / tpg, ti = sub - g * tpg;
;     const int rig0 = ti * step - halo;
;     const int rw = (wr_e & 1) * 64;
;     ...
;     } else {
;       bf16_t* Zw = (bf16_t*)smem + ((wr_e >> 1) * 2 + wc_e) * (128 * 132);
;       const int nt2w = nt * 2 + wc_e;
; #pragma unroll
;       for (int n = 0; n < 8; ++n) {
;         const int cl = n * 16 + fq_e * 4;
;         f32x4 b4 = {0.f, 0.f, 0.f, 0.f};
;         if (epi.pre_bias) b4 = *(const f32x4*)(epi.pre_bias + epi.norig(nt2w, cl));
; #pragma unroll
;         for (int m = 0; m < 4; ++m) {
;           const int rl = rw + m * 16 + fr_e;
;           const int pos = rig0 + rl;
;           const bool ok = pos >= 0 && pos < grows;
;           f32x4 vv = acc[m][n] + b4;
;           if (!ok) vv = (f32x4){0.f, 0.f, 0.f, 0.f};
;           uint2 u; u.x = pack2(vv[0], vv[1]); u.y = pack2(vv[2], vv[3]);
;           *(uint2*)(Zw + rl * 132 + cl) = u;
;         }
;       }
	v_mfma_f32_16x16x32_bf16 v[30:33], v[224:227], v[176:179], v[70:73]
	v_ashrrev_i32_e32 v98, 8, v8
	v_add_u32_e32 v6, s4, v98
	v_mul_hi_i32 v7, v6, s26
	v_lshrrev_b32_e32 v9, 31, v7
	v_ashrrev_i32_e32 v7, 3, v7
	v_add_u32_e32 v70, v7, v9
	v_and_b32_e32 v71, 15, v8
	v_mad_u64_u32 v[6:7], s[4:5], v70, s27, v[6:7]
	v_lshrrev_b32_e32 v74, 1, v8
	v_bfe_u32 v73, v8, 6, 1
	v_mul_lo_u32 v72, v6, s28
	v_and_or_b32 v71, v74, 64, v71
	v_add_u32_e32 v99, v72, v71
	v_lshl_or_b32 v73, v98, 1, v73
	v_mul_lo_u32 v73, v73, s29
	v_add_u32_e32 v100, -1, v99
	v_and_or_b32 v73, v74, 24, v73
	v_pk_add_f32 v[74:75], v[128:129], 0 op_sel_hi:[1,0]
	v_pk_add_f32 v[76:77], v[126:127], 0 op_sel_hi:[1,0]
	v_cmp_gt_u32_e32 vcc, s30, v100
	v_mfma_f32_16x16x32_bf16 v[22:25], v[224:227], v[204:207], v[18:21]
	v_mad_u32_u24 v71, v71, s31, v73
	v_add_u32_e32 v73, 15, v99
	v_cmp_gt_u32_e64 s[4:5], s30, v73
	v_mfma_f32_16x16x32_bf16 v[18:21], v[224:227], v[208:211], v[2:5]
	s_lshl_b32 s24, s6, 7
	v_cndmask_b32_e32 v75, 0, v75, vcc
	v_pk_add_f32 v[84:85], v[84:85], 0 op_sel_hi:[1,0]
	v_mfma_f32_16x16x32_bf16 v[2:5], v[228:231], v[208:211], v[86:89]
	v_add_f32_e64 v82, v82, 0
	v_add_f32_e64 v83, v83, 0
	v_pk_add_f32 v[66:67], v[66:67], 0 op_sel_hi:[1,0]
	v_pk_add_f32 v[62:63], v[62:63], 0 op_sel_hi:[1,0]
	v_cndmask_b32_e32 v86, 0, v74, vcc
	v_cndmask_b32_e32 v74, 0, v76, vcc
	v_cndmask_b32_e32 v76, 0, v77, vcc
	v_cvt_pk_bf16_f32 v74, v74, v76
	v_pk_add_f32 v[76:77], v[112:113], 0 op_sel_hi:[1,0]
	v_cvt_pk_bf16_f32 v75, v86, v75
	v_pk_add_f32 v[86:87], v[110:111], 0 op_sel_hi:[1,0]
	v_cndmask_b32_e64 v73, 0, v76, s[4:5]
	v_cndmask_b32_e64 v77, 0, v77, s[4:5]
	v_cvt_pk_bf16_f32 v77, v73, v77
	v_add_u32_e32 v73, 31, v99
	v_cmp_gt_u32_e64 s[6:7], s30, v73
	v_cndmask_b32_e64 v76, 0, v86, s[4:5]
	v_cndmask_b32_e64 v86, 0, v87, s[4:5]
	v_cndmask_b32_e64 v73, 0, v84, s[6:7]
	v_cndmask_b32_e64 v82, 0, v82, s[6:7]
	v_cndmask_b32_e64 v83, 0, v83, s[6:7]
	v_cndmask_b32_e64 v84, 0, v85, s[6:7]
	v_cvt_pk_bf16_f32 v82, v82, v83
	v_cvt_pk_bf16_f32 v83, v73, v84
	v_add_u32_e32 v73, 47, v99
	v_cvt_pk_bf16_f32 v76, v76, v86
	v_pk_add_f32 v[84:85], v[174:175], 0 op_sel_hi:[1,0]
	v_pk_add_f32 v[86:87], v[172:173], 0 op_sel_hi:[1,0]
	v_cmp_gt_u32_e64 s[8:9], s30, v73
	v_pk_add_f32 v[88:89], v[122:123], 0 op_sel_hi:[1,0]
	v_mfma_f32_16x16x32_bf16 v[26:29], v[224:227], v[200:203], v[192:195]
	v_cndmask_b32_e64 v73, 0, v84, s[8:9]
	v_cndmask_b32_e64 v84, 0, v86, s[8:9]
	v_cndmask_b32_e64 v86, 0, v87, s[8:9]
	v_cndmask_b32_e64 v85, 0, v85, s[8:9]
	v_cvt_pk_bf16_f32 v84, v84, v86
	v_pk_add_f32 v[86:87], v[124:125], 0 op_sel_hi:[1,0]
	v_cvt_pk_bf16_f32 v85, v73, v85
	v_mfma_f32_16x16x32_bf16 v[14:17], v[228:231], v[176:179], v[160:163]
	v_cndmask_b32_e32 v73, 0, v86, vcc
	v_cndmask_b32_e32 v87, 0, v87, vcc
	v_cndmask_b32_e32 v86, 0, v88, vcc
	v_cndmask_b32_e32 v88, 0, v89, vcc
	v_cvt_pk_bf16_f32 v86, v86, v88
	v_cvt_pk_bf16_f32 v87, v73, v87
	ds_write2_b64 v71, v[74:75], v[86:87] offset1:4
	v_pk_add_f32 v[74:75], v[108:109], 0 op_sel_hi:[1,0]
	v_pk_add_f32 v[86:87], v[106:107], 0 op_sel_hi:[1,0]
	v_cndmask_b32_e64 v73, 0, v74, s[4:5]
	v_cndmask_b32_e64 v75, 0, v75, s[4:5]
	v_cndmask_b32_e64 v74, 0, v86, s[4:5]
	v_cndmask_b32_e64 v86, 0, v87, s[4:5]
	v_cvt_pk_bf16_f32 v74, v74, v86
	v_cvt_pk_bf16_f32 v75, v73, v75
	v_add_u32_e32 v73, 0x1000, v71
	ds_write2_b64 v73, v[76:77], v[74:75] offset0:16 offset1:20
	v_pk_add_f32 v[74:75], v[80:81], 0 op_sel_hi:[1,0]
	v_pk_add_f32 v[76:77], v[78:79], 0 op_sel_hi:[1,0]
	v_cndmask_b32_e64 v78, 0, v74, s[6:7]
	v_cndmask_b32_e64 v75, 0, v75, s[6:7]
	v_cndmask_b32_e64 v74, 0, v76, s[6:7]
	v_cndmask_b32_e64 v76, 0, v77, s[6:7]
	v_cvt_pk_bf16_f32 v74, v74, v76
	v_cvt_pk_bf16_f32 v75, v78, v75
	v_add_u32_e32 v86, 0x2000, v71
	ds_write2_b64 v86, v[82:83], v[74:75] offset0:32 offset1:36
	v_pk_add_f32 v[74:75], v[186:187], 0 op_sel_hi:[1,0]
	v_pk_add_f32 v[76:77], v[184:185], 0 op_sel_hi:[1,0]
	v_cndmask_b32_e64 v78, 0, v74, s[8:9]
	v_cndmask_b32_e64 v75, 0, v75, s[8:9]
	v_cndmask_b32_e64 v74, 0, v76, s[8:9]
	v_cndmask_b32_e64 v76, 0, v77, s[8:9]
	v_cvt_pk_bf16_f32 v74, v74, v76
	v_cvt_pk_bf16_f32 v75, v78, v75
	v_add_u32_e32 v87, 0x3000, v71
	ds_write2_b64 v87, v[84:85], v[74:75] offset0:48 offset1:52
	v_pk_add_f32 v[74:75], v[120:121], 0 op_sel_hi:[1,0]
	v_pk_add_f32 v[76:77], v[118:119], 0 op_sel_hi:[1,0]
	v_cndmask_b32_e32 v78, 0, v74, vcc
	v_cndmask_b32_e32 v75, 0, v75, vcc
	v_cndmask_b32_e32 v74, 0, v76, vcc
	v_cndmask_b32_e32 v76, 0, v77, vcc
	v_cvt_pk_bf16_f32 v74, v74, v76
	v_cvt_pk_bf16_f32 v75, v78, v75
	v_pk_add_f32 v[76:77], v[96:97], 0 op_sel_hi:[1,0]
	v_pk_add_f32 v[78:79], v[94:95], 0 op_sel_hi:[1,0]
	v_cndmask_b32_e64 v80, 0, v76, s[4:5]
	v_cndmask_b32_e64 v77, 0, v77, s[4:5]
	v_cndmask_b32_e64 v76, 0, v78, s[4:5]
	v_cndmask_b32_e64 v78, 0, v79, s[4:5]
	v_cvt_pk_bf16_f32 v76, v76, v78
	v_cvt_pk_bf16_f32 v77, v80, v77
	v_pk_add_f32 v[78:79], v[214:215], 0 op_sel_hi:[1,0]
	v_pk_add_f32 v[80:81], v[212:213], 0 op_sel_hi:[1,0]
	v_cndmask_b32_e64 v82, 0, v78, s[6:7]
	v_cndmask_b32_e64 v79, 0, v79, s[6:7]
	v_cndmask_b32_e64 v78, 0, v80, s[6:7]
	v_cndmask_b32_e64 v80, 0, v81, s[6:7]
	v_cvt_pk_bf16_f32 v78, v78, v80
	v_cvt_pk_bf16_f32 v79, v82, v79
	v_pk_add_f32 v[80:81], v[222:223], 0 op_sel_hi:[1,0]
	v_pk_add_f32 v[82:83], v[220:221], 0 op_sel_hi:[1,0]
	v_cndmask_b32_e64 v84, 0, v80, s[8:9]
	v_cndmask_b32_e64 v81, 0, v81, s[8:9]
	v_cndmask_b32_e64 v80, 0, v82, s[8:9]
	v_cndmask_b32_e64 v82, 0, v83, s[8:9]
	v_cvt_pk_bf16_f32 v80, v80, v82
	v_cvt_pk_bf16_f32 v81, v84, v81
	v_pk_add_f32 v[82:83], v[116:117], 0 op_sel_hi:[1,0]
	v_pk_add_f32 v[84:85], v[114:115], 0 op_sel_hi:[1,0]
; __device__ __forceinline__ unsigned pack2(float a, float b) { unsigned r; asm("v_cvt_pk_bf16_f32 %0, %1, %2" : "=v"(r) : "v"(a), "v"(b)); return r; }
; template <bool SWAP, class Epi, bool THIN = false> ...
;     ...
;     } else {
;       bf16_t* Zw = (bf16_t*)smem + ((wr_e >> 1) * 2 + wc_e) * (128 * 132);
;       const int nt2w = nt * 2 + wc_e;
; #pragma unroll
;       for (int n = 0; n < 8; ++n) {
;         const int cl = n * 16 + fq_e * 4;
;         f32x4 b4 = {0.f, 0.f, 0.f, 0.f};
;         if (epi.pre_bias) b4 = *(const f32x4*)(epi.pre_bias + epi.norig(nt2w, cl));
; #pragma unroll
;         for (int m = 0; m < 4; ++m) {
;           const int rl = rw + m * 16 + fr_e;
;           const int pos = rig0 + rl;
;           const bool ok = pos >= 0 && pos < grows;
;           f32x4 vv = acc[m][n] + b4;
;           if (!ok) vv = (f32x4){0.f, 0.f, 0.f, 0.f};
;           uint2 u; u.x = pack2(vv[0], vv[1]); u.y = pack2(vv[2], vv[3]);
;           *(uint2*)(Zw + rl * 132 + cl) = u;
;         }
;       }
	v_cndmask_b32_e32 v88, 0, v82, vcc
	v_cndmask_b32_e32 v83, 0, v83, vcc
	v_cndmask_b32_e32 v82, 0, v84, vcc
	v_mfma_f32_16x16x32_bf16 v[10:13], v[228:231], v[200:203], v[164:167]
	v_cndmask_b32_e32 v84, 0, v85, vcc
	v_cvt_pk_bf16_f32 v82, v82, v84
	v_cvt_pk_bf16_f32 v83, v88, v83
	v_mfma_f32_16x16x32_bf16 v[6:9], v[228:231], v[204:207], v[168:171]
	ds_write2_b64 v71, v[74:75], v[82:83] offset0:8 offset1:12
	v_pk_add_f32 v[74:75], v[92:93], 0 op_sel_hi:[1,0]
	v_pk_add_f32 v[82:83], v[90:91], 0 op_sel_hi:[1,0]
	v_cndmask_b32_e64 v84, 0, v74, s[4:5]
	v_cndmask_b32_e64 v75, 0, v75, s[4:5]
	v_cndmask_b32_e64 v74, 0, v82, s[4:5]
	v_cndmask_b32_e64 v82, 0, v83, s[4:5]
	v_cvt_pk_bf16_f32 v74, v74, v82
	v_cvt_pk_bf16_f32 v75, v84, v75
	v_pk_add_f32 v[28:29], v[28:29], 0 op_sel_hi:[1,0]
	v_pk_add_f32 v[26:27], v[26:27], 0 op_sel_hi:[1,0]
	ds_write2_b64 v73, v[76:77], v[74:75] offset0:24 offset1:28
	v_pk_add_f32 v[74:75], v[218:219], 0 op_sel_hi:[1,0]
	v_pk_add_f32 v[76:77], v[216:217], 0 op_sel_hi:[1,0]
	v_pk_add_f32 v[58:59], v[58:59], 0 op_sel_hi:[1,0]
	v_pk_add_f32 v[54:55], v[54:55], 0 op_sel_hi:[1,0]
	v_pk_add_f32 v[50:51], v[50:51], 0 op_sel_hi:[1,0]
	v_pk_add_f32 v[46:47], v[46:47], 0 op_sel_hi:[1,0]
	v_pk_add_f32 v[42:43], v[42:43], 0 op_sel_hi:[1,0]
	v_pk_add_f32 v[38:39], v[38:39], 0 op_sel_hi:[1,0]
	v_pk_add_f32 v[34:35], v[34:35], 0 op_sel_hi:[1,0]
	v_pk_add_f32 v[30:31], v[30:31], 0 op_sel_hi:[1,0]
	v_cndmask_b32_e64 v28, 0, v28, s[4:5]
	v_cndmask_b32_e64 v26, 0, v26, s[4:5]
	v_cndmask_b32_e64 v27, 0, v27, s[4:5]
	v_pk_add_f32 v[22:23], v[22:23], 0 op_sel_hi:[1,0]
	v_pk_add_f32 v[18:19], v[18:19], 0 op_sel_hi:[1,0]
	v_pk_add_f32 v[14:15], v[14:15], 0 op_sel_hi:[1,0]
	v_pk_add_f32 v[10:11], v[10:11], 0 op_sel_hi:[1,0]
	v_pk_add_f32 v[6:7], v[6:7], 0 op_sel_hi:[1,0]
	v_pk_add_f32 v[2:3], v[2:3], 0 op_sel_hi:[1,0]
	v_cndmask_b32_e64 v82, 0, v74, s[6:7]
	v_cndmask_b32_e64 v75, 0, v75, s[6:7]
	v_cndmask_b32_e64 v74, 0, v76, s[6:7]
	v_pk_add_f32 v[68:69], v[68:69], 0 op_sel_hi:[1,0]
	v_cndmask_b32_e64 v66, 0, v66, s[8:9]
	v_cndmask_b32_e64 v67, 0, v67, s[8:9]
	v_pk_add_f32 v[64:65], v[64:65], 0 op_sel_hi:[1,0]
	v_cndmask_b32_e32 v62, 0, v62, vcc
	v_cndmask_b32_e32 v63, 0, v63, vcc
	v_pk_add_f32 v[60:61], v[60:61], 0 op_sel_hi:[1,0]
	v_cndmask_b32_e64 v58, 0, v58, s[4:5]
	v_cndmask_b32_e64 v59, 0, v59, s[4:5]
	v_pk_add_f32 v[56:57], v[56:57], 0 op_sel_hi:[1,0]
	v_cndmask_b32_e64 v54, 0, v54, s[6:7]
	v_cndmask_b32_e64 v55, 0, v55, s[6:7]
	v_pk_add_f32 v[52:53], v[52:53], 0 op_sel_hi:[1,0]
	v_cndmask_b32_e64 v50, 0, v50, s[8:9]
	v_cndmask_b32_e64 v51, 0, v51, s[8:9]
	v_pk_add_f32 v[48:49], v[48:49], 0 op_sel_hi:[1,0]
	v_cndmask_b32_e32 v46, 0, v46, vcc
	v_cndmask_b32_e32 v47, 0, v47, vcc
	v_pk_add_f32 v[44:45], v[44:45], 0 op_sel_hi:[1,0]
	v_cndmask_b32_e64 v42, 0, v42, s[4:5]
	v_cndmask_b32_e64 v43, 0, v43, s[4:5]
	v_pk_add_f32 v[40:41], v[40:41], 0 op_sel_hi:[1,0]
	v_cndmask_b32_e64 v38, 0, v38, s[6:7]
	v_cndmask_b32_e64 v39, 0, v39, s[6:7]
	v_pk_add_f32 v[36:37], v[36:37], 0 op_sel_hi:[1,0]
	v_cndmask_b32_e64 v34, 0, v34, s[8:9]
	v_cndmask_b32_e64 v35, 0, v35, s[8:9]
	v_pk_add_f32 v[32:33], v[32:33], 0 op_sel_hi:[1,0]
	v_cndmask_b32_e32 v30, 0, v30, vcc
	v_cndmask_b32_e32 v31, 0, v31, vcc
	v_cndmask_b32_e64 v29, 0, v29, s[4:5]
	v_cvt_pk_bf16_f32 v26, v26, v27
	v_cvt_pk_bf16_f32 v27, v28, v29
	v_pk_add_f32 v[24:25], v[24:25], 0 op_sel_hi:[1,0]
	v_cndmask_b32_e64 v22, 0, v22, s[6:7]
	v_cndmask_b32_e64 v23, 0, v23, s[6:7]
	v_pk_add_f32 v[20:21], v[20:21], 0 op_sel_hi:[1,0]
	v_cndmask_b32_e64 v18, 0, v18, s[8:9]
	v_cndmask_b32_e64 v19, 0, v19, s[8:9]
	v_pk_add_f32 v[16:17], v[16:17], 0 op_sel_hi:[1,0]
	v_cndmask_b32_e32 v14, 0, v14, vcc
	v_cndmask_b32_e32 v15, 0, v15, vcc
	v_pk_add_f32 v[12:13], v[12:13], 0 op_sel_hi:[1,0]
	v_cndmask_b32_e64 v10, 0, v10, s[4:5]
	v_cndmask_b32_e64 v11, 0, v11, s[4:5]
	v_pk_add_f32 v[8:9], v[8:9], 0 op_sel_hi:[1,0]
	v_cndmask_b32_e64 v6, 0, v6, s[6:7]
	v_cndmask_b32_e64 v7, 0, v7, s[6:7]
	v_pk_add_f32 v[4:5], v[4:5], 0 op_sel_hi:[1,0]
	v_cndmask_b32_e64 v2, 0, v2, s[8:9]
	v_cndmask_b32_e64 v3, 0, v3, s[8:9]
	v_mov_b32_e32 v28, v142
	v_cndmask_b32_e64 v76, 0, v77, s[6:7]
	v_cvt_pk_bf16_f32 v74, v74, v76
	v_cvt_pk_bf16_f32 v75, v82, v75
	ds_write2_b64 v86, v[78:79], v[74:75] offset0:40 offset1:44
	v_cndmask_b32_e64 v68, 0, v68, s[8:9]
	v_cndmask_b32_e64 v69, 0, v69, s[8:9]
	v_cvt_pk_bf16_f32 v66, v66, v67
	v_cvt_pk_bf16_f32 v67, v68, v69
	ds_write2_b64 v87, v[80:81], v[66:67] offset0:56 offset1:60
	v_cndmask_b32_e32 v64, 0, v64, vcc
	v_cndmask_b32_e32 v65, 0, v65, vcc
	v_cvt_pk_bf16_f32 v62, v62, v63
	v_cvt_pk_bf16_f32 v63, v64, v65
	v_cndmask_b32_e64 v60, 0, v60, s[4:5]
	v_cndmask_b32_e64 v61, 0, v61, s[4:5]
; __device__ __forceinline__ int get_tid() { int t = threadIdx.x & 255; asm volatile("" : "+v"(t)); return t; }
; __device__ __forceinline__ unsigned pack2(float a, float b) { unsigned r; asm("v_cvt_pk_bf16_f32 %0, %1, %2" : "=v"(r) : "v"(a), "v"(b)); return r; }
;   template <class F>
;   __device__ __forceinline__ void finish(const bf16_t* Z, int g, int rig0, int nt, F&& pre) const {
;     typedef f32x2_t f32x2;
;     const int tid = get_tid();
;     if (MODE == 0 || nt < 8) {
;       if (MODE == 0) {
;         const int f2 = (tid & 31) * 2, q8 = tid >> 5;
;         const int q0 = 1 + 16 * q8, q1 = (q0 + 16 < 127) ? q0 + 16 : 127;
;         const int na = norig(nt, f2), ng = norig(nt, 64 + f2);
;         const f32x2 a0 = *(const f32x2*)(cw + na), a1 = *(const f32x2*)(cw + NC + na), a2 = *(const f32x2*)(cw + 2 * NC + na), ab = *(const f32x2*)(cb + na);
;         const f32x2 g0 = *(const f32x2*)(cw + ng), g1 = *(const f32x2*)(cw + NC + ng), g2 = *(const f32x2*)(cw + 2 * NC + ng), gb = *(const f32x2*)(cb + ng);
;         pre();
;         f32x2 am = ldz(Z, q0 - 1, f2), ac = ldz(Z, q0, f2);
;         f32x2 gm = ldz(Z, q0 - 1, 64 + f2), gc = ldz(Z, q0, 64 + f2);
; template <bool SWAP, class Epi, bool THIN = false> ...
;     ...
;     } else {
;       bf16_t* Zw = (bf16_t*)smem + ((wr_e >> 1) * 2 + wc_e) * (128 * 132);
;       const int nt2w = nt * 2 + wc_e;
; #pragma unroll
;       for (int n = 0; n < 8; ++n) {
;         const int cl = n * 16 + fq_e * 4;
;         f32x4 b4 = {0.f, 0.f, 0.f, 0.f};
;         if (epi.pre_bias) b4 = *(const f32x4*)(epi.pre_bias + epi.norig(nt2w, cl));
; #pragma unroll
;         for (int m = 0; m < 4; ++m) {
;           const int rl = rw + m * 16 + fr_e;
;           const int pos = rig0 + rl;
;           const bool ok = pos >= 0 && pos < grows;
;           f32x4 vv = acc[m][n] + b4;
;           if (!ok) vv = (f32x4){0.f, 0.f, 0.f, 0.f};
;           uint2 u; u.x = pack2(vv[0], vv[1]); u.y = pack2(vv[2], vv[3]);
;           *(uint2*)(Zw + rl * 132 + cl) = u;
;         }
;       }
;       __syncthreads();
;       {
;         auto no_pre = []() {};
;         const bf16_t* Zr = (const bf16_t*)smem + ((wr_e >> 1) * 2) * (128 * 132);
;         epi.finish(Zr, g, rig0, nt * 2, no_pre);
	v_cvt_pk_bf16_f32 v58, v58, v59
	v_cvt_pk_bf16_f32 v59, v60, v61
	v_cndmask_b32_e64 v56, 0, v56, s[6:7]
	v_cndmask_b32_e64 v57, 0, v57, s[6:7]
	v_cvt_pk_bf16_f32 v54, v54, v55
	v_cvt_pk_bf16_f32 v55, v56, v57
	v_cndmask_b32_e64 v52, 0, v52, s[8:9]
	v_cndmask_b32_e64 v53, 0, v53, s[8:9]
	v_cvt_pk_bf16_f32 v50, v50, v51
	v_cvt_pk_bf16_f32 v51, v52, v53
	v_cndmask_b32_e32 v48, 0, v48, vcc
	v_cndmask_b32_e32 v49, 0, v49, vcc
	v_cvt_pk_bf16_f32 v46, v46, v47
	v_cvt_pk_bf16_f32 v47, v48, v49
	ds_write2_b64 v71, v[62:63], v[46:47] offset0:16 offset1:20
	v_cndmask_b32_e64 v44, 0, v44, s[4:5]
	v_cndmask_b32_e64 v45, 0, v45, s[4:5]
	v_cvt_pk_bf16_f32 v42, v42, v43
	v_cvt_pk_bf16_f32 v43, v44, v45
	ds_write2_b64 v73, v[58:59], v[42:43] offset0:32 offset1:36
	v_cndmask_b32_e64 v40, 0, v40, s[6:7]
	v_cndmask_b32_e64 v41, 0, v41, s[6:7]
	v_cvt_pk_bf16_f32 v38, v38, v39
	v_cvt_pk_bf16_f32 v39, v40, v41
	ds_write2_b64 v86, v[54:55], v[38:39] offset0:48 offset1:52
	v_cndmask_b32_e64 v36, 0, v36, s[8:9]
	v_cndmask_b32_e64 v37, 0, v37, s[8:9]
	v_cvt_pk_bf16_f32 v34, v34, v35
	v_cvt_pk_bf16_f32 v35, v36, v37
	ds_write2_b64 v87, v[50:51], v[34:35] offset0:64 offset1:68
	v_cndmask_b32_e32 v32, 0, v32, vcc
	v_cndmask_b32_e32 v33, 0, v33, vcc
	v_cvt_pk_bf16_f32 v30, v30, v31
	v_cvt_pk_bf16_f32 v31, v32, v33
	v_cndmask_b32_e64 v24, 0, v24, s[6:7]
	v_cndmask_b32_e64 v25, 0, v25, s[6:7]
	v_cvt_pk_bf16_f32 v22, v22, v23
	v_cvt_pk_bf16_f32 v23, v24, v25
	v_cndmask_b32_e64 v20, 0, v20, s[8:9]
	v_cndmask_b32_e64 v21, 0, v21, s[8:9]
	v_cvt_pk_bf16_f32 v18, v18, v19
	v_cvt_pk_bf16_f32 v19, v20, v21
	v_cndmask_b32_e32 v16, 0, v16, vcc
	v_cndmask_b32_e32 v17, 0, v17, vcc
	v_cvt_pk_bf16_f32 v14, v14, v15
	v_cvt_pk_bf16_f32 v15, v16, v17
	ds_write2_b64 v71, v[30:31], v[14:15] offset0:24 offset1:28
	v_cndmask_b32_e64 v12, 0, v12, s[4:5]
	v_cndmask_b32_e64 v13, 0, v13, s[4:5]
	v_cvt_pk_bf16_f32 v10, v10, v11
	v_cvt_pk_bf16_f32 v11, v12, v13
	ds_write2_b64 v73, v[26:27], v[10:11] offset0:40 offset1:44
	v_cndmask_b32_e64 v8, 0, v8, s[6:7]
	v_cndmask_b32_e64 v9, 0, v9, s[6:7]
	v_cvt_pk_bf16_f32 v6, v6, v7
	v_cvt_pk_bf16_f32 v7, v8, v9
	ds_write2_b64 v86, v[22:23], v[6:7] offset0:56 offset1:60
	v_cndmask_b32_e64 v4, 0, v4, s[8:9]
	v_cndmask_b32_e64 v5, 0, v5, s[8:9]
	v_cvt_pk_bf16_f32 v2, v2, v3
	v_cvt_pk_bf16_f32 v3, v4, v5
	ds_write2_b64 v87, v[18:19], v[2:3] offset0:72 offset1:76
	s_waitcnt lgkmcnt(0)
	s_barrier
	v_mul_i32_i24_e32 v2, 0x10800, v98
	v_ashrrev_i32_e32 v29, 1, v28
	v_and_b32_e32 v38, -16, v29
	v_min_i32_e32 v3, 0x6e, v38
	v_or_b32_e32 v20, 1, v38
	v_add_u32_e32 v3, 17, v3
	v_cmp_lt_i32_e32 vcc, v20, v3
	v_ashrrev_i32_e32 v71, 31, v70
	s_and_saveexec_b64 s[4:5], vcc
	s_cbranch_execz .LBB0_3432
	v_lshlrev_b32_e32 v4, 1, v28
	v_and_b32_e32 v21, 62, v4
	v_or_b32_e32 v4, s24, v21
	s_add_i32 s6, s24, 0xb00
	v_ashrrev_i32_e32 v5, 31, v4
	v_or_b32_e32 v12, s6, v21
	v_lshlrev_b64 v[10:11], 2, v[4:5]
	v_lshl_add_u64 v[14:15], s[16:17], 0, v[10:11]
	v_lshl_add_u64 v[18:19], s[22:23], 0, v[10:11]
	v_ashrrev_i32_e32 v13, 31, v12
	v_lshl_add_u64 v[16:17], s[20:21], 0, v[10:11]
	global_load_dwordx2 v[4:5], v[14:15], off
	global_load_dwordx2 v[6:7], v[16:17], off
	global_load_dwordx2 v[8:9], v[18:19], off
	v_lshlrev_b64 v[18:19], 2, v[12:13]
	v_lshl_add_u64 v[10:11], s[18:19], 0, v[10:11]
	v_lshl_add_u64 v[22:23], s[16:17], 0, v[18:19]
	global_load_dwordx2 v[10:11], v[10:11], off
	v_lshl_add_u64 v[24:25], s[20:21], 0, v[18:19]
	v_lshl_add_u64 v[26:27], s[22:23], 0, v[18:19]
	global_load_dwordx2 v[12:13], v[22:23], off
	global_load_dwordx2 v[14:15], v[24:25], off
	global_load_dwordx2 v[16:17], v[26:27], off
	v_lshl_add_u64 v[18:19], s[18:19], 0, v[18:19]
	global_load_dwordx2 v[18:19], v[18:19], off
	v_lshlrev_b32_e32 v136, 1, v21
	v_mul_lo_u32 v22, v38, s31
	v_mul_lo_u32 v20, v20, s31
	v_add3_u32 v22, v2, v22, v136
	v_add3_u32 v20, v2, v20, v136
	ds_read2_b32 v[22:23], v22 offset1:32
	ds_read2_b32 v[20:21], v20 offset1:32
	s_ashr_i32 s25, s24, 31
	s_lshl_b64 s[6:7], s[24:25], 1
	s_add_u32 s6, s12, s6
	s_addc_u32 s7, s13, s7
	v_lshrrev_b32_e32 v29, 4, v29
	v_and_b32_e32 v28, 31, v28
	s_waitcnt lgkmcnt(1)
	v_lshlrev_b32_e32 v32, 16, v23
	v_and_b32_e32 v33, 0xffff0000, v23
	v_lshlrev_b32_e32 v34, 16, v22
	v_and_b32_e32 v35, 0xffff0000, v22
	v_lshl_add_u64 v[22:23], s[6:7], 0, v[136:137]
	v_mad_u64_u32 v[30:31], s[6:7], v29, s33, v[2:3]
	v_lshlrev_b32_e32 v28, 2, v28
	s_waitcnt lgkmcnt(0)
	v_lshlrev_b32_e32 v24, 16, v21
	v_and_b32_e32 v25, 0xffff0000, v21
	v_lshlrev_b32_e32 v26, 16, v20
	v_and_b32_e32 v27, 0xffff0000, v20
	v_lshlrev_b64 v[20:21], 11, v[70:71]
	v_add3_u32 v39, v30, v28, s34
	s_mov_b64 s[6:7], 0
	s_waitcnt vmcnt(0)
	s_branch .LBB0_3428

; template <bool SWAP, class Epi, bool THIN = false> ...
;     ...
;     for (int st = 0; st < ns; ++st) {
;       asm volatile("s_waitcnt vmcnt(0)" ::: "memory");
;       __builtin_amdgcn_s_barrier();
;       asm volatile("" ::: "memory");
;       if (st + 1 < ns) {
;         char* nb = smem + ((st + 1) & 1) * 65536;
;         const int ko = (st + 1) * 64;
; #pragma unroll
;         for (int i = 0; i < 4; ++i) { GLDS16(A + (size_t)(ap[i] + ko), nb + tid * 16 + i * 8192); GLDS16(Bt + (size_t)(bp[i] + ko), nb + 32768 + tid * 16 + i * 8192); }
;       }
;       const char* sa = smem + (st & 1) * 65536 + (wr * 64 + fr) * 128;
;       const char* sb = smem + (st & 1) * 65536 + 32768 + (wc * 128 + fr) * 128;
;       if constexpr (THIN) {
;         if (wc == 0) {
; #pragma unroll
;           for (int ks = 0; ks < 2; ++ks) {
;             bf16x8 af[4], bf[2];
; #pragma unroll
;             for (int m = 0; m < 4; ++m) af[m] = *(const bf16x8*)(sa + m * 2048 + (((ks * 4 + fq) ^ swz) << 4));
; #pragma unroll
;             for (int n = 0; n < 2; ++n) bf[n] = *(const bf16x8*)(sb + n * 2048 + (((ks * 4 + fq) ^ swz) << 4));
; #pragma unroll
;             for (int m = 0; m < 4; ++m)
; #pragma unroll
;               for (int n = 0; n < 2; ++n)
;                 acc[m][n] = SWAP ? __builtin_amdgcn_mfma_f32_16x16x32_bf16(bf[n], af[m], acc[m][n], 0, 0, 0)
;                                  : __builtin_amdgcn_mfma_f32_16x16x32_bf16(af[m], bf[n], acc[m][n], 0, 0, 0);
;           }
;         }
;       } else {
;       bf16x8 afA[4], afB[4], bfb[2][2];
; #pragma unroll
;       for (int m = 0; m < 4; ++m) afA[m] = *(const bf16x8*)(sa + m * 2048 + ((fq ^ swz) << 4));
; #pragma unroll
;       for (int n = 0; n < 2; ++n) bfb[0][n] = *(const bf16x8*)(sb + n * 2048 + ((fq ^ swz) << 4));
; #pragma unroll
;       for (int gq = 0; gq < 8; ++gq) {
;         const int ks = gq >> 2, nh = gq & 3;
;         if (gq < 7) {
;           const int ks2 = (gq + 1) >> 2, nh2 = (gq + 1) & 3;
; #pragma unroll
;           for (int n = 0; n < 2; ++n) bfb[(gq + 1) & 1][n] = *(const bf16x8*)(sb + (nh2 * 2 + n) * 2048 + (((ks2 * 4 + fq) ^ swz) << 4));
;         }
;         if (gq == 3) {
; #pragma unroll
;           for (int m = 0; m < 4; ++m) afB[m] = *(const bf16x8*)(sa + m * 2048 + (((4 + fq) ^ swz) << 4));
;         }
;         __builtin_amdgcn_sched_barrier(0);
; #pragma unroll
.LBB0_3516:
	s_add_i32 s9, s7, 0x10000
	s_and_b32 s8, s9, 0x10000
	v_add_u32_e32 v139, s8, v144
	s_nop 0
	v_readfirstlane_b32 s10, v139
	s_waitcnt vmcnt(0)
	s_barrier
	s_and_b32 s7, s7, 0x10000
	v_add_u32_e32 v130, s7, v145
	v_add_u32_e32 v139, v130, v147
	ds_read_b128 v[168:171], v139
	ds_read_b128 v[172:175], v139 offset:2048
	ds_read_b128 v[176:179], v139 offset:4096
	ds_read_b128 v[180:183], v139 offset:6144
	v_or_b32_e32 v139, s7, v146
	v_add_u32_e32 v141, v139, v147
	ds_read_b128 v[184:187], v141 offset:32768
	ds_read_b128 v[188:191], v141 offset:34816
	ds_read_b128 v[192:195], v141 offset:36864
	ds_read_b128 v[196:199], v141 offset:38912
	v_add_u32_e32 v130, v130, v148
	s_waitcnt lgkmcnt(3)
	v_mfma_f32_16x16x32_bf16 v[126:129], v[184:187], v[168:171], v[126:129]
	s_mov_b32 m0, s10
	v_mfma_f32_16x16x32_bf16 v[110:113], v[184:187], v[172:175], v[110:113]
	global_load_lds_dwordx4 v138, s[24:25]
	v_add_u32_e32 v138, 0x80, v138
	v_mfma_f32_16x16x32_bf16 v[82:85], v[184:187], v[176:179], v[82:85]
	v_mfma_f32_16x16x32_bf16 v[50:53], v[184:187], v[180:183], v[50:53]
	ds_read_b128 v[184:187], v141 offset:40960
	ds_read_b128 v[200:203], v141 offset:43008
	s_waitcnt lgkmcnt(4)
	v_mfma_f32_16x16x32_bf16 v[122:125], v[188:191], v[168:171], v[122:125]
	s_add_u32 m0, s10, 0x8000
	v_mfma_f32_16x16x32_bf16 v[106:109], v[188:191], v[172:175], v[106:109]
	global_load_lds_dwordx4 v137, s[20:21]
	v_add_u32_e32 v137, 0x80, v137
	v_mfma_f32_16x16x32_bf16 v[78:81], v[188:191], v[176:179], v[78:81]
	v_mfma_f32_16x16x32_bf16 v[38:41], v[188:191], v[180:183], v[38:41]
	s_waitcnt lgkmcnt(3)
	v_mfma_f32_16x16x32_bf16 v[118:121], v[192:195], v[168:171], v[118:121]
	s_add_u32 m0, s10, 0x2000
	v_mfma_f32_16x16x32_bf16 v[94:97], v[192:195], v[172:175], v[94:97]
	global_load_lds_dwordx4 v136, s[24:25]
	v_add_u32_e32 v136, 0x80, v136
	v_mfma_f32_16x16x32_bf16 v[58:61], v[192:195], v[176:179], v[58:61]
	v_mfma_f32_16x16x32_bf16 v[26:29], v[192:195], v[180:183], v[26:29]
	ds_read_b128 v[188:191], v141 offset:45056
	ds_read_b128 v[192:195], v141 offset:47104
	s_waitcnt lgkmcnt(4)
	v_mfma_f32_16x16x32_bf16 v[114:117], v[196:199], v[168:171], v[114:117]
	s_add_u32 m0, s10, 0xa000
	v_mfma_f32_16x16x32_bf16 v[86:89], v[196:199], v[172:175], v[86:89]
	global_load_lds_dwordx4 v135, s[20:21]
	v_add_u32_e32 v135, 0x80, v135
	v_mfma_f32_16x16x32_bf16 v[54:57], v[196:199], v[176:179], v[54:57]
	v_mfma_f32_16x16x32_bf16 v[22:25], v[196:199], v[180:183], v[22:25]
	v_add_u32_e32 v139, v139, v148
	s_waitcnt lgkmcnt(3)
	v_mfma_f32_16x16x32_bf16 v[102:105], v[184:187], v[168:171], v[102:105]
	ds_read_b128 v[196:199], v139 offset:32768
	ds_read_b128 v[204:207], v139 offset:34816
	s_add_u32 m0, s10, 0x4000
	v_mfma_f32_16x16x32_bf16 v[74:77], v[184:187], v[172:175], v[74:77]
	global_load_lds_dwordx4 v134, s[24:25]
	v_add_u32_e32 v134, 0x80, v134
	v_mfma_f32_16x16x32_bf16 v[46:49], v[184:187], v[176:179], v[46:49]
	v_mfma_f32_16x16x32_bf16 v[10:13], v[184:187], v[180:183], v[10:13]
	ds_read_b128 v[184:187], v130
	ds_read_b128 v[208:211], v130 offset:2048
	ds_read_b128 v[212:215], v130 offset:4096
	ds_read_b128 v[216:219], v130 offset:6144
	s_waitcnt lgkmcnt(8)
	v_mfma_f32_16x16x32_bf16 v[98:101], v[200:203], v[168:171], v[98:101]
	s_add_u32 m0, s10, 0xc000
	v_mfma_f32_16x16x32_bf16 v[66:69], v[200:203], v[172:175], v[66:69]
	global_load_lds_dwordx4 v133, s[20:21]
	v_add_u32_e32 v133, 0x80, v133
	v_mfma_f32_16x16x32_bf16 v[34:37], v[200:203], v[176:179], v[34:37]
	v_mfma_f32_16x16x32_bf16 v[6:9], v[200:203], v[180:183], v[6:9]
	s_waitcnt lgkmcnt(7)
	v_mfma_f32_16x16x32_bf16 v[70:73], v[188:191], v[168:171], v[70:73]
	s_add_u32 m0, s10, 0x6000
	s_waitcnt lgkmcnt(6)
	v_mfma_f32_16x16x32_bf16 v[62:65], v[192:195], v[168:171], v[62:65]
	global_load_lds_dwordx4 v132, s[24:25]
	v_add_u32_e32 v132, 0x80, v132
	v_mfma_f32_16x16x32_bf16 v[42:45], v[188:191], v[172:175], v[42:45]
	v_mfma_f32_16x16x32_bf16 v[30:33], v[192:195], v[172:175], v[30:33]
	ds_read_b128 v[168:171], v139 offset:36864
	ds_read_b128 v[172:175], v139 offset:38912
	v_mfma_f32_16x16x32_bf16 v[18:21], v[188:191], v[176:179], v[18:21]
	s_add_u32 m0, s10, 0xe000
	v_mfma_f32_16x16x32_bf16 v[14:17], v[192:195], v[176:179], v[14:17]
	global_load_lds_dwordx4 v140, s[20:21]
	v_add_u32_e32 v140, 0x80, v140
	v_mfma_f32_16x16x32_bf16 v[2:5], v[188:191], v[180:183], v[2:5]
	v_mfma_f32_16x16x32_bf16 v[90:93], v[192:195], v[180:183], v[90:93]
	ds_read_b128 v[176:179], v139 offset:40960
	ds_read_b128 v[180:183], v139 offset:43008
	s_waitcnt lgkmcnt(7)
	v_mfma_f32_16x16x32_bf16 v[126:129], v[196:199], v[184:187], v[126:129]
	v_mfma_f32_16x16x32_bf16 v[122:125], v[204:207], v[184:187], v[122:125]
	s_waitcnt lgkmcnt(6)
	v_mfma_f32_16x16x32_bf16 v[110:113], v[196:199], v[208:211], v[110:113]
	v_mfma_f32_16x16x32_bf16 v[106:109], v[204:207], v[208:211], v[106:109]
	s_waitcnt lgkmcnt(5)
	v_mfma_f32_16x16x32_bf16 v[82:85], v[196:199], v[212:215], v[82:85]
	v_mfma_f32_16x16x32_bf16 v[78:81], v[204:207], v[212:215], v[78:81]
	s_waitcnt lgkmcnt(4)
	v_mfma_f32_16x16x32_bf16 v[50:53], v[196:199], v[216:219], v[50:53]
	v_mfma_f32_16x16x32_bf16 v[38:41], v[204:207], v[216:219], v[38:41]
	s_waitcnt lgkmcnt(3)
	v_mfma_f32_16x16x32_bf16 v[118:121], v[168:171], v[184:187], v[118:121]
	v_mfma_f32_16x16x32_bf16 v[94:97], v[168:171], v[208:211], v[94:97]
	v_mfma_f32_16x16x32_bf16 v[58:61], v[168:171], v[212:215], v[58:61]
	v_mfma_f32_16x16x32_bf16 v[26:29], v[168:171], v[216:219], v[26:29]
	ds_read_b128 v[168:171], v139 offset:45056
	ds_read_b128 v[188:191], v139 offset:47104
	s_waitcnt lgkmcnt(4)
; template <bool SWAP, class Epi, bool THIN = false> ...
;     ...
;     for (int st = 0; st < ns; ++st) {
;       asm volatile("s_waitcnt vmcnt(0)" ::: "memory");
;       __builtin_amdgcn_s_barrier();
;       asm volatile("" ::: "memory");
;       if (st + 1 < ns) {
;         char* nb = smem + ((st + 1) & 1) * 65536;
;         const int ko = (st + 1) * 64;
; #pragma unroll
;         for (int i = 0; i < 4; ++i) { GLDS16(A + (size_t)(ap[i] + ko), nb + tid * 16 + i * 8192); GLDS16(Bt + (size_t)(bp[i] + ko), nb + 32768 + tid * 16 + i * 8192); }
;       }
;       const char* sa = smem + (st & 1) * 65536 + (wr * 64 + fr) * 128;
;       const char* sb = smem + (st & 1) * 65536 + 32768 + (wc * 128 + fr) * 128;
;       if constexpr (THIN) {
;         if (wc == 0) {
; #pragma unroll
;           for (int ks = 0; ks < 2; ++ks) {
;             bf16x8 af[4], bf[2];
; #pragma unroll
;             for (int m = 0; m < 4; ++m) af[m] = *(const bf16x8*)(sa + m * 2048 + (((ks * 4 + fq) ^ swz) << 4));
; #pragma unroll
;             for (int n = 0; n < 2; ++n) bf[n] = *(const bf16x8*)(sb + n * 2048 + (((ks * 4 + fq) ^ swz) << 4));
; #pragma unroll
;             for (int m = 0; m < 4; ++m)
; #pragma unroll
;               for (int n = 0; n < 2; ++n)
;                 acc[m][n] = SWAP ? __builtin_amdgcn_mfma_f32_16x16x32_bf16(bf[n], af[m], acc[m][n], 0, 0, 0)
;                                  : __builtin_amdgcn_mfma_f32_16x16x32_bf16(af[m], bf[n], acc[m][n], 0, 0, 0);
;           }
;         }
;       } else {
;       bf16x8 afA[4], afB[4], bfb[2][2];
; #pragma unroll
;       for (int m = 0; m < 4; ++m) afA[m] = *(const bf16x8*)(sa + m * 2048 + ((fq ^ swz) << 4));
; #pragma unroll
;       for (int n = 0; n < 2; ++n) bfb[0][n] = *(const bf16x8*)(sb + n * 2048 + ((fq ^ swz) << 4));
; #pragma unroll
;       for (int gq = 0; gq < 8; ++gq) {
;         const int ks = gq >> 2, nh = gq & 3;
;         if (gq < 7) {
;           const int ks2 = (gq + 1) >> 2, nh2 = (gq + 1) & 3;
; #pragma unroll
;           for (int n = 0; n < 2; ++n) bfb[(gq + 1) & 1][n] = *(const bf16x8*)(sb + (nh2 * 2 + n) * 2048 + (((ks2 * 4 + fq) ^ swz) << 4));
;         }
;         if (gq == 3) {
; #pragma unroll
;           for (int m = 0; m < 4; ++m) afB[m] = *(const bf16x8*)(sa + m * 2048 + (((4 + fq) ^ swz) << 4));
;         }
;         __builtin_amdgcn_sched_barrier(0);
; #pragma unroll
	v_mfma_f32_16x16x32_bf16 v[114:117], v[172:175], v[184:187], v[114:117]
	v_mfma_f32_16x16x32_bf16 v[86:89], v[172:175], v[208:211], v[86:89]
	v_mfma_f32_16x16x32_bf16 v[54:57], v[172:175], v[212:215], v[54:57]
	v_mfma_f32_16x16x32_bf16 v[22:25], v[172:175], v[216:219], v[22:25]
	s_waitcnt lgkmcnt(3)
	v_mfma_f32_16x16x32_bf16 v[102:105], v[176:179], v[184:187], v[102:105]
	s_waitcnt lgkmcnt(2)
	v_mfma_f32_16x16x32_bf16 v[98:101], v[180:183], v[184:187], v[98:101]
	v_mfma_f32_16x16x32_bf16 v[74:77], v[176:179], v[208:211], v[74:77]
	v_mfma_f32_16x16x32_bf16 v[66:69], v[180:183], v[208:211], v[66:69]
	v_mfma_f32_16x16x32_bf16 v[46:49], v[176:179], v[212:215], v[46:49]
	v_mfma_f32_16x16x32_bf16 v[34:37], v[180:183], v[212:215], v[34:37]
	v_mfma_f32_16x16x32_bf16 v[10:13], v[176:179], v[216:219], v[10:13]
	v_mfma_f32_16x16x32_bf16 v[6:9], v[180:183], v[216:219], v[6:9]
	s_waitcnt lgkmcnt(1)
	v_mfma_f32_16x16x32_bf16 v[70:73], v[168:171], v[184:187], v[70:73]
	s_add_i32 s6, s6, 64
	s_cmpk_eq_i32 s6, 0xac0
	s_mov_b32 s7, s9
	s_waitcnt lgkmcnt(0)
	v_mfma_f32_16x16x32_bf16 v[62:65], v[188:191], v[184:187], v[62:65]
	v_mfma_f32_16x16x32_bf16 v[42:45], v[168:171], v[208:211], v[42:45]
	v_mfma_f32_16x16x32_bf16 v[30:33], v[188:191], v[208:211], v[30:33]
	v_mfma_f32_16x16x32_bf16 v[18:21], v[168:171], v[212:215], v[18:21]
	v_mfma_f32_16x16x32_bf16 v[14:17], v[188:191], v[212:215], v[14:17]
	v_mfma_f32_16x16x32_bf16 v[2:5], v[168:171], v[216:219], v[2:5]
	v_mfma_f32_16x16x32_bf16 v[90:93], v[188:191], v[216:219], v[90:93]
	s_cbranch_scc0 .LBB0_3516
	v_add_u32_e32 v130, s8, v145
	s_waitcnt vmcnt(0)
	s_barrier
	v_add_u32_e32 v140, v130, v147
	ds_read_b128 v[132:135], v140
	ds_read_b128 v[136:139], v140 offset:2048
	ds_read_b128 v[168:171], v140 offset:4096
	ds_read_b128 v[172:175], v140 offset:6144
	v_add_u32_e32 v140, s8, v146
	v_add_u32_e32 v141, v140, v147
	ds_read_b128 v[176:179], v141 offset:32768
	ds_read_b128 v[180:183], v141 offset:34816
	ds_read_b128 v[184:187], v141 offset:36864
	ds_read_b128 v[188:191], v141 offset:38912
	v_add_u32_e32 v130, v130, v148
	s_waitcnt lgkmcnt(0)
	v_mfma_f32_16x16x32_bf16 v[126:129], v[176:179], v[132:135], v[126:129]
	v_mfma_f32_16x16x32_bf16 v[110:113], v[176:179], v[136:139], v[110:113]
	v_mfma_f32_16x16x32_bf16 v[82:85], v[176:179], v[168:171], v[82:85]
	v_mfma_f32_16x16x32_bf16 v[50:53], v[176:179], v[172:175], v[50:53]
	ds_read_b128 v[176:179], v141 offset:40960
	ds_read_b128 v[192:195], v141 offset:43008
	v_mfma_f32_16x16x32_bf16 v[122:125], v[180:183], v[132:135], v[122:125]
	v_mfma_f32_16x16x32_bf16 v[106:109], v[180:183], v[136:139], v[106:109]
	v_mfma_f32_16x16x32_bf16 v[78:81], v[180:183], v[168:171], v[78:81]
	v_mfma_f32_16x16x32_bf16 v[38:41], v[180:183], v[172:175], v[38:41]
	v_mfma_f32_16x16x32_bf16 v[118:121], v[184:187], v[132:135], v[118:121]
	v_mfma_f32_16x16x32_bf16 v[180:183], v[184:187], v[136:139], v[94:97]
	v_mfma_f32_16x16x32_bf16 v[200:203], v[184:187], v[168:171], v[58:61]
	v_mfma_f32_16x16x32_bf16 v[204:207], v[188:191], v[168:171], v[54:57]
	v_mfma_f32_16x16x32_bf16 v[184:187], v[184:187], v[172:175], v[26:29]
	s_nop 2
	ds_read_b128 v[26:29], v141 offset:45056
	ds_read_b128 v[54:57], v141 offset:47104
	v_mfma_f32_16x16x32_bf16 v[114:117], v[188:191], v[132:135], v[114:117]
	v_mfma_f32_16x16x32_bf16 v[196:199], v[188:191], v[136:139], v[86:89]
	v_mfma_f32_16x16x32_bf16 v[188:191], v[188:191], v[172:175], v[22:25]
	v_add_u32_e32 v140, v140, v148
	s_waitcnt lgkmcnt(0)
	v_mfma_f32_16x16x32_bf16 v[102:105], v[176:179], v[132:135], v[102:105]
	ds_read_b128 v[22:25], v140 offset:32768
	ds_read_b128 v[86:89], v140 offset:34816
	v_mfma_f32_16x16x32_bf16 v[74:77], v[176:179], v[136:139], v[74:77]
	v_mfma_f32_16x16x32_bf16 v[46:49], v[176:179], v[168:171], v[46:49]
	v_mfma_f32_16x16x32_bf16 v[10:13], v[176:179], v[172:175], v[10:13]
	ds_read_b128 v[176:179], v130
	ds_read_b128 v[208:211], v130 offset:2048
	ds_read_b128 v[212:215], v130 offset:4096
	ds_read_b128 v[216:219], v130 offset:6144
	v_mfma_f32_16x16x32_bf16 v[98:101], v[192:195], v[132:135], v[98:101]
	v_mfma_f32_16x16x32_bf16 v[66:69], v[192:195], v[136:139], v[66:69]
	v_mfma_f32_16x16x32_bf16 v[34:37], v[192:195], v[168:171], v[34:37]
	v_mfma_f32_16x16x32_bf16 v[6:9], v[192:195], v[172:175], v[6:9]
	v_mfma_f32_16x16x32_bf16 v[220:223], v[26:29], v[168:171], v[18:21]
	v_mfma_f32_16x16x32_bf16 v[168:171], v[54:57], v[168:171], v[14:17]
	s_nop 2
	ds_read_b128 v[14:17], v140 offset:36864
	ds_read_b128 v[18:21], v140 offset:38912
	v_mfma_f32_16x16x32_bf16 v[70:73], v[26:29], v[132:135], v[70:73]
	v_mfma_f32_16x16x32_bf16 v[132:135], v[54:57], v[132:135], v[62:65]
	v_mfma_f32_16x16x32_bf16 v[192:195], v[26:29], v[136:139], v[42:45]
	v_mfma_f32_16x16x32_bf16 v[136:139], v[54:57], v[136:139], v[30:33]
	v_mfma_f32_16x16x32_bf16 v[2:5], v[26:29], v[172:175], v[2:5]
	v_mfma_f32_16x16x32_bf16 v[172:175], v[54:57], v[172:175], v[90:93]
	ds_read_b128 v[224:227], v140 offset:40960
	ds_read_b128 v[228:231], v140 offset:43008
	s_waitcnt lgkmcnt(0)
	v_mfma_f32_16x16x32_bf16 v[126:129], v[22:25], v[176:179], v[126:129]
	v_mfma_f32_16x16x32_bf16 v[122:125], v[86:89], v[176:179], v[122:125]
	v_mfma_f32_16x16x32_bf16 v[94:97], v[22:25], v[208:211], v[110:113]
	v_mfma_f32_16x16x32_bf16 v[90:93], v[86:89], v[208:211], v[106:109]
	v_mfma_f32_16x16x32_bf16 v[62:65], v[22:25], v[212:215], v[82:85]
	v_mfma_f32_16x16x32_bf16 v[58:61], v[86:89], v[212:215], v[78:81]
	v_mfma_f32_16x16x32_bf16 v[30:33], v[22:25], v[216:219], v[50:53]
	v_mfma_f32_16x16x32_bf16 v[26:29], v[86:89], v[216:219], v[38:41]
	v_mfma_f32_16x16x32_bf16 v[86:89], v[14:17], v[208:211], v[180:183]
	v_mfma_f32_16x16x32_bf16 v[22:25], v[14:17], v[216:219], v[184:187]
	s_nop 1
	ds_read_b128 v[180:183], v140 offset:45056
	ds_read_b128 v[184:187], v140 offset:47104
	v_mfma_f32_16x16x32_bf16 v[118:121], v[14:17], v[176:179], v[118:121]
	v_mfma_f32_16x16x32_bf16 v[114:117], v[18:21], v[176:179], v[114:117]
	v_mfma_f32_16x16x32_bf16 v[82:85], v[18:21], v[208:211], v[196:199]
	v_mfma_f32_16x16x32_bf16 v[54:57], v[14:17], v[212:215], v[200:203]
	v_mfma_f32_16x16x32_bf16 v[50:53], v[18:21], v[212:215], v[204:207]
	v_mfma_f32_16x16x32_bf16 v[18:21], v[18:21], v[216:219], v[188:191]
	v_mfma_f32_16x16x32_bf16 v[110:113], v[224:227], v[176:179], v[102:105]
	v_mfma_f32_16x16x32_bf16 v[106:109], v[228:231], v[176:179], v[98:101]
	v_mfma_f32_16x16x32_bf16 v[78:81], v[224:227], v[208:211], v[74:77]
	v_mfma_f32_16x16x32_bf16 v[74:77], v[228:231], v[208:211], v[66:69]
	v_mfma_f32_16x16x32_bf16 v[46:49], v[224:227], v[212:215], v[46:49]
	v_mfma_f32_16x16x32_bf16 v[42:45], v[228:231], v[212:215], v[34:37]
	v_mfma_f32_16x16x32_bf16 v[14:17], v[224:227], v[216:219], v[10:13]
	v_mfma_f32_16x16x32_bf16 v[10:13], v[228:231], v[216:219], v[6:9]
	v_mov_b32_e32 v130, v1
	s_waitcnt vmcnt(0) lgkmcnt(0)
	s_barrier
; __device__ __forceinline__ int get_tid512() { int t = threadIdx.x; asm volatile("" : "+v"(t)); return t; }
; __device__ __forceinline__ unsigned pack2(float a, float b) { unsigned r; asm("v_cvt_pk_bf16_f32 %0, %1, %2" : "=v"(r) : "v"(a), "v"(b)); return r; }
; __device__ __forceinline__ float bf2f(bf16_t h) { return __uint_as_float(((unsigned)h) << 16); }
;   __device__ __forceinline__ void c4(int g, int rig, int col, f32x4 v) const {
;     const size_t o = ((size_t)g * 2048 + rig) * 1024 + col;
;     f32x4 bs;
;     if (BASE_F32) bs = __builtin_nontemporal_load((const f32x4*)((const float*)base + o));
;     else {
;       const uint2 u = *(const uint2*)((const bf16_t*)base + o);
;       bs[0] = bf2f((bf16_t)(u.x & 0xffff)); bs[1] = bf2f((bf16_t)(u.x >> 16)); bs[2] = bf2f((bf16_t)(u.y & 0xffff)); bs[3] = bf2f((bf16_t)(u.y >> 16));
;     }
;     const f32x4 gt = *(const f32x4*)(gate + (size_t)g * 6144 + col);
;     f32x4 bi = {0.f, 0.f, 0.f, 0.f};
;     if (bias) bi = *(const f32x4*)(bias + col);
;     f32x4 r;
; #pragma unroll
;     for (int j = 0; j < 4; ++j) r[j] = bs[j] + gt[j] * (v[j] + bi[j]);
;     uint2 w; w.x = pack2(r[0], r[1]); w.y = pack2(r[2], r[3]);
;     *(uint2*)(X16 + o) = w;
;   }
; template <bool SWAP, class Epi, bool THIN = false> ...
;     ...
;     const int te = get_tid512();
;     const int fr_e = te & 15, fq_e = (te & 63) >> 4, wr_e = te >> 7, wc_e = (te >> 6) & 1;
;     const int sub = 2 * mt + (wr_e >> 1);
;     const int g = sub / tpg, ti = sub - g * tpg;
;     const int rig0 = ti * step - halo;
;     const int rw = (wr_e & 1) * 64;
;     if constexpr (Epi::KIND == 0) {
; #pragma unroll
;       for (int m = 0; m < 4; ++m) {
;         const int rig = rig0 + rw + m * 16 + fr_e;
;         if constexpr (Epi::ROWSUM) {
;           float ss = 0.f;
; #pragma unroll
;           for (int n = 0; n < 8; ++n) {
;             const int col = nt * 256 + wc_e * 128 + n * 16 + fq_e * 4;
;             if (col < N) ss += epi.c4(g, rig, col, acc[m][n]);
;           }
;           ss += __shfl_xor(ss, 16); ss += __shfl_xor(ss, 32);
;           if (fq_e == 0) epi.rowsum(g, rig, nt * 2 + wc_e, ss);
;         } else {
; #pragma unroll
;           for (int n = 0; n < 8; ++n) {
;             const int col = nt * 256 + wc_e * 128 + n * 16 + fq_e * 4;
;             if (col < N) epi.c4(g, rig, col, acc[m][n]);
;           }
	v_mfma_f32_16x16x32_bf16 v[98:101], v[184:187], v[176:179], v[132:135]
	v_ashrrev_i32_e32 v7, 8, v130
	v_add_u32_e32 v7, s5, v7
	v_ashrrev_i32_e32 v8, 31, v7
	v_lshrrev_b32_e32 v8, 28, v8
	v_add_u32_e32 v8, v7, v8
	v_ashrrev_i32_e32 v134, 4, v8
	v_lshlrev_b32_e32 v8, 11, v134
	v_lshlrev_b32_e32 v7, 7, v7
	v_sub_u32_e32 v7, v7, v8
	v_lshrrev_b32_e32 v8, 1, v130
	v_and_b32_e32 v6, 15, v130
	v_and_b32_e32 v8, 64, v8
	v_mfma_f32_16x16x32_bf16 v[66:69], v[184:187], v[208:211], v[136:139]
	v_ashrrev_i32_e32 v135, 31, v134
	s_nop 1
	v_or3_b32 v136, v7, v8, v6
	v_lshlrev_b32_e32 v6, 1, v130
	v_and_b32_e32 v132, 0x80, v6
	v_mfma_f32_16x16x32_bf16 v[6:9], v[180:183], v[216:219], v[2:5]
	v_ashrrev_i32_e32 v137, 31, v136
	v_lshlrev_b64 v[138:139], 21, v[134:135]
	v_lshlrev_b64 v[140:141], 10, v[136:137]
	v_lshrrev_b32_e32 v2, 2, v130
	v_and_b32_e32 v2, 12, v2
	v_mfma_f32_16x16x32_bf16 v[102:105], v[180:183], v[176:179], v[70:73]
	v_or3_b32 v132, v2, v132, s4
	v_mad_i64_i32 v[134:135], s[4:5], v134, s31, 0
	v_mfma_f32_16x16x32_bf16 v[70:73], v[180:183], v[208:211], v[192:195]
	v_lshl_add_u64 v[140:141], v[140:141], 0, v[138:139]
	v_cmp_gt_i32_e32 vcc, s34, v132
	v_ashrrev_i32_e32 v133, 31, v132
	v_mfma_f32_16x16x32_bf16 v[38:41], v[180:183], v[212:215], v[220:223]
	v_lshl_add_u64 v[134:135], s[22:23], 0, v[134:135]
	v_lshl_add_u64 v[140:141], v[140:141], 1, s[18:19]
	v_mfma_f32_16x16x32_bf16 v[34:37], v[184:187], v[212:215], v[168:171]
	v_mfma_f32_16x16x32_bf16 v[2:5], v[184:187], v[216:219], v[172:175]
	s_and_saveexec_b64 s[4:5], vcc
	s_cbranch_execz .LBB0_3519
	s_nop 0
	v_lshl_add_u64 v[172:173], v[132:133], 1, v[140:141]
	global_load_dwordx2 v[174:175], v[172:173], off
	v_lshl_add_u64 v[168:169], v[132:133], 2, v[134:135]
	global_load_dwordx4 v[168:171], v[168:169], off
	v_add_f32_e32 v126, 0, v126
	v_add_f32_e32 v127, 0, v127
	v_add_f32_e32 v128, 0, v128
	v_add_f32_e32 v129, 0, v129
	s_waitcnt vmcnt(1)
	v_lshlrev_b32_e32 v130, 16, v174
	v_and_b32_e32 v137, 0xffff0000, v174
	v_lshlrev_b32_e32 v167, 16, v175
	v_and_b32_e32 v174, 0xffff0000, v175
	s_waitcnt vmcnt(0)
	v_fmac_f32_e32 v130, v126, v168
	v_fmac_f32_e32 v137, v127, v169
	v_fmac_f32_e32 v167, v128, v170
	v_fmac_f32_e32 v174, v129, v171
	v_cvt_pk_bf16_f32 v126, v130, v137
	v_cvt_pk_bf16_f32 v127, v167, v174
	global_store_dwordx2 v[172:173], v[126:127], off
